# GEMM loops: half of the LDS-DMA address adds (v_lshl_add_u64) folded into the saddr+voffset form of global_load_lds_dwordx4 (on top of setprio/barrier-edge edit and f8f6f4 fp8 GEMM)
# speedup vs baseline: 1.0119x; 1.0008x over previous
; #define PG8_STAGE(bufoff, gbase, voff) do { _Pragma("unroll") for (int _i = 0; _i < 2; ++_i) \
;         __builtin_amdgcn_global_load_lds((const unsigned*)((const char*)(gbase) + (voff)[_i]), (LAS unsigned*)(lds + (bufoff) + ldsw + _i * 8192), 16, 0, 0); } while (0)
; #define PG8_LDA(dst, b, h) do { _Pragma("unroll") for (int m = 0; m < 4; ++m) _Pragma("unroll") for (int k = 0; k < 2; ++k) dst[m][k] = *(const LAS bf16x8*)(lds + PG8_SA(b, h) + aoff + m * 2048 + k * 1024); } while (0)
; #define PG8_LDB(dst, b, h) do { _Pragma("unroll") for (int n = 0; n < 2; ++n) _Pragma("unroll") for (int k = 0; k < 2; ++k) dst[n][k] = *(const LAS bf16x8*)(lds + PG8_SB(b, h) + boff + n * 2048 + k * 1024); } while (0)
; #define PG8_WAIT_V(n) asm volatile("s_waitcnt vmcnt(" #n ")" ::: "memory")
; #define PG8_WAIT_L(n) asm volatile("s_waitcnt lgkmcnt(" #n ")" ::: "memory")
; #define PG8_BAR __builtin_amdgcn_s_barrier()
; #define PG8_SCHED __builtin_amdgcn_sched_barrier(0)
; template <class Epi, bool FP8 = false>
; __device__ __forceinline__ void gemm_phase(LAS unsigned char* lds, const Gemm g, const StaticOrder& S_, const Epi& E, const int tid) {
;     ...
;             PG8_LDB(B0, 0, 0); PG8_LDB(B1, 0, 1); PG8_SCHED; PG8_LDA(At, 0, 0); PG8_STAGE(PG8_SA(1, 1), a1 + hstepA, voffA);
;             PG8_WAIT_V(8); PG8_WAIT_L(0); PG8_BAR; PG8_MMA(0, 0, At, B0); PG8_MMA(0, 1, At, B1); PG8_BAR; PG8_SCHED;
;             PG8_LDA(At, 0, 1); PG8_STAGE(PG8_SB(0, 0), b2, voffB); PG8_STAGE(PG8_SB(0, 1), b2 + hstepB, voffB); PG8_STAGE(PG8_SA(0, 0), a2, voffA);
;             PG8_WAIT_V(8); PG8_WAIT_L(0); PG8_BAR; PG8_MMA(1, 0, At, B0); PG8_MMA(1, 1, At, B1); PG8_BAR; PG8_SCHED;
.LBB0_233:
	ds_read_b128 v[150:153], v147
	ds_read_b128 v[154:157], v147 offset:1024
	ds_read_b128 v[158:161], v147 offset:2048
	ds_read_b128 v[162:165], v147 offset:3072
	ds_read_b128 v[166:169], v148
	ds_read_b128 v[170:173], v148 offset:1024
	ds_read_b128 v[174:177], v148 offset:2048
	ds_read_b128 v[178:181], v148 offset:3072
	s_add_u32 s44, s30, 0xfff80080
	s_addc_u32 s45, s31, -1
	s_cmp_eq_u32 s70, 28
	s_cselect_b32 s47, s17, s45
	s_cselect_b32 s46, s43, s44
	s_cselect_b32 s45, s15, s69
	s_cselect_b32 s44, s66, s68
	s_add_i32 m0, s29, 0xc000
	ds_read_b128 v[182:185], v149
	ds_read_b128 v[186:189], v149 offset:1024
	ds_read_b128 v[190:193], v149 offset:2048
	ds_read_b128 v[194:197], v149 offset:3072
	ds_read_b128 v[198:201], v149 offset:4096
	ds_read_b128 v[202:205], v149 offset:5120
	ds_read_b128 v[206:209], v149 offset:6144
	ds_read_b128 v[210:213], v149 offset:7168
	global_load_lds_dwordx4 v136, s[30:31]
	s_add_i32 m0, s29, 0xe000
	s_nop 0
	global_load_lds_dwordx4 v138, s[30:31]
	s_waitcnt vmcnt(8)
	s_waitcnt lgkmcnt(0)
	s_setprio 1
	s_barrier
	v_mfma_f32_16x16x32_bf16 v[124:127], v[150:153], v[182:185], v[124:127]
	v_mfma_f32_16x16x32_bf16 v[120:123], v[158:161], v[182:185], v[120:123]
	v_mfma_f32_16x16x32_bf16 v[108:111], v[150:153], v[190:193], v[108:111]
	v_mfma_f32_16x16x32_bf16 v[104:107], v[158:161], v[190:193], v[104:107]
	v_mfma_f32_16x16x32_bf16 v[92:95], v[150:153], v[198:201], v[92:95]
	v_mfma_f32_16x16x32_bf16 v[88:91], v[158:161], v[198:201], v[88:91]
	v_mfma_f32_16x16x32_bf16 v[76:79], v[150:153], v[206:209], v[76:79]
	v_mfma_f32_16x16x32_bf16 v[72:75], v[158:161], v[206:209], v[72:75]
	v_mfma_f32_16x16x32_bf16 v[124:127], v[154:157], v[186:189], v[124:127]
	v_mfma_f32_16x16x32_bf16 v[120:123], v[162:165], v[186:189], v[120:123]
	v_mfma_f32_16x16x32_bf16 v[108:111], v[154:157], v[194:197], v[108:111]
	v_mfma_f32_16x16x32_bf16 v[104:107], v[162:165], v[194:197], v[104:107]
	v_mfma_f32_16x16x32_bf16 v[92:95], v[154:157], v[202:205], v[92:95]
	v_mfma_f32_16x16x32_bf16 v[88:91], v[162:165], v[202:205], v[88:91]
	v_mfma_f32_16x16x32_bf16 v[76:79], v[154:157], v[210:213], v[76:79]
	v_mfma_f32_16x16x32_bf16 v[72:75], v[162:165], v[210:213], v[72:75]
	v_mfma_f32_16x16x32_bf16 v[116:119], v[166:169], v[182:185], v[116:119]
	v_mfma_f32_16x16x32_bf16 v[112:115], v[174:177], v[182:185], v[112:115]
	v_mfma_f32_16x16x32_bf16 v[100:103], v[166:169], v[190:193], v[100:103]
	v_mfma_f32_16x16x32_bf16 v[96:99], v[174:177], v[190:193], v[96:99]
	v_mfma_f32_16x16x32_bf16 v[84:87], v[166:169], v[198:201], v[84:87]
	v_mfma_f32_16x16x32_bf16 v[80:83], v[174:177], v[198:201], v[80:83]
	v_mfma_f32_16x16x32_bf16 v[68:71], v[166:169], v[206:209], v[68:71]
	v_mfma_f32_16x16x32_bf16 v[64:67], v[174:177], v[206:209], v[64:67]
	v_mfma_f32_16x16x32_bf16 v[116:119], v[170:173], v[186:189], v[116:119]
	v_mfma_f32_16x16x32_bf16 v[112:115], v[178:181], v[186:189], v[112:115]
	v_mfma_f32_16x16x32_bf16 v[100:103], v[170:173], v[194:197], v[100:103]
	v_mfma_f32_16x16x32_bf16 v[96:99], v[178:181], v[194:197], v[96:99]
	v_mfma_f32_16x16x32_bf16 v[84:87], v[170:173], v[202:205], v[84:87]
	v_mfma_f32_16x16x32_bf16 v[80:83], v[178:181], v[202:205], v[80:83]
	v_mfma_f32_16x16x32_bf16 v[68:71], v[170:173], v[210:213], v[68:71]
	v_mfma_f32_16x16x32_bf16 v[64:67], v[178:181], v[210:213], v[64:67]
	s_setprio 0
	s_barrier
	s_add_i32 s71, s61, s51
	v_lshl_add_u64 v[214:215], s[44:45], 0, v[128:129]
	s_mov_b32 m0, s71
	ds_read_b128 v[182:185], v149 offset:16384
	ds_read_b128 v[186:189], v149 offset:17408
	ds_read_b128 v[190:193], v149 offset:18432
	ds_read_b128 v[194:197], v149 offset:19456
	ds_read_b128 v[198:201], v149 offset:20480
	ds_read_b128 v[202:205], v149 offset:21504
	ds_read_b128 v[206:209], v149 offset:22528
	ds_read_b128 v[210:213], v149 offset:23552
	global_load_lds_dwordx4 v[214:215], off
	s_add_i32 m0, s71, 0x2000
	s_add_u32 s72, s44, 0x80000
	v_lshl_add_u64 v[216:217], s[44:45], 0, v[130:131]
	s_addc_u32 s73, s45, 0
	s_add_i32 s71, s62, s51
	global_load_lds_dwordx4 v[216:217], off
	s_mov_b32 m0, s71
	v_lshl_add_u64 v[220:221], s[46:47], 0, v[132:133]
	global_load_lds_dwordx4 v128, s[72:73]
	s_add_i32 m0, s71, 0x2000
	s_nop 0
	global_load_lds_dwordx4 v130, s[72:73]
	v_lshl_add_u64 v[218:219], s[46:47], 0, v[134:135]
	s_mov_b32 m0, s29
	s_nop 0
	global_load_lds_dwordx4 v[218:219], off
	s_mov_b32 m0, s54
	s_nop 0
	global_load_lds_dwordx4 v[220:221], off
	s_waitcnt vmcnt(8)
	s_waitcnt lgkmcnt(0)
	s_setprio 1
	s_barrier
	v_mfma_f32_16x16x32_bf16 v[60:63], v[150:153], v[182:185], v[60:63]
	v_mfma_f32_16x16x32_bf16 v[56:59], v[158:161], v[182:185], v[56:59]
	v_mfma_f32_16x16x32_bf16 v[44:47], v[150:153], v[190:193], v[44:47]
	v_mfma_f32_16x16x32_bf16 v[40:43], v[158:161], v[190:193], v[40:43]
	v_mfma_f32_16x16x32_bf16 v[28:31], v[150:153], v[198:201], v[28:31]
	v_mfma_f32_16x16x32_bf16 v[24:27], v[158:161], v[198:201], v[24:27]
	v_mfma_f32_16x16x32_bf16 v[12:15], v[150:153], v[206:209], v[12:15]
	v_mfma_f32_16x16x32_bf16 v[8:11], v[158:161], v[206:209], v[8:11]
	v_mfma_f32_16x16x32_bf16 v[60:63], v[154:157], v[186:189], v[60:63]
	v_mfma_f32_16x16x32_bf16 v[56:59], v[162:165], v[186:189], v[56:59]
	v_mfma_f32_16x16x32_bf16 v[44:47], v[154:157], v[194:197], v[44:47]
	v_mfma_f32_16x16x32_bf16 v[40:43], v[162:165], v[194:197], v[40:43]
	v_mfma_f32_16x16x32_bf16 v[28:31], v[154:157], v[202:205], v[28:31]
	v_mfma_f32_16x16x32_bf16 v[24:27], v[162:165], v[202:205], v[24:27]
	v_mfma_f32_16x16x32_bf16 v[12:15], v[154:157], v[210:213], v[12:15]
	v_mfma_f32_16x16x32_bf16 v[8:11], v[162:165], v[210:213], v[8:11]
	v_mfma_f32_16x16x32_bf16 v[52:55], v[166:169], v[182:185], v[52:55]
	v_mfma_f32_16x16x32_bf16 v[48:51], v[174:177], v[182:185], v[48:51]
	v_mfma_f32_16x16x32_bf16 v[36:39], v[166:169], v[190:193], v[36:39]
	v_mfma_f32_16x16x32_bf16 v[32:35], v[174:177], v[190:193], v[32:35]
	v_mfma_f32_16x16x32_bf16 v[20:23], v[166:169], v[198:201], v[20:23]
	v_mfma_f32_16x16x32_bf16 v[16:19], v[174:177], v[198:201], v[16:19]
	v_mfma_f32_16x16x32_bf16 v[4:7], v[166:169], v[206:209], v[4:7]
	v_mfma_f32_16x16x32_bf16 v[0:3], v[174:177], v[206:209], v[0:3]
	v_mfma_f32_16x16x32_bf16 v[52:55], v[170:173], v[186:189], v[52:55]
	v_mfma_f32_16x16x32_bf16 v[48:51], v[178:181], v[186:189], v[48:51]
	v_mfma_f32_16x16x32_bf16 v[36:39], v[170:173], v[194:197], v[36:39]
	v_mfma_f32_16x16x32_bf16 v[32:35], v[178:181], v[194:197], v[32:35]
	v_mfma_f32_16x16x32_bf16 v[20:23], v[170:173], v[202:205], v[20:23]
	v_mfma_f32_16x16x32_bf16 v[16:19], v[178:181], v[202:205], v[16:19]
	v_mfma_f32_16x16x32_bf16 v[4:7], v[170:173], v[210:213], v[4:7]
	v_mfma_f32_16x16x32_bf16 v[0:3], v[178:181], v[210:213], v[0:3]
	s_setprio 0
	s_barrier
; #define PG8_STAGE(bufoff, gbase, voff) do { _Pragma("unroll") for (int _i = 0; _i < 2; ++_i) \
;         __builtin_amdgcn_global_load_lds((const unsigned*)((const char*)(gbase) + (voff)[_i]), (LAS unsigned*)(lds + (bufoff) + ldsw + _i * 8192), 16, 0, 0); } while (0)
; #define PG8_LDA(dst, b, h) do { _Pragma("unroll") for (int m = 0; m < 4; ++m) _Pragma("unroll") for (int k = 0; k < 2; ++k) dst[m][k] = *(const LAS bf16x8*)(lds + PG8_SA(b, h) + aoff + m * 2048 + k * 1024); } while (0)
; #define PG8_LDB(dst, b, h) do { _Pragma("unroll") for (int n = 0; n < 2; ++n) _Pragma("unroll") for (int k = 0; k < 2; ++k) dst[n][k] = *(const LAS bf16x8*)(lds + PG8_SB(b, h) + boff + n * 2048 + k * 1024); } while (0)
; #define PG8_WAIT_V(n) asm volatile("s_waitcnt vmcnt(" #n ")" ::: "memory")
; #define PG8_WAIT_L(n) asm volatile("s_waitcnt lgkmcnt(" #n ")" ::: "memory")
; #define PG8_BAR __builtin_amdgcn_s_barrier()
; #define PG8_SCHED __builtin_amdgcn_sched_barrier(0)
; template <class Epi, bool FP8 = false>
; __device__ __forceinline__ void gemm_phase(LAS unsigned char* lds, const Gemm g, const StaticOrder& S_, const Epi& E, const int tid) {
;     ...
;             PG8_LDB(B0, 1, 0); PG8_LDB(B1, 1, 1); PG8_SCHED; PG8_LDA(At, 1, 0); PG8_STAGE(PG8_SA(0, 1), a2 + hstepA, voffA);
;             PG8_WAIT_V(8); PG8_WAIT_L(0); PG8_BAR; PG8_MMA(0, 0, At, B0); PG8_MMA(0, 1, At, B1); PG8_BAR; PG8_SCHED;
;             PG8_LDA(At, 1, 1); PG8_STAGE(PG8_SB(1, 0), b3, voffB); PG8_STAGE(PG8_SB(1, 1), b3 + hstepB, voffB); PG8_STAGE(PG8_SA(1, 0), a3, voffA);
;             PG8_WAIT_V(8); PG8_WAIT_L(0); PG8_BAR; PG8_MMA(1, 0, At, B0); PG8_MMA(1, 1, At, B1); PG8_BAR; PG8_SCHED;
;         }
;         if (wr == 0) PG8_BAR;
	s_add_i32 s71, 0, 0x18000
	s_add_i32 s72, 0, 0x1c000
	v_add_u32_e32 v162, s71, v145
	v_add_u32_e32 v178, s72, v145
	ds_read_b128 v[150:153], v162
	ds_read_b128 v[154:157], v162 offset:1024
	ds_read_b128 v[158:161], v162 offset:2048
	ds_read_b128 v[162:165], v162 offset:3072
	ds_read_b128 v[166:169], v178
	ds_read_b128 v[170:173], v178 offset:1024
	ds_read_b128 v[174:177], v178 offset:2048
	ds_read_b128 v[178:181], v178 offset:3072
	s_add_u32 s46, s46, 0x80000
	s_addc_u32 s47, s47, 0
	s_mov_b32 m0, s55
	ds_read_b128 v[182:185], v149 offset:32768
	ds_read_b128 v[186:189], v149 offset:33792
	ds_read_b128 v[190:193], v149 offset:34816
	ds_read_b128 v[194:197], v149 offset:35840
	ds_read_b128 v[198:201], v149 offset:36864
	ds_read_b128 v[202:205], v149 offset:37888
	ds_read_b128 v[206:209], v149 offset:38912
	ds_read_b128 v[210:213], v149 offset:39936
	global_load_lds_dwordx4 v134, s[46:47]
	s_mov_b32 m0, s56
	s_nop 0
	global_load_lds_dwordx4 v132, s[46:47]
	s_waitcnt vmcnt(8)
	s_waitcnt lgkmcnt(0)
	s_setprio 1
	s_barrier
	v_mfma_f32_16x16x32_bf16 v[124:127], v[150:153], v[182:185], v[124:127]
	v_mfma_f32_16x16x32_bf16 v[120:123], v[158:161], v[182:185], v[120:123]
	v_mfma_f32_16x16x32_bf16 v[108:111], v[150:153], v[190:193], v[108:111]
	v_mfma_f32_16x16x32_bf16 v[104:107], v[158:161], v[190:193], v[104:107]
	v_mfma_f32_16x16x32_bf16 v[92:95], v[150:153], v[198:201], v[92:95]
	v_mfma_f32_16x16x32_bf16 v[88:91], v[158:161], v[198:201], v[88:91]
	v_mfma_f32_16x16x32_bf16 v[76:79], v[150:153], v[206:209], v[76:79]
	v_mfma_f32_16x16x32_bf16 v[72:75], v[158:161], v[206:209], v[72:75]
	v_mfma_f32_16x16x32_bf16 v[124:127], v[154:157], v[186:189], v[124:127]
	v_mfma_f32_16x16x32_bf16 v[120:123], v[162:165], v[186:189], v[120:123]
	v_mfma_f32_16x16x32_bf16 v[108:111], v[154:157], v[194:197], v[108:111]
	v_mfma_f32_16x16x32_bf16 v[104:107], v[162:165], v[194:197], v[104:107]
	v_mfma_f32_16x16x32_bf16 v[92:95], v[154:157], v[202:205], v[92:95]
	v_mfma_f32_16x16x32_bf16 v[88:91], v[162:165], v[202:205], v[88:91]
	v_mfma_f32_16x16x32_bf16 v[76:79], v[154:157], v[210:213], v[76:79]
	v_mfma_f32_16x16x32_bf16 v[72:75], v[162:165], v[210:213], v[72:75]
	v_mfma_f32_16x16x32_bf16 v[116:119], v[166:169], v[182:185], v[116:119]
	v_mfma_f32_16x16x32_bf16 v[112:115], v[174:177], v[182:185], v[112:115]
	v_mfma_f32_16x16x32_bf16 v[100:103], v[166:169], v[190:193], v[100:103]
	v_mfma_f32_16x16x32_bf16 v[96:99], v[174:177], v[190:193], v[96:99]
	v_mfma_f32_16x16x32_bf16 v[84:87], v[166:169], v[198:201], v[84:87]
	v_mfma_f32_16x16x32_bf16 v[80:83], v[174:177], v[198:201], v[80:83]
	v_mfma_f32_16x16x32_bf16 v[68:71], v[166:169], v[206:209], v[68:71]
	v_mfma_f32_16x16x32_bf16 v[64:67], v[174:177], v[206:209], v[64:67]
	v_mfma_f32_16x16x32_bf16 v[116:119], v[170:173], v[186:189], v[116:119]
	v_mfma_f32_16x16x32_bf16 v[112:115], v[178:181], v[186:189], v[112:115]
	v_mfma_f32_16x16x32_bf16 v[100:103], v[170:173], v[194:197], v[100:103]
	v_mfma_f32_16x16x32_bf16 v[96:99], v[178:181], v[194:197], v[96:99]
	v_mfma_f32_16x16x32_bf16 v[84:87], v[170:173], v[202:205], v[84:87]
	v_mfma_f32_16x16x32_bf16 v[80:83], v[178:181], v[202:205], v[80:83]
	v_mfma_f32_16x16x32_bf16 v[68:71], v[170:173], v[210:213], v[68:71]
	v_mfma_f32_16x16x32_bf16 v[64:67], v[178:181], v[210:213], v[64:67]
	s_setprio 0
	s_barrier
	s_add_i32 s46, s71, s51
	v_lshl_add_u64 v[214:215], v[214:215], 0, s[10:11]
	s_mov_b32 m0, s46
	ds_read_b128 v[182:185], v149 offset:49152
	ds_read_b128 v[186:189], v149 offset:50176
	ds_read_b128 v[190:193], v149 offset:51200
	ds_read_b128 v[194:197], v149 offset:52224
	ds_read_b128 v[198:201], v149 offset:53248
	ds_read_b128 v[202:205], v149 offset:54272
	ds_read_b128 v[206:209], v149 offset:55296
	ds_read_b128 v[210:213], v149 offset:56320
	global_load_lds_dwordx4 v[214:215], off
	s_add_i32 m0, s46, 0x2000
	s_add_u32 s44, s44, 0x80080
	v_lshl_add_u64 v[214:215], v[216:217], 0, s[10:11]
	s_addc_u32 s45, s45, 0
	s_add_i32 s46, s72, s51
	global_load_lds_dwordx4 v[214:215], off
	s_mov_b32 m0, s46
	s_nop 0
	global_load_lds_dwordx4 v128, s[44:45]
	s_add_i32 m0, s46, 0x2000
	s_nop 0
	global_load_lds_dwordx4 v130, s[44:45]
	v_lshl_add_u64 v[214:215], v[218:219], 0, s[10:11]
	s_mov_b32 m0, s58
	s_nop 0
	global_load_lds_dwordx4 v[214:215], off
	v_lshl_add_u64 v[214:215], v[220:221], 0, s[10:11]
	s_mov_b32 m0, s59
	s_nop 0
	global_load_lds_dwordx4 v[214:215], off
	s_waitcnt vmcnt(8)
	s_waitcnt lgkmcnt(0)
	s_setprio 1
	s_barrier
	v_mfma_f32_16x16x32_bf16 v[60:63], v[150:153], v[182:185], v[60:63]
	v_mfma_f32_16x16x32_bf16 v[56:59], v[158:161], v[182:185], v[56:59]
	v_mfma_f32_16x16x32_bf16 v[44:47], v[150:153], v[190:193], v[44:47]
	v_mfma_f32_16x16x32_bf16 v[40:43], v[158:161], v[190:193], v[40:43]
	v_mfma_f32_16x16x32_bf16 v[28:31], v[150:153], v[198:201], v[28:31]
	v_mfma_f32_16x16x32_bf16 v[24:27], v[158:161], v[198:201], v[24:27]
	v_mfma_f32_16x16x32_bf16 v[12:15], v[150:153], v[206:209], v[12:15]
	v_mfma_f32_16x16x32_bf16 v[8:11], v[158:161], v[206:209], v[8:11]
	v_mfma_f32_16x16x32_bf16 v[60:63], v[154:157], v[186:189], v[60:63]
	v_mfma_f32_16x16x32_bf16 v[56:59], v[162:165], v[186:189], v[56:59]
	v_mfma_f32_16x16x32_bf16 v[44:47], v[154:157], v[194:197], v[44:47]
	v_mfma_f32_16x16x32_bf16 v[40:43], v[162:165], v[194:197], v[40:43]
	v_mfma_f32_16x16x32_bf16 v[28:31], v[154:157], v[202:205], v[28:31]
	v_mfma_f32_16x16x32_bf16 v[24:27], v[162:165], v[202:205], v[24:27]
	v_mfma_f32_16x16x32_bf16 v[12:15], v[154:157], v[210:213], v[12:15]
	v_mfma_f32_16x16x32_bf16 v[8:11], v[162:165], v[210:213], v[8:11]
	v_mfma_f32_16x16x32_bf16 v[52:55], v[166:169], v[182:185], v[52:55]
	v_mfma_f32_16x16x32_bf16 v[48:51], v[174:177], v[182:185], v[48:51]
	v_mfma_f32_16x16x32_bf16 v[36:39], v[166:169], v[190:193], v[36:39]
	v_mfma_f32_16x16x32_bf16 v[32:35], v[174:177], v[190:193], v[32:35]
	v_mfma_f32_16x16x32_bf16 v[20:23], v[166:169], v[198:201], v[20:23]
	v_mfma_f32_16x16x32_bf16 v[16:19], v[174:177], v[198:201], v[16:19]
	v_mfma_f32_16x16x32_bf16 v[4:7], v[166:169], v[206:209], v[4:7]
	v_mfma_f32_16x16x32_bf16 v[0:3], v[174:177], v[206:209], v[0:3]
	v_mfma_f32_16x16x32_bf16 v[52:55], v[170:173], v[186:189], v[52:55]
	v_mfma_f32_16x16x32_bf16 v[48:51], v[178:181], v[186:189], v[48:51]
	v_mfma_f32_16x16x32_bf16 v[36:39], v[170:173], v[194:197], v[36:39]
	v_mfma_f32_16x16x32_bf16 v[32:35], v[178:181], v[194:197], v[32:35]
	v_mfma_f32_16x16x32_bf16 v[20:23], v[170:173], v[202:205], v[20:23]
	v_mfma_f32_16x16x32_bf16 v[16:19], v[178:181], v[202:205], v[16:19]
	v_mfma_f32_16x16x32_bf16 v[4:7], v[170:173], v[210:213], v[4:7]
	v_mfma_f32_16x16x32_bf16 v[0:3], v[178:181], v[210:213], v[0:3]
	s_setprio 0
	s_barrier
	s_add_i32 s70, s70, 2
	s_add_u32 s30, s30, 0x100
	s_addc_u32 s31, s31, 0
	s_add_u32 s68, s68, 0x100
	s_addc_u32 s69, s69, 0
	s_cmp_gt_u32 s70, 29
	s_cbranch_scc0 .LBB0_233
	s_and_b64 vcc, exec, s[12:13]
	s_cbranch_vccz .LBB0_236
	s_barrier

; #define PG8_STAGE(bufoff, gbase, voff) do { _Pragma("unroll") for (int _i = 0; _i < 2; ++_i) \
;         __builtin_amdgcn_global_load_lds((const unsigned*)((const char*)(gbase) + (voff)[_i]), (LAS unsigned*)(lds + (bufoff) + ldsw + _i * 8192), 16, 0, 0); } while (0)
; #define PG8_LDA(dst, b, h) do { _Pragma("unroll") for (int m = 0; m < 4; ++m) _Pragma("unroll") for (int k = 0; k < 2; ++k) dst[m][k] = *(const LAS bf16x8*)(lds + PG8_SA(b, h) + aoff + m * 2048 + k * 1024); } while (0)
; #define PG8_LDB(dst, b, h) do { _Pragma("unroll") for (int n = 0; n < 2; ++n) _Pragma("unroll") for (int k = 0; k < 2; ++k) dst[n][k] = *(const LAS bf16x8*)(lds + PG8_SB(b, h) + boff + n * 2048 + k * 1024); } while (0)
; #define PG8_WAIT_V(n) asm volatile("s_waitcnt vmcnt(" #n ")" ::: "memory")
; #define PG8_WAIT_L(n) asm volatile("s_waitcnt lgkmcnt(" #n ")" ::: "memory")
; #define PG8_BAR __builtin_amdgcn_s_barrier()
; #define PG8_SCHED __builtin_amdgcn_sched_barrier(0)
; template <class Epi, bool FP8 = false>
; __device__ __forceinline__ void gemm_phase(LAS unsigned char* lds, const Gemm g, const StaticOrder& S_, const Epi& E, const int tid) {
;     ...
;             PG8_LDB(B0, 0, 0); PG8_LDB(B1, 0, 1); PG8_SCHED; PG8_LDA(At, 0, 0); PG8_STAGE(PG8_SA(1, 1), a1 + hstepA, voffA);
;             PG8_WAIT_V(8); PG8_WAIT_L(0); PG8_BAR; PG8_MMA(0, 0, At, B0); PG8_MMA(0, 1, At, B1); PG8_BAR; PG8_SCHED;
;             PG8_LDA(At, 0, 1); PG8_STAGE(PG8_SB(0, 0), b2, voffB); PG8_STAGE(PG8_SB(0, 1), b2 + hstepB, voffB); PG8_STAGE(PG8_SA(0, 0), a2, voffA);
;             PG8_WAIT_V(8); PG8_WAIT_L(0); PG8_BAR; PG8_MMA(1, 0, At, B0); PG8_MMA(1, 1, At, B1); PG8_BAR; PG8_SCHED;
.LBB0_319:
	ds_read_b128 v[150:153], v146
	ds_read_b128 v[154:157], v146 offset:1024
	ds_read_b128 v[158:161], v146 offset:2048
	ds_read_b128 v[162:165], v146 offset:3072
	ds_read_b128 v[166:169], v147
	ds_read_b128 v[170:173], v147 offset:1024
	ds_read_b128 v[174:177], v147 offset:2048
	ds_read_b128 v[178:181], v147 offset:3072
	s_add_u32 s50, s48, 0x100
	s_addc_u32 s51, s49, 0
	s_cmpk_eq_i32 s77, 0x54
	s_cselect_b32 s55, s7, s51
	s_cselect_b32 s54, s6, s50
	s_cselect_b32 s53, s45, s76
	s_cselect_b32 s52, s44, s75
	s_add_i32 m0, s60, 0xc000
	ds_read_b128 v[182:185], v148
	ds_read_b128 v[186:189], v148 offset:1024
	ds_read_b128 v[190:193], v148 offset:2048
	ds_read_b128 v[194:197], v148 offset:3072
	ds_read_b128 v[198:201], v148 offset:4096
	ds_read_b128 v[202:205], v148 offset:5120
	ds_read_b128 v[206:209], v148 offset:6144
	ds_read_b128 v[210:213], v148 offset:7168
	global_load_lds_dwordx4 v132, s[48:49]
	s_add_i32 m0, s60, 0xe000
	s_nop 0
	global_load_lds_dwordx4 v134, s[48:49]
	s_waitcnt vmcnt(8)
	s_waitcnt lgkmcnt(0)
	s_setprio 1
	s_barrier
	v_mfma_f32_16x16x32_bf16 v[124:127], v[150:153], v[182:185], v[124:127]
	v_mfma_f32_16x16x32_bf16 v[120:123], v[158:161], v[182:185], v[120:123]
	v_mfma_f32_16x16x32_bf16 v[112:115], v[150:153], v[190:193], v[112:115]
	v_mfma_f32_16x16x32_bf16 v[104:107], v[158:161], v[190:193], v[104:107]
	v_mfma_f32_16x16x32_bf16 v[96:99], v[150:153], v[198:201], v[96:99]
	v_mfma_f32_16x16x32_bf16 v[88:91], v[158:161], v[198:201], v[88:91]
	v_mfma_f32_16x16x32_bf16 v[80:83], v[150:153], v[206:209], v[80:83]
	v_mfma_f32_16x16x32_bf16 v[72:75], v[158:161], v[206:209], v[72:75]
	v_mfma_f32_16x16x32_bf16 v[124:127], v[154:157], v[186:189], v[124:127]
	v_mfma_f32_16x16x32_bf16 v[120:123], v[162:165], v[186:189], v[120:123]
	v_mfma_f32_16x16x32_bf16 v[112:115], v[154:157], v[194:197], v[112:115]
	v_mfma_f32_16x16x32_bf16 v[104:107], v[162:165], v[194:197], v[104:107]
	v_mfma_f32_16x16x32_bf16 v[96:99], v[154:157], v[202:205], v[96:99]
	v_mfma_f32_16x16x32_bf16 v[88:91], v[162:165], v[202:205], v[88:91]
	v_mfma_f32_16x16x32_bf16 v[80:83], v[154:157], v[210:213], v[80:83]
	v_mfma_f32_16x16x32_bf16 v[72:75], v[162:165], v[210:213], v[72:75]
	v_mfma_f32_16x16x32_bf16 v[116:119], v[166:169], v[182:185], v[116:119]
	v_mfma_f32_16x16x32_bf16 v[108:111], v[174:177], v[182:185], v[108:111]
	v_mfma_f32_16x16x32_bf16 v[100:103], v[166:169], v[190:193], v[100:103]
	v_mfma_f32_16x16x32_bf16 v[92:95], v[174:177], v[190:193], v[92:95]
	v_mfma_f32_16x16x32_bf16 v[84:87], v[166:169], v[198:201], v[84:87]
	v_mfma_f32_16x16x32_bf16 v[76:79], v[174:177], v[198:201], v[76:79]
	v_mfma_f32_16x16x32_bf16 v[68:71], v[166:169], v[206:209], v[68:71]
	v_mfma_f32_16x16x32_bf16 v[64:67], v[174:177], v[206:209], v[64:67]
	v_mfma_f32_16x16x32_bf16 v[116:119], v[170:173], v[186:189], v[116:119]
	v_mfma_f32_16x16x32_bf16 v[108:111], v[178:181], v[186:189], v[108:111]
	v_mfma_f32_16x16x32_bf16 v[100:103], v[170:173], v[194:197], v[100:103]
	v_mfma_f32_16x16x32_bf16 v[92:95], v[178:181], v[194:197], v[92:95]
	v_mfma_f32_16x16x32_bf16 v[84:87], v[170:173], v[202:205], v[84:87]
	v_mfma_f32_16x16x32_bf16 v[76:79], v[178:181], v[202:205], v[76:79]
	v_mfma_f32_16x16x32_bf16 v[68:71], v[170:173], v[210:213], v[68:71]
	v_mfma_f32_16x16x32_bf16 v[64:67], v[178:181], v[210:213], v[64:67]
	s_setprio 0
	s_barrier
	s_add_i32 s48, s71, s59
	v_lshl_add_u64 v[140:141], s[52:53], 0, v[128:129]
	s_mov_b32 m0, s48
	ds_read_b128 v[182:185], v148 offset:16384
	ds_read_b128 v[186:189], v148 offset:17408
	ds_read_b128 v[190:193], v148 offset:18432
	ds_read_b128 v[194:197], v148 offset:19456
	ds_read_b128 v[198:201], v148 offset:20480
	ds_read_b128 v[202:205], v148 offset:21504
	ds_read_b128 v[206:209], v148 offset:22528
	ds_read_b128 v[210:213], v148 offset:23552
	global_load_lds_dwordx4 v[140:141], off
	s_add_i32 m0, s48, 0x2000
	s_add_u32 s48, s52, 0x160000
	v_lshl_add_u64 v[214:215], s[52:53], 0, v[130:131]
	s_addc_u32 s49, s53, 0
	s_add_i32 s78, s72, s59
	global_load_lds_dwordx4 v[214:215], off
	s_mov_b32 m0, s78
	v_lshl_add_u64 v[218:219], s[54:55], 0, v[130:131]
	global_load_lds_dwordx4 v128, s[48:49]
	s_add_i32 m0, s78, 0x2000
	s_nop 0
	global_load_lds_dwordx4 v130, s[48:49]
	v_lshl_add_u64 v[216:217], s[54:55], 0, v[128:129]
	s_mov_b32 m0, s60
	s_nop 0
	global_load_lds_dwordx4 v[216:217], off
	s_mov_b32 m0, s61
	s_nop 0
	global_load_lds_dwordx4 v[218:219], off
	s_waitcnt vmcnt(8)
	s_waitcnt lgkmcnt(0)
	s_setprio 1
	s_barrier
	v_mfma_f32_16x16x32_bf16 v[60:63], v[150:153], v[182:185], v[60:63]
	v_mfma_f32_16x16x32_bf16 v[56:59], v[158:161], v[182:185], v[56:59]
	v_mfma_f32_16x16x32_bf16 v[48:51], v[150:153], v[190:193], v[48:51]
	v_mfma_f32_16x16x32_bf16 v[40:43], v[158:161], v[190:193], v[40:43]
	v_mfma_f32_16x16x32_bf16 v[32:35], v[150:153], v[198:201], v[32:35]
	v_mfma_f32_16x16x32_bf16 v[24:27], v[158:161], v[198:201], v[24:27]
	v_mfma_f32_16x16x32_bf16 v[16:19], v[150:153], v[206:209], v[16:19]
	v_mfma_f32_16x16x32_bf16 v[8:11], v[158:161], v[206:209], v[8:11]
	v_mfma_f32_16x16x32_bf16 v[60:63], v[154:157], v[186:189], v[60:63]
	v_mfma_f32_16x16x32_bf16 v[56:59], v[162:165], v[186:189], v[56:59]
	v_mfma_f32_16x16x32_bf16 v[48:51], v[154:157], v[194:197], v[48:51]
	v_mfma_f32_16x16x32_bf16 v[40:43], v[162:165], v[194:197], v[40:43]
	v_mfma_f32_16x16x32_bf16 v[32:35], v[154:157], v[202:205], v[32:35]
	v_mfma_f32_16x16x32_bf16 v[24:27], v[162:165], v[202:205], v[24:27]
	v_mfma_f32_16x16x32_bf16 v[16:19], v[154:157], v[210:213], v[16:19]
	v_mfma_f32_16x16x32_bf16 v[8:11], v[162:165], v[210:213], v[8:11]
	v_mfma_f32_16x16x32_bf16 v[52:55], v[166:169], v[182:185], v[52:55]
	v_mfma_f32_16x16x32_bf16 v[44:47], v[174:177], v[182:185], v[44:47]
	v_mfma_f32_16x16x32_bf16 v[36:39], v[166:169], v[190:193], v[36:39]
	v_mfma_f32_16x16x32_bf16 v[28:31], v[174:177], v[190:193], v[28:31]
	v_mfma_f32_16x16x32_bf16 v[20:23], v[166:169], v[198:201], v[20:23]
	v_mfma_f32_16x16x32_bf16 v[12:15], v[174:177], v[198:201], v[12:15]
	v_mfma_f32_16x16x32_bf16 v[4:7], v[166:169], v[206:209], v[4:7]
	v_mfma_f32_16x16x32_bf16 v[0:3], v[174:177], v[206:209], v[0:3]
	v_mfma_f32_16x16x32_bf16 v[52:55], v[170:173], v[186:189], v[52:55]
	v_mfma_f32_16x16x32_bf16 v[44:47], v[178:181], v[186:189], v[44:47]
	v_mfma_f32_16x16x32_bf16 v[36:39], v[170:173], v[194:197], v[36:39]
	v_mfma_f32_16x16x32_bf16 v[28:31], v[178:181], v[194:197], v[28:31]
	v_mfma_f32_16x16x32_bf16 v[20:23], v[170:173], v[202:205], v[20:23]
	v_mfma_f32_16x16x32_bf16 v[12:15], v[178:181], v[202:205], v[12:15]
	v_mfma_f32_16x16x32_bf16 v[4:7], v[170:173], v[210:213], v[4:7]
	v_mfma_f32_16x16x32_bf16 v[0:3], v[178:181], v[210:213], v[0:3]
	s_setprio 0
	s_barrier
; #define PG8_STAGE(bufoff, gbase, voff) do { _Pragma("unroll") for (int _i = 0; _i < 2; ++_i) \
;         __builtin_amdgcn_global_load_lds((const unsigned*)((const char*)(gbase) + (voff)[_i]), (LAS unsigned*)(lds + (bufoff) + ldsw + _i * 8192), 16, 0, 0); } while (0)
; #define PG8_LDA(dst, b, h) do { _Pragma("unroll") for (int m = 0; m < 4; ++m) _Pragma("unroll") for (int k = 0; k < 2; ++k) dst[m][k] = *(const LAS bf16x8*)(lds + PG8_SA(b, h) + aoff + m * 2048 + k * 1024); } while (0)
; #define PG8_LDB(dst, b, h) do { _Pragma("unroll") for (int n = 0; n < 2; ++n) _Pragma("unroll") for (int k = 0; k < 2; ++k) dst[n][k] = *(const LAS bf16x8*)(lds + PG8_SB(b, h) + boff + n * 2048 + k * 1024); } while (0)
; #define PG8_WAIT_V(n) asm volatile("s_waitcnt vmcnt(" #n ")" ::: "memory")
; #define PG8_WAIT_L(n) asm volatile("s_waitcnt lgkmcnt(" #n ")" ::: "memory")
; #define PG8_BAR __builtin_amdgcn_s_barrier()
; #define PG8_SCHED __builtin_amdgcn_sched_barrier(0)
; template <class Epi, bool FP8 = false>
; __device__ __forceinline__ void gemm_phase(LAS unsigned char* lds, const Gemm g, const StaticOrder& S_, const Epi& E, const int tid) {
;     ...
;             PG8_LDB(B0, 1, 0); PG8_LDB(B1, 1, 1); PG8_SCHED; PG8_LDA(At, 1, 0); PG8_STAGE(PG8_SA(0, 1), a2 + hstepA, voffA);
;             PG8_WAIT_V(8); PG8_WAIT_L(0); PG8_BAR; PG8_MMA(0, 0, At, B0); PG8_MMA(0, 1, At, B1); PG8_BAR; PG8_SCHED;
;             PG8_LDA(At, 1, 1); PG8_STAGE(PG8_SB(1, 0), b3, voffB); PG8_STAGE(PG8_SB(1, 1), b3 + hstepB, voffB); PG8_STAGE(PG8_SA(1, 0), a3, voffA);
;             PG8_WAIT_V(8); PG8_WAIT_L(0); PG8_BAR; PG8_MMA(1, 0, At, B0); PG8_MMA(1, 1, At, B1); PG8_BAR; PG8_SCHED;
;         }
;         if (wr == 0) PG8_BAR;
	s_add_i32 s78, 0, 0x18000
	v_add_u32_e32 v149, s78, v144
	s_add_i32 s79, 0, 0x1c000
	ds_read_b128 v[150:153], v149
	ds_read_b128 v[154:157], v149 offset:1024
	ds_read_b128 v[158:161], v149 offset:2048
	ds_read_b128 v[162:165], v149 offset:3072
	v_add_u32_e32 v149, s79, v144
	ds_read_b128 v[166:169], v149
	ds_read_b128 v[170:173], v149 offset:1024
	ds_read_b128 v[174:177], v149 offset:2048
	ds_read_b128 v[178:181], v149 offset:3072
	s_add_u32 s48, s54, 0x160000
	s_addc_u32 s49, s55, 0
	s_mov_b32 m0, s62
	ds_read_b128 v[182:185], v148 offset:32768
	ds_read_b128 v[186:189], v148 offset:33792
	ds_read_b128 v[190:193], v148 offset:34816
	ds_read_b128 v[194:197], v148 offset:35840
	ds_read_b128 v[198:201], v148 offset:36864
	ds_read_b128 v[202:205], v148 offset:37888
	ds_read_b128 v[206:209], v148 offset:38912
	ds_read_b128 v[210:213], v148 offset:39936
	global_load_lds_dwordx4 v128, s[48:49]
	s_mov_b32 m0, s63
	s_nop 0
	global_load_lds_dwordx4 v130, s[48:49]
	s_waitcnt vmcnt(8)
	s_waitcnt lgkmcnt(0)
	s_setprio 1
	s_barrier
	v_mfma_f32_16x16x32_bf16 v[124:127], v[150:153], v[182:185], v[124:127]
	v_mfma_f32_16x16x32_bf16 v[120:123], v[158:161], v[182:185], v[120:123]
	v_mfma_f32_16x16x32_bf16 v[112:115], v[150:153], v[190:193], v[112:115]
	v_mfma_f32_16x16x32_bf16 v[104:107], v[158:161], v[190:193], v[104:107]
	v_mfma_f32_16x16x32_bf16 v[96:99], v[150:153], v[198:201], v[96:99]
	v_mfma_f32_16x16x32_bf16 v[88:91], v[158:161], v[198:201], v[88:91]
	v_mfma_f32_16x16x32_bf16 v[80:83], v[150:153], v[206:209], v[80:83]
	v_mfma_f32_16x16x32_bf16 v[72:75], v[158:161], v[206:209], v[72:75]
	v_mfma_f32_16x16x32_bf16 v[124:127], v[154:157], v[186:189], v[124:127]
	v_mfma_f32_16x16x32_bf16 v[120:123], v[162:165], v[186:189], v[120:123]
	v_mfma_f32_16x16x32_bf16 v[112:115], v[154:157], v[194:197], v[112:115]
	v_mfma_f32_16x16x32_bf16 v[104:107], v[162:165], v[194:197], v[104:107]
	v_mfma_f32_16x16x32_bf16 v[96:99], v[154:157], v[202:205], v[96:99]
	v_mfma_f32_16x16x32_bf16 v[88:91], v[162:165], v[202:205], v[88:91]
	v_mfma_f32_16x16x32_bf16 v[80:83], v[154:157], v[210:213], v[80:83]
	v_mfma_f32_16x16x32_bf16 v[72:75], v[162:165], v[210:213], v[72:75]
	v_mfma_f32_16x16x32_bf16 v[116:119], v[166:169], v[182:185], v[116:119]
	v_mfma_f32_16x16x32_bf16 v[108:111], v[174:177], v[182:185], v[108:111]
	v_mfma_f32_16x16x32_bf16 v[100:103], v[166:169], v[190:193], v[100:103]
	v_mfma_f32_16x16x32_bf16 v[92:95], v[174:177], v[190:193], v[92:95]
	v_mfma_f32_16x16x32_bf16 v[84:87], v[166:169], v[198:201], v[84:87]
	v_mfma_f32_16x16x32_bf16 v[76:79], v[174:177], v[198:201], v[76:79]
	v_mfma_f32_16x16x32_bf16 v[68:71], v[166:169], v[206:209], v[68:71]
	v_mfma_f32_16x16x32_bf16 v[64:67], v[174:177], v[206:209], v[64:67]
	v_mfma_f32_16x16x32_bf16 v[116:119], v[170:173], v[186:189], v[116:119]
	v_mfma_f32_16x16x32_bf16 v[108:111], v[178:181], v[186:189], v[108:111]
	v_mfma_f32_16x16x32_bf16 v[100:103], v[170:173], v[194:197], v[100:103]
	v_mfma_f32_16x16x32_bf16 v[92:95], v[178:181], v[194:197], v[92:95]
	v_mfma_f32_16x16x32_bf16 v[84:87], v[170:173], v[202:205], v[84:87]
	v_mfma_f32_16x16x32_bf16 v[76:79], v[178:181], v[202:205], v[76:79]
	v_mfma_f32_16x16x32_bf16 v[68:71], v[170:173], v[210:213], v[68:71]
	v_mfma_f32_16x16x32_bf16 v[64:67], v[178:181], v[210:213], v[64:67]
	s_setprio 0
	s_barrier
	s_add_i32 s48, s78, s59
	v_lshl_add_u64 v[140:141], v[140:141], 0, s[14:15]
	s_mov_b32 m0, s48
	ds_read_b128 v[182:185], v148 offset:49152
	ds_read_b128 v[186:189], v148 offset:50176
	ds_read_b128 v[190:193], v148 offset:51200
	ds_read_b128 v[194:197], v148 offset:52224
	ds_read_b128 v[198:201], v148 offset:53248
	ds_read_b128 v[202:205], v148 offset:54272
	ds_read_b128 v[206:209], v148 offset:55296
	ds_read_b128 v[210:213], v148 offset:56320
	global_load_lds_dwordx4 v[140:141], off
	s_add_i32 m0, s48, 0x2000
	s_add_u32 s48, s52, 0x160080
	v_lshl_add_u64 v[140:141], v[214:215], 0, s[14:15]
	s_addc_u32 s49, s53, 0
	s_add_i32 s52, s79, s59
	global_load_lds_dwordx4 v[140:141], off
	s_mov_b32 m0, s52
	s_nop 0
	global_load_lds_dwordx4 v128, s[48:49]
	s_add_i32 m0, s52, 0x2000
	s_nop 0
	global_load_lds_dwordx4 v130, s[48:49]
	v_lshl_add_u64 v[140:141], v[216:217], 0, s[14:15]
	s_mov_b32 m0, s68
	s_nop 0
	global_load_lds_dwordx4 v[140:141], off
	v_lshl_add_u64 v[140:141], v[218:219], 0, s[14:15]
	s_mov_b32 m0, s69
	s_nop 0
	global_load_lds_dwordx4 v[140:141], off
	s_waitcnt vmcnt(8)
	s_waitcnt lgkmcnt(0)
	s_setprio 1
	s_barrier
	v_mfma_f32_16x16x32_bf16 v[60:63], v[150:153], v[182:185], v[60:63]
	v_mfma_f32_16x16x32_bf16 v[56:59], v[158:161], v[182:185], v[56:59]
	v_mfma_f32_16x16x32_bf16 v[48:51], v[150:153], v[190:193], v[48:51]
	v_mfma_f32_16x16x32_bf16 v[40:43], v[158:161], v[190:193], v[40:43]
	v_mfma_f32_16x16x32_bf16 v[32:35], v[150:153], v[198:201], v[32:35]
	v_mfma_f32_16x16x32_bf16 v[24:27], v[158:161], v[198:201], v[24:27]
	v_mfma_f32_16x16x32_bf16 v[16:19], v[150:153], v[206:209], v[16:19]
	v_mfma_f32_16x16x32_bf16 v[8:11], v[158:161], v[206:209], v[8:11]
	v_mfma_f32_16x16x32_bf16 v[60:63], v[154:157], v[186:189], v[60:63]
	v_mfma_f32_16x16x32_bf16 v[56:59], v[162:165], v[186:189], v[56:59]
	v_mfma_f32_16x16x32_bf16 v[48:51], v[154:157], v[194:197], v[48:51]
	v_mfma_f32_16x16x32_bf16 v[40:43], v[162:165], v[194:197], v[40:43]
	v_mfma_f32_16x16x32_bf16 v[32:35], v[154:157], v[202:205], v[32:35]
	v_mfma_f32_16x16x32_bf16 v[24:27], v[162:165], v[202:205], v[24:27]
	v_mfma_f32_16x16x32_bf16 v[16:19], v[154:157], v[210:213], v[16:19]
	v_mfma_f32_16x16x32_bf16 v[8:11], v[162:165], v[210:213], v[8:11]
	v_mfma_f32_16x16x32_bf16 v[52:55], v[166:169], v[182:185], v[52:55]
	v_mfma_f32_16x16x32_bf16 v[44:47], v[174:177], v[182:185], v[44:47]
	v_mfma_f32_16x16x32_bf16 v[36:39], v[166:169], v[190:193], v[36:39]
	v_mfma_f32_16x16x32_bf16 v[28:31], v[174:177], v[190:193], v[28:31]
	v_mfma_f32_16x16x32_bf16 v[20:23], v[166:169], v[198:201], v[20:23]
	v_mfma_f32_16x16x32_bf16 v[12:15], v[174:177], v[198:201], v[12:15]
	v_mfma_f32_16x16x32_bf16 v[4:7], v[166:169], v[206:209], v[4:7]
	v_mfma_f32_16x16x32_bf16 v[0:3], v[174:177], v[206:209], v[0:3]
	v_mfma_f32_16x16x32_bf16 v[52:55], v[170:173], v[186:189], v[52:55]
	v_mfma_f32_16x16x32_bf16 v[44:47], v[178:181], v[186:189], v[44:47]
	v_mfma_f32_16x16x32_bf16 v[36:39], v[170:173], v[194:197], v[36:39]
	v_mfma_f32_16x16x32_bf16 v[28:31], v[178:181], v[194:197], v[28:31]
	v_mfma_f32_16x16x32_bf16 v[20:23], v[170:173], v[202:205], v[20:23]
	v_mfma_f32_16x16x32_bf16 v[12:15], v[178:181], v[202:205], v[12:15]
	v_mfma_f32_16x16x32_bf16 v[4:7], v[170:173], v[210:213], v[4:7]
	v_mfma_f32_16x16x32_bf16 v[0:3], v[178:181], v[210:213], v[0:3]
	s_setprio 0
	s_barrier
	s_add_i32 s77, s77, 2
	s_add_u32 s75, s75, 0x100
	s_addc_u32 s76, s76, 0
	s_cmpk_gt_u32 s77, 0x55
	s_mov_b64 s[48:49], s[50:51]
	s_cbranch_scc0 .LBB0_319
	s_and_b64 vcc, exec, s[16:17]
	s_cbranch_vccz .LBB0_322
	s_barrier

; #define PG8_STAGE(bufoff, gbase, voff) do { _Pragma("unroll") for (int _i = 0; _i < 2; ++_i) \
;         __builtin_amdgcn_global_load_lds((const unsigned*)((const char*)(gbase) + (voff)[_i]), (LAS unsigned*)(lds + (bufoff) + ldsw + _i * 8192), 16, 0, 0); } while (0)
; #define PG8_LDA(dst, b, h) do { _Pragma("unroll") for (int m = 0; m < 4; ++m) _Pragma("unroll") for (int k = 0; k < 2; ++k) dst[m][k] = *(const LAS bf16x8*)(lds + PG8_SA(b, h) + aoff + m * 2048 + k * 1024); } while (0)
; #define PG8_LDB(dst, b, h) do { _Pragma("unroll") for (int n = 0; n < 2; ++n) _Pragma("unroll") for (int k = 0; k < 2; ++k) dst[n][k] = *(const LAS bf16x8*)(lds + PG8_SB(b, h) + boff + n * 2048 + k * 1024); } while (0)
; #define PG8_WAIT_V(n) asm volatile("s_waitcnt vmcnt(" #n ")" ::: "memory")
; #define PG8_WAIT_L(n) asm volatile("s_waitcnt lgkmcnt(" #n ")" ::: "memory")
; #define PG8_BAR __builtin_amdgcn_s_barrier()
; #define PG8_SCHED __builtin_amdgcn_sched_barrier(0)
; template <class Epi, bool FP8 = false>
; __device__ __forceinline__ void gemm_phase(LAS unsigned char* lds, const Gemm g, const StaticOrder& S_, const Epi& E, const int tid) {
;     ...
;             PG8_LDB(B0, 0, 0); PG8_LDB(B1, 0, 1); PG8_SCHED; PG8_LDA(At, 0, 0); PG8_STAGE(PG8_SA(1, 1), a1 + hstepA, voffA);
;             PG8_WAIT_V(8); PG8_WAIT_L(0); PG8_BAR; PG8_MMA(0, 0, At, B0); PG8_MMA(0, 1, At, B1); PG8_BAR; PG8_SCHED;
;             PG8_LDA(At, 0, 1); PG8_STAGE(PG8_SB(0, 0), b2, voffB); PG8_STAGE(PG8_SB(0, 1), b2 + hstepB, voffB); PG8_STAGE(PG8_SA(0, 0), a2, voffA);
;             PG8_WAIT_V(8); PG8_WAIT_L(0); PG8_BAR; PG8_MMA(1, 0, At, B0); PG8_MMA(1, 1, At, B1); PG8_BAR; PG8_SCHED;
.LBB0_457:
	ds_read_b128 v[128:131], v190
	ds_read_b128 v[132:135], v190 offset:1024
	ds_read_b128 v[136:139], v190 offset:2048
	ds_read_b128 v[140:143], v190 offset:3072
	ds_read_b128 v[182:185], v192
	ds_read_b128 v[194:197], v192 offset:1024
	ds_read_b128 v[198:201], v192 offset:2048
	ds_read_b128 v[202:205], v192 offset:3072
	s_add_u32 s56, s54, 0xfff80080
	s_addc_u32 s57, s55, -1
	s_cmp_eq_u32 s61, 28
	s_cselect_b32 s59, s7, s57
	s_cselect_b32 s58, s42, s56
	s_cselect_b32 s57, s27, s60
	s_cselect_b32 s56, s43, s49
	s_add_i32 m0, s71, 0xc000
	ds_read_b128 v[206:209], v191
	ds_read_b128 v[210:213], v191 offset:1024
	ds_read_b128 v[214:217], v191 offset:2048
	ds_read_b128 v[218:221], v191 offset:3072
	ds_read_b128 v[222:225], v191 offset:4096
	ds_read_b128 v[226:229], v191 offset:5120
	ds_read_b128 v[230:233], v191 offset:6144
	ds_read_b128 v[234:237], v191 offset:7168
	global_load_lds_dwordx4 v174, s[54:55]
	s_add_i32 m0, s71, 0xe000
	s_nop 0
	global_load_lds_dwordx4 v176, s[54:55]
	s_waitcnt vmcnt(8)
	s_waitcnt lgkmcnt(0)
	s_setprio 1
	s_barrier
	v_mfma_f32_16x16x32_bf16 v[124:127], v[128:131], v[206:209], v[124:127]
	v_mfma_f32_16x16x32_bf16 v[120:123], v[136:139], v[206:209], v[120:123]
	v_mfma_f32_16x16x32_bf16 v[108:111], v[128:131], v[214:217], v[108:111]
	v_mfma_f32_16x16x32_bf16 v[104:107], v[136:139], v[214:217], v[104:107]
	v_mfma_f32_16x16x32_bf16 v[92:95], v[128:131], v[222:225], v[92:95]
	v_mfma_f32_16x16x32_bf16 v[88:91], v[136:139], v[222:225], v[88:91]
	v_mfma_f32_16x16x32_bf16 v[76:79], v[128:131], v[230:233], v[76:79]
	v_mfma_f32_16x16x32_bf16 v[72:75], v[136:139], v[230:233], v[72:75]
	v_mfma_f32_16x16x32_bf16 v[124:127], v[132:135], v[210:213], v[124:127]
	v_mfma_f32_16x16x32_bf16 v[120:123], v[140:143], v[210:213], v[120:123]
	v_mfma_f32_16x16x32_bf16 v[108:111], v[132:135], v[218:221], v[108:111]
	v_mfma_f32_16x16x32_bf16 v[104:107], v[140:143], v[218:221], v[104:107]
	v_mfma_f32_16x16x32_bf16 v[92:95], v[132:135], v[226:229], v[92:95]
	v_mfma_f32_16x16x32_bf16 v[88:91], v[140:143], v[226:229], v[88:91]
	v_mfma_f32_16x16x32_bf16 v[76:79], v[132:135], v[234:237], v[76:79]
	v_mfma_f32_16x16x32_bf16 v[72:75], v[140:143], v[234:237], v[72:75]
	v_mfma_f32_16x16x32_bf16 v[116:119], v[182:185], v[206:209], v[116:119]
	v_mfma_f32_16x16x32_bf16 v[112:115], v[198:201], v[206:209], v[112:115]
	v_mfma_f32_16x16x32_bf16 v[100:103], v[182:185], v[214:217], v[100:103]
	v_mfma_f32_16x16x32_bf16 v[96:99], v[198:201], v[214:217], v[96:99]
	v_mfma_f32_16x16x32_bf16 v[84:87], v[182:185], v[222:225], v[84:87]
	v_mfma_f32_16x16x32_bf16 v[80:83], v[198:201], v[222:225], v[80:83]
	v_mfma_f32_16x16x32_bf16 v[68:71], v[182:185], v[230:233], v[68:71]
	v_mfma_f32_16x16x32_bf16 v[64:67], v[198:201], v[230:233], v[64:67]
	v_mfma_f32_16x16x32_bf16 v[116:119], v[194:197], v[210:213], v[116:119]
	v_mfma_f32_16x16x32_bf16 v[112:115], v[202:205], v[210:213], v[112:115]
	v_mfma_f32_16x16x32_bf16 v[100:103], v[194:197], v[218:221], v[100:103]
	v_mfma_f32_16x16x32_bf16 v[96:99], v[202:205], v[218:221], v[96:99]
	v_mfma_f32_16x16x32_bf16 v[84:87], v[194:197], v[226:229], v[84:87]
	v_mfma_f32_16x16x32_bf16 v[80:83], v[202:205], v[226:229], v[80:83]
	v_mfma_f32_16x16x32_bf16 v[68:71], v[194:197], v[234:237], v[68:71]
	v_mfma_f32_16x16x32_bf16 v[64:67], v[202:205], v[234:237], v[64:67]
	s_setprio 0
	s_barrier
	s_add_i32 s62, s85, s70
	v_lshl_add_u64 v[186:187], s[56:57], 0, v[146:147]
	s_mov_b32 m0, s62
	ds_read_b128 v[206:209], v191 offset:16384
	ds_read_b128 v[210:213], v191 offset:17408
	ds_read_b128 v[214:217], v191 offset:18432
	ds_read_b128 v[218:221], v191 offset:19456
	ds_read_b128 v[222:225], v191 offset:20480
	ds_read_b128 v[226:229], v191 offset:21504
	ds_read_b128 v[230:233], v191 offset:22528
	ds_read_b128 v[234:237], v191 offset:23552
	global_load_lds_dwordx4 v[186:187], off
	s_add_i32 m0, s62, 0x2000
	s_add_u32 s62, s56, 0x80000
	v_lshl_add_u64 v[238:239], s[56:57], 0, v[150:151]
	s_addc_u32 s63, s57, 0
	s_add_i32 s66, s86, s70
	global_load_lds_dwordx4 v[238:239], off
	s_mov_b32 m0, s66
	v_lshl_add_u64 v[242:243], s[58:59], 0, v[148:149]
	global_load_lds_dwordx4 v146, s[62:63]
	s_add_i32 m0, s66, 0x2000
	s_nop 0
	global_load_lds_dwordx4 v150, s[62:63]
	v_lshl_add_u64 v[240:241], s[58:59], 0, v[144:145]
	s_mov_b32 m0, s71
	s_nop 0
	global_load_lds_dwordx4 v[240:241], off
	s_mov_b32 m0, s72
	s_nop 0
	global_load_lds_dwordx4 v[242:243], off
	s_waitcnt vmcnt(8)
	s_waitcnt lgkmcnt(0)
	s_setprio 1
	s_barrier
	v_mfma_f32_16x16x32_bf16 v[60:63], v[128:131], v[206:209], v[60:63]
	v_mfma_f32_16x16x32_bf16 v[56:59], v[136:139], v[206:209], v[56:59]
	v_mfma_f32_16x16x32_bf16 v[44:47], v[128:131], v[214:217], v[44:47]
	v_mfma_f32_16x16x32_bf16 v[40:43], v[136:139], v[214:217], v[40:43]
	v_mfma_f32_16x16x32_bf16 v[28:31], v[128:131], v[222:225], v[28:31]
	v_mfma_f32_16x16x32_bf16 v[24:27], v[136:139], v[222:225], v[24:27]
	v_mfma_f32_16x16x32_bf16 v[12:15], v[128:131], v[230:233], v[12:15]
	v_mfma_f32_16x16x32_bf16 v[8:11], v[136:139], v[230:233], v[8:11]
	v_mfma_f32_16x16x32_bf16 v[60:63], v[132:135], v[210:213], v[60:63]
	v_mfma_f32_16x16x32_bf16 v[56:59], v[140:143], v[210:213], v[56:59]
	v_mfma_f32_16x16x32_bf16 v[44:47], v[132:135], v[218:221], v[44:47]
	v_mfma_f32_16x16x32_bf16 v[40:43], v[140:143], v[218:221], v[40:43]
	v_mfma_f32_16x16x32_bf16 v[28:31], v[132:135], v[226:229], v[28:31]
	v_mfma_f32_16x16x32_bf16 v[24:27], v[140:143], v[226:229], v[24:27]
	v_mfma_f32_16x16x32_bf16 v[12:15], v[132:135], v[234:237], v[12:15]
	v_mfma_f32_16x16x32_bf16 v[8:11], v[140:143], v[234:237], v[8:11]
	v_mfma_f32_16x16x32_bf16 v[52:55], v[182:185], v[206:209], v[52:55]
	v_mfma_f32_16x16x32_bf16 v[48:51], v[198:201], v[206:209], v[48:51]
	v_mfma_f32_16x16x32_bf16 v[36:39], v[182:185], v[214:217], v[36:39]
	v_mfma_f32_16x16x32_bf16 v[32:35], v[198:201], v[214:217], v[32:35]
	v_mfma_f32_16x16x32_bf16 v[20:23], v[182:185], v[222:225], v[20:23]
	v_mfma_f32_16x16x32_bf16 v[16:19], v[198:201], v[222:225], v[16:19]
	v_mfma_f32_16x16x32_bf16 v[4:7], v[182:185], v[230:233], v[4:7]
	v_mfma_f32_16x16x32_bf16 v[0:3], v[198:201], v[230:233], v[0:3]
	v_mfma_f32_16x16x32_bf16 v[52:55], v[194:197], v[210:213], v[52:55]
	v_mfma_f32_16x16x32_bf16 v[48:51], v[202:205], v[210:213], v[48:51]
	v_mfma_f32_16x16x32_bf16 v[36:39], v[194:197], v[218:221], v[36:39]
	v_mfma_f32_16x16x32_bf16 v[32:35], v[202:205], v[218:221], v[32:35]
	v_mfma_f32_16x16x32_bf16 v[20:23], v[194:197], v[226:229], v[20:23]
	v_mfma_f32_16x16x32_bf16 v[16:19], v[202:205], v[226:229], v[16:19]
	v_mfma_f32_16x16x32_bf16 v[4:7], v[194:197], v[234:237], v[4:7]
	v_mfma_f32_16x16x32_bf16 v[0:3], v[202:205], v[234:237], v[0:3]
	s_setprio 0
	s_barrier
; #define PG8_STAGE(bufoff, gbase, voff) do { _Pragma("unroll") for (int _i = 0; _i < 2; ++_i) \
;         __builtin_amdgcn_global_load_lds((const unsigned*)((const char*)(gbase) + (voff)[_i]), (LAS unsigned*)(lds + (bufoff) + ldsw + _i * 8192), 16, 0, 0); } while (0)
; #define PG8_LDA(dst, b, h) do { _Pragma("unroll") for (int m = 0; m < 4; ++m) _Pragma("unroll") for (int k = 0; k < 2; ++k) dst[m][k] = *(const LAS bf16x8*)(lds + PG8_SA(b, h) + aoff + m * 2048 + k * 1024); } while (0)
; #define PG8_LDB(dst, b, h) do { _Pragma("unroll") for (int n = 0; n < 2; ++n) _Pragma("unroll") for (int k = 0; k < 2; ++k) dst[n][k] = *(const LAS bf16x8*)(lds + PG8_SB(b, h) + boff + n * 2048 + k * 1024); } while (0)
; #define PG8_WAIT_V(n) asm volatile("s_waitcnt vmcnt(" #n ")" ::: "memory")
; #define PG8_WAIT_L(n) asm volatile("s_waitcnt lgkmcnt(" #n ")" ::: "memory")
; #define PG8_BAR __builtin_amdgcn_s_barrier()
; #define PG8_SCHED __builtin_amdgcn_sched_barrier(0)
; template <class Epi, bool FP8 = false>
; __device__ __forceinline__ void gemm_phase(LAS unsigned char* lds, const Gemm g, const StaticOrder& S_, const Epi& E, const int tid) {
;     ...
;             PG8_LDB(B0, 1, 0); PG8_LDB(B1, 1, 1); PG8_SCHED; PG8_LDA(At, 1, 0); PG8_STAGE(PG8_SA(0, 1), a2 + hstepA, voffA);
;             PG8_WAIT_V(8); PG8_WAIT_L(0); PG8_BAR; PG8_MMA(0, 0, At, B0); PG8_MMA(0, 1, At, B1); PG8_BAR; PG8_SCHED;
;             PG8_LDA(At, 1, 1); PG8_STAGE(PG8_SB(1, 0), b3, voffB); PG8_STAGE(PG8_SB(1, 1), b3 + hstepB, voffB); PG8_STAGE(PG8_SA(1, 0), a3, voffA);
;             PG8_WAIT_V(8); PG8_WAIT_L(0); PG8_BAR; PG8_MMA(1, 0, At, B0); PG8_MMA(1, 1, At, B1); PG8_BAR; PG8_SCHED;
;         }
;         if (wr == 0) PG8_BAR;
	s_add_i32 s62, 0, 0x18000
	s_add_i32 s63, 0, 0x1c000
	v_add_u32_e32 v140, s62, v163
	v_add_u32_e32 v152, s63, v163
	ds_read_b128 v[128:131], v140
	ds_read_b128 v[132:135], v140 offset:1024
	ds_read_b128 v[136:139], v140 offset:2048
	ds_read_b128 v[140:143], v140 offset:3072
	ds_read_b128 v[182:185], v152
	ds_read_b128 v[194:197], v152 offset:1024
	ds_read_b128 v[198:201], v152 offset:2048
	ds_read_b128 v[202:205], v152 offset:3072
	s_add_u32 s58, s58, 0x80000
	s_addc_u32 s59, s59, 0
	s_mov_b32 m0, s73
	ds_read_b128 v[206:209], v191 offset:32768
	ds_read_b128 v[210:213], v191 offset:33792
	ds_read_b128 v[214:217], v191 offset:34816
	ds_read_b128 v[218:221], v191 offset:35840
	ds_read_b128 v[222:225], v191 offset:36864
	ds_read_b128 v[226:229], v191 offset:37888
	ds_read_b128 v[230:233], v191 offset:38912
	ds_read_b128 v[234:237], v191 offset:39936
	global_load_lds_dwordx4 v144, s[58:59]
	s_mov_b32 m0, s74
	s_nop 0
	global_load_lds_dwordx4 v148, s[58:59]
	s_waitcnt vmcnt(8)
	s_waitcnt lgkmcnt(0)
	s_setprio 1
	s_barrier
	v_mfma_f32_16x16x32_bf16 v[124:127], v[128:131], v[206:209], v[124:127]
	v_mfma_f32_16x16x32_bf16 v[120:123], v[136:139], v[206:209], v[120:123]
	v_mfma_f32_16x16x32_bf16 v[108:111], v[128:131], v[214:217], v[108:111]
	v_mfma_f32_16x16x32_bf16 v[104:107], v[136:139], v[214:217], v[104:107]
	v_mfma_f32_16x16x32_bf16 v[92:95], v[128:131], v[222:225], v[92:95]
	v_mfma_f32_16x16x32_bf16 v[88:91], v[136:139], v[222:225], v[88:91]
	v_mfma_f32_16x16x32_bf16 v[76:79], v[128:131], v[230:233], v[76:79]
	v_mfma_f32_16x16x32_bf16 v[72:75], v[136:139], v[230:233], v[72:75]
	v_mfma_f32_16x16x32_bf16 v[124:127], v[132:135], v[210:213], v[124:127]
	v_mfma_f32_16x16x32_bf16 v[120:123], v[140:143], v[210:213], v[120:123]
	v_mfma_f32_16x16x32_bf16 v[108:111], v[132:135], v[218:221], v[108:111]
	v_mfma_f32_16x16x32_bf16 v[104:107], v[140:143], v[218:221], v[104:107]
	v_mfma_f32_16x16x32_bf16 v[92:95], v[132:135], v[226:229], v[92:95]
	v_mfma_f32_16x16x32_bf16 v[88:91], v[140:143], v[226:229], v[88:91]
	v_mfma_f32_16x16x32_bf16 v[76:79], v[132:135], v[234:237], v[76:79]
	v_mfma_f32_16x16x32_bf16 v[72:75], v[140:143], v[234:237], v[72:75]
	v_mfma_f32_16x16x32_bf16 v[116:119], v[182:185], v[206:209], v[116:119]
	v_mfma_f32_16x16x32_bf16 v[112:115], v[198:201], v[206:209], v[112:115]
	v_mfma_f32_16x16x32_bf16 v[100:103], v[182:185], v[214:217], v[100:103]
	v_mfma_f32_16x16x32_bf16 v[96:99], v[198:201], v[214:217], v[96:99]
	v_mfma_f32_16x16x32_bf16 v[84:87], v[182:185], v[222:225], v[84:87]
	v_mfma_f32_16x16x32_bf16 v[80:83], v[198:201], v[222:225], v[80:83]
	v_mfma_f32_16x16x32_bf16 v[68:71], v[182:185], v[230:233], v[68:71]
	v_mfma_f32_16x16x32_bf16 v[64:67], v[198:201], v[230:233], v[64:67]
	v_mfma_f32_16x16x32_bf16 v[116:119], v[194:197], v[210:213], v[116:119]
	v_mfma_f32_16x16x32_bf16 v[112:115], v[202:205], v[210:213], v[112:115]
	v_mfma_f32_16x16x32_bf16 v[100:103], v[194:197], v[218:221], v[100:103]
	v_mfma_f32_16x16x32_bf16 v[96:99], v[202:205], v[218:221], v[96:99]
	v_mfma_f32_16x16x32_bf16 v[84:87], v[194:197], v[226:229], v[84:87]
	v_mfma_f32_16x16x32_bf16 v[80:83], v[202:205], v[226:229], v[80:83]
	v_mfma_f32_16x16x32_bf16 v[68:71], v[194:197], v[234:237], v[68:71]
	v_mfma_f32_16x16x32_bf16 v[64:67], v[202:205], v[234:237], v[64:67]
	s_setprio 0
	s_barrier
	s_add_i32 s58, s62, s70
	v_lshl_add_u64 v[186:187], v[186:187], 0, s[14:15]
	s_mov_b32 m0, s58
	ds_read_b128 v[206:209], v191 offset:49152
	ds_read_b128 v[210:213], v191 offset:50176
	ds_read_b128 v[214:217], v191 offset:51200
	ds_read_b128 v[218:221], v191 offset:52224
	ds_read_b128 v[222:225], v191 offset:53248
	ds_read_b128 v[226:229], v191 offset:54272
	ds_read_b128 v[230:233], v191 offset:55296
	ds_read_b128 v[234:237], v191 offset:56320
	global_load_lds_dwordx4 v[186:187], off
	s_add_i32 m0, s58, 0x2000
	s_add_u32 s56, s56, 0x80080
	v_lshl_add_u64 v[186:187], v[238:239], 0, s[14:15]
	s_addc_u32 s57, s57, 0
	s_add_i32 s58, s63, s70
	global_load_lds_dwordx4 v[186:187], off
	s_mov_b32 m0, s58
	s_nop 0
	global_load_lds_dwordx4 v146, s[56:57]
	s_add_i32 m0, s58, 0x2000
	s_nop 0
	global_load_lds_dwordx4 v150, s[56:57]
	v_lshl_add_u64 v[186:187], v[240:241], 0, s[14:15]
	s_mov_b32 m0, s79
	s_nop 0
	global_load_lds_dwordx4 v[186:187], off
	v_lshl_add_u64 v[186:187], v[242:243], 0, s[14:15]
	s_mov_b32 m0, s80
	s_nop 0
	global_load_lds_dwordx4 v[186:187], off
	s_waitcnt vmcnt(8)
	s_waitcnt lgkmcnt(0)
	s_setprio 1
	s_barrier
	v_mfma_f32_16x16x32_bf16 v[60:63], v[128:131], v[206:209], v[60:63]
	v_mfma_f32_16x16x32_bf16 v[56:59], v[136:139], v[206:209], v[56:59]
	v_mfma_f32_16x16x32_bf16 v[44:47], v[128:131], v[214:217], v[44:47]
	v_mfma_f32_16x16x32_bf16 v[40:43], v[136:139], v[214:217], v[40:43]
	v_mfma_f32_16x16x32_bf16 v[28:31], v[128:131], v[222:225], v[28:31]
	v_mfma_f32_16x16x32_bf16 v[24:27], v[136:139], v[222:225], v[24:27]
	v_mfma_f32_16x16x32_bf16 v[12:15], v[128:131], v[230:233], v[12:15]
	v_mfma_f32_16x16x32_bf16 v[8:11], v[136:139], v[230:233], v[8:11]
	v_mfma_f32_16x16x32_bf16 v[60:63], v[132:135], v[210:213], v[60:63]
	v_mfma_f32_16x16x32_bf16 v[56:59], v[140:143], v[210:213], v[56:59]
	v_mfma_f32_16x16x32_bf16 v[44:47], v[132:135], v[218:221], v[44:47]
	v_mfma_f32_16x16x32_bf16 v[40:43], v[140:143], v[218:221], v[40:43]
	v_mfma_f32_16x16x32_bf16 v[28:31], v[132:135], v[226:229], v[28:31]
	v_mfma_f32_16x16x32_bf16 v[24:27], v[140:143], v[226:229], v[24:27]
	v_mfma_f32_16x16x32_bf16 v[12:15], v[132:135], v[234:237], v[12:15]
	v_mfma_f32_16x16x32_bf16 v[8:11], v[140:143], v[234:237], v[8:11]
	v_mfma_f32_16x16x32_bf16 v[52:55], v[182:185], v[206:209], v[52:55]
	v_mfma_f32_16x16x32_bf16 v[48:51], v[198:201], v[206:209], v[48:51]
	v_mfma_f32_16x16x32_bf16 v[36:39], v[182:185], v[214:217], v[36:39]
	v_mfma_f32_16x16x32_bf16 v[32:35], v[198:201], v[214:217], v[32:35]
	v_mfma_f32_16x16x32_bf16 v[20:23], v[182:185], v[222:225], v[20:23]
	v_mfma_f32_16x16x32_bf16 v[16:19], v[198:201], v[222:225], v[16:19]
	v_mfma_f32_16x16x32_bf16 v[4:7], v[182:185], v[230:233], v[4:7]
	v_mfma_f32_16x16x32_bf16 v[0:3], v[198:201], v[230:233], v[0:3]
	v_mfma_f32_16x16x32_bf16 v[52:55], v[194:197], v[210:213], v[52:55]
	v_mfma_f32_16x16x32_bf16 v[48:51], v[202:205], v[210:213], v[48:51]
	v_mfma_f32_16x16x32_bf16 v[36:39], v[194:197], v[218:221], v[36:39]
	v_mfma_f32_16x16x32_bf16 v[32:35], v[202:205], v[218:221], v[32:35]
	v_mfma_f32_16x16x32_bf16 v[20:23], v[194:197], v[226:229], v[20:23]
	v_mfma_f32_16x16x32_bf16 v[16:19], v[202:205], v[226:229], v[16:19]
	v_mfma_f32_16x16x32_bf16 v[4:7], v[194:197], v[234:237], v[4:7]
	v_mfma_f32_16x16x32_bf16 v[0:3], v[202:205], v[234:237], v[0:3]
	s_setprio 0
	s_barrier
	s_add_i32 s61, s61, 2
	s_add_u32 s54, s54, 0x100
	s_addc_u32 s55, s55, 0
	s_add_u32 s49, s49, 0x100
	s_addc_u32 s60, s60, 0
	s_cmp_gt_u32 s61, 29
	s_cbranch_scc0 .LBB0_457
	s_and_b64 vcc, exec, s[16:17]
	s_cbranch_vccz .LBB0_460
	s_barrier

; #define PG8_STAGE(bufoff, gbase, voff) do { _Pragma("unroll") for (int _i = 0; _i < 2; ++_i) \
;         __builtin_amdgcn_global_load_lds((const unsigned*)((const char*)(gbase) + (voff)[_i]), (LAS unsigned*)(lds + (bufoff) + ldsw + _i * 8192), 16, 0, 0); } while (0)
; #define PG8_LDA(dst, b, h) do { _Pragma("unroll") for (int m = 0; m < 4; ++m) _Pragma("unroll") for (int k = 0; k < 2; ++k) dst[m][k] = *(const LAS bf16x8*)(lds + PG8_SA(b, h) + aoff + m * 2048 + k * 1024); } while (0)
; #define PG8_LDB(dst, b, h) do { _Pragma("unroll") for (int n = 0; n < 2; ++n) _Pragma("unroll") for (int k = 0; k < 2; ++k) dst[n][k] = *(const LAS bf16x8*)(lds + PG8_SB(b, h) + boff + n * 2048 + k * 1024); } while (0)
; #define PG8_WAIT_V(n) asm volatile("s_waitcnt vmcnt(" #n ")" ::: "memory")
; #define PG8_WAIT_L(n) asm volatile("s_waitcnt lgkmcnt(" #n ")" ::: "memory")
; #define PG8_BAR __builtin_amdgcn_s_barrier()
; #define PG8_SCHED __builtin_amdgcn_sched_barrier(0)
; template <class Epi, bool FP8 = false>
; __device__ __forceinline__ void gemm_phase(LAS unsigned char* lds, const Gemm g, const StaticOrder& S_, const Epi& E, const int tid) {
;     ...
;             PG8_LDB(B0, 0, 0); PG8_LDB(B1, 0, 1); PG8_SCHED; PG8_LDA(At, 0, 0); PG8_STAGE(PG8_SA(1, 1), a1 + hstepA, voffA);
;             PG8_WAIT_V(8); PG8_WAIT_L(0); PG8_BAR; PG8_MMA(0, 0, At, B0); PG8_MMA(0, 1, At, B1); PG8_BAR; PG8_SCHED;
;             PG8_LDA(At, 0, 1); PG8_STAGE(PG8_SB(0, 0), b2, voffB); PG8_STAGE(PG8_SB(0, 1), b2 + hstepB, voffB); PG8_STAGE(PG8_SA(0, 0), a2, voffA);
;             PG8_WAIT_V(8); PG8_WAIT_L(0); PG8_BAR; PG8_MMA(1, 0, At, B0); PG8_MMA(1, 1, At, B1); PG8_BAR; PG8_SCHED;
.LBB0_596:
	ds_read_b128 v[156:159], v197 offset:1024
	ds_read_b128 v[152:155], v197
	ds_read_b128 v[148:151], v197 offset:3072
	ds_read_b128 v[144:147], v197 offset:2048
	ds_read_b128 v[140:143], v198 offset:1024
	ds_read_b128 v[136:139], v198
	ds_read_b128 v[132:135], v198 offset:3072
	ds_read_b128 v[128:131], v198 offset:2048
	s_add_u32 s54, s52, 0xfffc0080
	s_addc_u32 s55, s53, -1
	s_cmp_eq_u32 s85, 12
	s_cselect_b32 s57, s27, s55
	s_cselect_b32 s56, s42, s54
	s_cselect_b32 s55, s25, s84
	s_cselect_b32 s54, s43, s66
	s_add_i32 m0, s63, 0xc000
	ds_read_b128 v[186:189], v199
	ds_read_b128 v[190:193], v199 offset:1024
	ds_read_b128 v[200:203], v199 offset:2048
	ds_read_b128 v[204:207], v199 offset:3072
	ds_read_b128 v[208:211], v199 offset:4096
	ds_read_b128 v[212:215], v199 offset:5120
	ds_read_b128 v[216:219], v199 offset:6144
	ds_read_b128 v[220:223], v199 offset:7168
	global_load_lds_dwordx4 v178, s[52:53]
	s_add_i32 m0, s63, 0xe000
	s_nop 0
	global_load_lds_dwordx4 v180, s[52:53]
	s_waitcnt vmcnt(8)
	s_waitcnt lgkmcnt(0)
	s_setprio 1
	s_barrier
	v_mfma_f32_16x16x128_f8f6f4 v[124:127], v[152:159], v[186:193], v[124:127]
	v_mfma_f32_16x16x128_f8f6f4 v[120:123], v[144:151], v[186:193], v[120:123]
	v_mfma_f32_16x16x128_f8f6f4 v[112:115], v[152:159], v[200:207], v[112:115]
	v_mfma_f32_16x16x128_f8f6f4 v[104:107], v[144:151], v[200:207], v[104:107]
	v_mfma_f32_16x16x128_f8f6f4 v[96:99], v[152:159], v[208:215], v[96:99]
	v_mfma_f32_16x16x128_f8f6f4 v[88:91], v[144:151], v[208:215], v[88:91]
	v_mfma_f32_16x16x128_f8f6f4 v[84:87], v[152:159], v[216:223], v[84:87]
	v_mfma_f32_16x16x128_f8f6f4 v[72:75], v[144:151], v[216:223], v[72:75]
	v_mfma_f32_16x16x128_f8f6f4 v[116:119], v[136:143], v[186:193], v[116:119]
	v_mfma_f32_16x16x128_f8f6f4 v[108:111], v[128:135], v[186:193], v[108:111]
	v_mfma_f32_16x16x128_f8f6f4 v[100:103], v[136:143], v[200:207], v[100:103]
	v_mfma_f32_16x16x128_f8f6f4 v[92:95], v[128:135], v[200:207], v[92:95]
	v_mfma_f32_16x16x128_f8f6f4 v[80:83], v[136:143], v[208:215], v[80:83]
	v_mfma_f32_16x16x128_f8f6f4 v[76:79], v[128:135], v[208:215], v[76:79]
	v_mfma_f32_16x16x128_f8f6f4 v[68:71], v[136:143], v[216:223], v[68:71]
	v_mfma_f32_16x16x128_f8f6f4 v[64:67], v[128:135], v[216:223], v[64:67]
	s_setprio 0
	s_barrier
	s_add_i32 s86, s74, s60
	v_lshl_add_u64 v[186:187], s[54:55], 0, v[160:161]
	s_mov_b32 m0, s86
	ds_read_b128 v[200:203], v199 offset:16384
	ds_read_b128 v[204:207], v199 offset:17408
	ds_read_b128 v[208:211], v199 offset:18432
	ds_read_b128 v[212:215], v199 offset:19456
	ds_read_b128 v[216:219], v199 offset:20480
	ds_read_b128 v[220:223], v199 offset:21504
	ds_read_b128 v[224:227], v199 offset:22528
	ds_read_b128 v[228:231], v199 offset:23552
	global_load_lds_dwordx4 v[186:187], off
	s_add_i32 m0, s86, 0x2000
	s_add_u32 s86, s54, 0x40000
	v_lshl_add_u64 v[188:189], s[54:55], 0, v[162:163]
	s_addc_u32 s87, s55, 0
	s_add_i32 s88, s75, s60
	global_load_lds_dwordx4 v[188:189], off
	s_mov_b32 m0, s88
	v_lshl_add_u64 v[192:193], s[56:57], 0, v[164:165]
	global_load_lds_dwordx4 v160, s[86:87]
	s_add_i32 m0, s88, 0x2000
	s_nop 0
	global_load_lds_dwordx4 v162, s[86:87]
	v_lshl_add_u64 v[190:191], s[56:57], 0, v[166:167]
	s_mov_b32 m0, s63
	s_nop 0
	global_load_lds_dwordx4 v[190:191], off
	s_mov_b32 m0, s68
	s_nop 0
	global_load_lds_dwordx4 v[192:193], off
	s_waitcnt vmcnt(8)
	s_waitcnt lgkmcnt(0)
	s_setprio 1
	s_barrier
	v_mfma_f32_16x16x128_f8f6f4 v[60:63], v[152:159], v[200:207], v[60:63]
	v_mfma_f32_16x16x128_f8f6f4 v[56:59], v[144:151], v[200:207], v[56:59]
	v_mfma_f32_16x16x128_f8f6f4 v[48:51], v[152:159], v[208:215], v[48:51]
	v_mfma_f32_16x16x128_f8f6f4 v[40:43], v[144:151], v[208:215], v[40:43]
	v_mfma_f32_16x16x128_f8f6f4 v[32:35], v[152:159], v[216:223], v[32:35]
	v_mfma_f32_16x16x128_f8f6f4 v[24:27], v[144:151], v[216:223], v[24:27]
	v_mfma_f32_16x16x128_f8f6f4 v[16:19], v[152:159], v[224:231], v[16:19]
	v_mfma_f32_16x16x128_f8f6f4 v[8:11], v[144:151], v[224:231], v[8:11]
	v_mfma_f32_16x16x128_f8f6f4 v[52:55], v[136:143], v[200:207], v[52:55]
	v_mfma_f32_16x16x128_f8f6f4 v[44:47], v[128:135], v[200:207], v[44:47]
	v_mfma_f32_16x16x128_f8f6f4 v[36:39], v[136:143], v[208:215], v[36:39]
	v_mfma_f32_16x16x128_f8f6f4 v[28:31], v[128:135], v[208:215], v[28:31]
	v_mfma_f32_16x16x128_f8f6f4 v[20:23], v[136:143], v[216:223], v[20:23]
	v_mfma_f32_16x16x128_f8f6f4 v[12:15], v[128:135], v[216:223], v[12:15]
	v_mfma_f32_16x16x128_f8f6f4 v[4:7], v[136:143], v[224:231], v[4:7]
	v_mfma_f32_16x16x128_f8f6f4 v[0:3], v[128:135], v[224:231], v[0:3]
	s_setprio 0
	s_barrier
; #define PG8_STAGE(bufoff, gbase, voff) do { _Pragma("unroll") for (int _i = 0; _i < 2; ++_i) \
;         __builtin_amdgcn_global_load_lds((const unsigned*)((const char*)(gbase) + (voff)[_i]), (LAS unsigned*)(lds + (bufoff) + ldsw + _i * 8192), 16, 0, 0); } while (0)
; #define PG8_LDA(dst, b, h) do { _Pragma("unroll") for (int m = 0; m < 4; ++m) _Pragma("unroll") for (int k = 0; k < 2; ++k) dst[m][k] = *(const LAS bf16x8*)(lds + PG8_SA(b, h) + aoff + m * 2048 + k * 1024); } while (0)
; #define PG8_LDB(dst, b, h) do { _Pragma("unroll") for (int n = 0; n < 2; ++n) _Pragma("unroll") for (int k = 0; k < 2; ++k) dst[n][k] = *(const LAS bf16x8*)(lds + PG8_SB(b, h) + boff + n * 2048 + k * 1024); } while (0)
; #define PG8_WAIT_V(n) asm volatile("s_waitcnt vmcnt(" #n ")" ::: "memory")
; #define PG8_WAIT_L(n) asm volatile("s_waitcnt lgkmcnt(" #n ")" ::: "memory")
; #define PG8_BAR __builtin_amdgcn_s_barrier()
; #define PG8_SCHED __builtin_amdgcn_sched_barrier(0)
; template <class Epi, bool FP8 = false>
; __device__ __forceinline__ void gemm_phase(LAS unsigned char* lds, const Gemm g, const StaticOrder& S_, const Epi& E, const int tid) {
;     ...
;             PG8_LDB(B0, 1, 0); PG8_LDB(B1, 1, 1); PG8_SCHED; PG8_LDA(At, 1, 0); PG8_STAGE(PG8_SA(0, 1), a2 + hstepA, voffA);
;             PG8_WAIT_V(8); PG8_WAIT_L(0); PG8_BAR; PG8_MMA(0, 0, At, B0); PG8_MMA(0, 1, At, B1); PG8_BAR; PG8_SCHED;
;             PG8_LDA(At, 1, 1); PG8_STAGE(PG8_SB(1, 0), b3, voffB); PG8_STAGE(PG8_SB(1, 1), b3 + hstepB, voffB); PG8_STAGE(PG8_SA(1, 0), a3, voffA);
;             PG8_WAIT_V(8); PG8_WAIT_L(0); PG8_BAR; PG8_MMA(1, 0, At, B0); PG8_MMA(1, 1, At, B1); PG8_BAR; PG8_SCHED;
;         }
;         if (wr == 0) PG8_BAR;
	s_add_i32 s86, 0, 0x18000
	v_add_u32_e32 v128, s86, v195
	s_add_i32 s87, 0, 0x1c000
	ds_read_b128 v[156:159], v128 offset:1024
	ds_read_b128 v[152:155], v128
	ds_read_b128 v[148:151], v128 offset:3072
	ds_read_b128 v[144:147], v128 offset:2048
	v_add_u32_e32 v128, s87, v195
	ds_read_b128 v[140:143], v128 offset:1024
	ds_read_b128 v[136:139], v128
	ds_read_b128 v[132:135], v128 offset:3072
	ds_read_b128 v[128:131], v128 offset:2048
	s_add_u32 s56, s56, 0x40000
	s_addc_u32 s57, s57, 0
	s_mov_b32 m0, s69
	ds_read_b128 v[200:203], v199 offset:32768
	ds_read_b128 v[204:207], v199 offset:33792
	ds_read_b128 v[208:211], v199 offset:34816
	ds_read_b128 v[212:215], v199 offset:35840
	ds_read_b128 v[216:219], v199 offset:36864
	ds_read_b128 v[220:223], v199 offset:37888
	ds_read_b128 v[224:227], v199 offset:38912
	ds_read_b128 v[228:231], v199 offset:39936
	global_load_lds_dwordx4 v166, s[56:57]
	s_mov_b32 m0, s70
	s_nop 0
	global_load_lds_dwordx4 v164, s[56:57]
	s_waitcnt vmcnt(8)
	s_waitcnt lgkmcnt(0)
	s_setprio 1
	s_barrier
	v_mfma_f32_16x16x128_f8f6f4 v[124:127], v[152:159], v[200:207], v[124:127]
	v_mfma_f32_16x16x128_f8f6f4 v[120:123], v[144:151], v[200:207], v[120:123]
	v_mfma_f32_16x16x128_f8f6f4 v[112:115], v[152:159], v[208:215], v[112:115]
	v_mfma_f32_16x16x128_f8f6f4 v[104:107], v[144:151], v[208:215], v[104:107]
	v_mfma_f32_16x16x128_f8f6f4 v[96:99], v[152:159], v[216:223], v[96:99]
	v_mfma_f32_16x16x128_f8f6f4 v[88:91], v[144:151], v[216:223], v[88:91]
	v_mfma_f32_16x16x128_f8f6f4 v[84:87], v[152:159], v[224:231], v[84:87]
	v_mfma_f32_16x16x128_f8f6f4 v[72:75], v[144:151], v[224:231], v[72:75]
	v_mfma_f32_16x16x128_f8f6f4 v[116:119], v[136:143], v[200:207], v[116:119]
	v_mfma_f32_16x16x128_f8f6f4 v[108:111], v[128:135], v[200:207], v[108:111]
	v_mfma_f32_16x16x128_f8f6f4 v[100:103], v[136:143], v[208:215], v[100:103]
	v_mfma_f32_16x16x128_f8f6f4 v[92:95], v[128:135], v[208:215], v[92:95]
	v_mfma_f32_16x16x128_f8f6f4 v[80:83], v[136:143], v[216:223], v[80:83]
	v_mfma_f32_16x16x128_f8f6f4 v[76:79], v[128:135], v[216:223], v[76:79]
	v_mfma_f32_16x16x128_f8f6f4 v[68:71], v[136:143], v[224:231], v[68:71]
	v_mfma_f32_16x16x128_f8f6f4 v[64:67], v[128:135], v[224:231], v[64:67]
	s_setprio 0
	s_barrier
	s_add_i32 s56, s86, s60
	v_lshl_add_u64 v[186:187], v[186:187], 0, s[10:11]
	s_mov_b32 m0, s56
	ds_read_b128 v[200:203], v199 offset:49152
	ds_read_b128 v[204:207], v199 offset:50176
	ds_read_b128 v[208:211], v199 offset:51200
	ds_read_b128 v[212:215], v199 offset:52224
	ds_read_b128 v[216:219], v199 offset:53248
	ds_read_b128 v[220:223], v199 offset:54272
	ds_read_b128 v[224:227], v199 offset:55296
	ds_read_b128 v[228:231], v199 offset:56320
	global_load_lds_dwordx4 v[186:187], off
	s_add_i32 m0, s56, 0x2000
	s_add_u32 s54, s54, 0x40080
	v_lshl_add_u64 v[186:187], v[188:189], 0, s[10:11]
	s_addc_u32 s55, s55, 0
	s_add_i32 s56, s87, s60
	global_load_lds_dwordx4 v[186:187], off
	s_mov_b32 m0, s56
	s_nop 0
	global_load_lds_dwordx4 v160, s[54:55]
	s_add_i32 m0, s56, 0x2000
	s_nop 0
	global_load_lds_dwordx4 v162, s[54:55]
	v_lshl_add_u64 v[186:187], v[190:191], 0, s[10:11]
	s_mov_b32 m0, s72
	s_nop 0
	global_load_lds_dwordx4 v[186:187], off
	v_lshl_add_u64 v[186:187], v[192:193], 0, s[10:11]
	s_mov_b32 m0, s73
	s_nop 0
	global_load_lds_dwordx4 v[186:187], off
	s_waitcnt vmcnt(8)
	s_waitcnt lgkmcnt(0)
	s_setprio 1
	s_barrier
	v_mfma_f32_16x16x128_f8f6f4 v[60:63], v[152:159], v[200:207], v[60:63]
	v_mfma_f32_16x16x128_f8f6f4 v[56:59], v[144:151], v[200:207], v[56:59]
	v_mfma_f32_16x16x128_f8f6f4 v[48:51], v[152:159], v[208:215], v[48:51]
	v_mfma_f32_16x16x128_f8f6f4 v[40:43], v[144:151], v[208:215], v[40:43]
	v_mfma_f32_16x16x128_f8f6f4 v[32:35], v[152:159], v[216:223], v[32:35]
	v_mfma_f32_16x16x128_f8f6f4 v[24:27], v[144:151], v[216:223], v[24:27]
	v_mfma_f32_16x16x128_f8f6f4 v[16:19], v[152:159], v[224:231], v[16:19]
	v_mfma_f32_16x16x128_f8f6f4 v[8:11], v[144:151], v[224:231], v[8:11]
	v_mfma_f32_16x16x128_f8f6f4 v[52:55], v[136:143], v[200:207], v[52:55]
	v_mfma_f32_16x16x128_f8f6f4 v[44:47], v[128:135], v[200:207], v[44:47]
	v_mfma_f32_16x16x128_f8f6f4 v[36:39], v[136:143], v[208:215], v[36:39]
	v_mfma_f32_16x16x128_f8f6f4 v[28:31], v[128:135], v[208:215], v[28:31]
	v_mfma_f32_16x16x128_f8f6f4 v[20:23], v[136:143], v[216:223], v[20:23]
	v_mfma_f32_16x16x128_f8f6f4 v[12:15], v[128:135], v[216:223], v[12:15]
	v_mfma_f32_16x16x128_f8f6f4 v[4:7], v[136:143], v[224:231], v[4:7]
	v_mfma_f32_16x16x128_f8f6f4 v[0:3], v[128:135], v[224:231], v[0:3]
	s_setprio 0
	s_barrier
	s_add_i32 s85, s85, 2
	s_add_u32 s52, s52, 0x100
	s_addc_u32 s53, s53, 0
	s_add_u32 s66, s66, 0x100
	s_addc_u32 s84, s84, 0
	s_cmp_gt_u32 s85, 13
	s_cbranch_scc0 .LBB0_596
	s_and_b64 vcc, exec, s[12:13]
	s_cbranch_vccz .LBB0_599
	s_barrier

; #define PG8_STAGE(bufoff, gbase, voff) do { _Pragma("unroll") for (int _i = 0; _i < 2; ++_i) \
;         __builtin_amdgcn_global_load_lds((const unsigned*)((const char*)(gbase) + (voff)[_i]), (LAS unsigned*)(lds + (bufoff) + ldsw + _i * 8192), 16, 0, 0); } while (0)
; #define PG8_LDA(dst, b, h) do { _Pragma("unroll") for (int m = 0; m < 4; ++m) _Pragma("unroll") for (int k = 0; k < 2; ++k) dst[m][k] = *(const LAS bf16x8*)(lds + PG8_SA(b, h) + aoff + m * 2048 + k * 1024); } while (0)
; #define PG8_LDB(dst, b, h) do { _Pragma("unroll") for (int n = 0; n < 2; ++n) _Pragma("unroll") for (int k = 0; k < 2; ++k) dst[n][k] = *(const LAS bf16x8*)(lds + PG8_SB(b, h) + boff + n * 2048 + k * 1024); } while (0)
; #define PG8_WAIT_V(n) asm volatile("s_waitcnt vmcnt(" #n ")" ::: "memory")
; #define PG8_WAIT_L(n) asm volatile("s_waitcnt lgkmcnt(" #n ")" ::: "memory")
; #define PG8_BAR __builtin_amdgcn_s_barrier()
; #define PG8_SCHED __builtin_amdgcn_sched_barrier(0)
; template <class Epi, bool FP8 = false>
; __device__ __forceinline__ void gemm_phase(LAS unsigned char* lds, const Gemm g, const StaticOrder& S_, const Epi& E, const int tid) {
;     ...
;             PG8_LDB(B0, 0, 0); PG8_LDB(B1, 0, 1); PG8_SCHED; PG8_LDA(At, 0, 0); PG8_STAGE(PG8_SA(1, 1), a1 + hstepA, voffA);
;             PG8_WAIT_V(8); PG8_WAIT_L(0); PG8_BAR; PG8_MMA(0, 0, At, B0); PG8_MMA(0, 1, At, B1); PG8_BAR; PG8_SCHED;
;             PG8_LDA(At, 0, 1); PG8_STAGE(PG8_SB(0, 0), b2, voffB); PG8_STAGE(PG8_SB(0, 1), b2 + hstepB, voffB); PG8_STAGE(PG8_SA(0, 0), a2, voffA);
;             PG8_WAIT_V(8); PG8_WAIT_L(0); PG8_BAR; PG8_MMA(1, 0, At, B0); PG8_MMA(1, 1, At, B1); PG8_BAR; PG8_SCHED;
.LBB0_1095:
	ds_read_b128 v[144:147], v174
	ds_read_b128 v[178:181], v174 offset:1024
	ds_read_b128 v[182:185], v174 offset:2048
	ds_read_b128 v[186:189], v174 offset:3072
	ds_read_b128 v[190:193], v175
	ds_read_b128 v[194:197], v175 offset:1024
	ds_read_b128 v[198:201], v175 offset:2048
	ds_read_b128 v[202:205], v175 offset:3072
	s_add_u32 s8, s26, 0x100
	s_addc_u32 s9, s27, 0
	s_cmp_eq_u32 s69, 12
	s_cselect_b32 s49, s23, s9
	s_cselect_b32 s48, s22, s8
	s_cselect_b32 s47, s21, s68
	s_cselect_b32 s46, s66, s67
	s_add_i32 m0, s54, 0xc000
	ds_read_b128 v[206:209], v176
	ds_read_b128 v[210:213], v176 offset:1024
	ds_read_b128 v[214:217], v176 offset:2048
	ds_read_b128 v[218:221], v176 offset:3072
	ds_read_b128 v[222:225], v176 offset:4096
	ds_read_b128 v[226:229], v176 offset:5120
	ds_read_b128 v[230:233], v176 offset:6144
	ds_read_b128 v[234:237], v176 offset:7168
	global_load_lds_dwordx4 v136, s[26:27]
	s_add_i32 m0, s54, 0xe000
	s_nop 0
	global_load_lds_dwordx4 v138, s[26:27]
	s_waitcnt vmcnt(8)
	s_waitcnt lgkmcnt(0)
	s_setprio 1
	s_barrier
	v_mfma_f32_16x16x32_bf16 v[124:127], v[144:147], v[206:209], v[124:127]
	v_mfma_f32_16x16x32_bf16 v[120:123], v[182:185], v[206:209], v[120:123]
	v_mfma_f32_16x16x32_bf16 v[108:111], v[144:147], v[214:217], v[108:111]
	v_mfma_f32_16x16x32_bf16 v[104:107], v[182:185], v[214:217], v[104:107]
	v_mfma_f32_16x16x32_bf16 v[92:95], v[144:147], v[222:225], v[92:95]
	v_mfma_f32_16x16x32_bf16 v[88:91], v[182:185], v[222:225], v[88:91]
	v_mfma_f32_16x16x32_bf16 v[76:79], v[144:147], v[230:233], v[76:79]
	v_mfma_f32_16x16x32_bf16 v[72:75], v[182:185], v[230:233], v[72:75]
	v_mfma_f32_16x16x32_bf16 v[124:127], v[178:181], v[210:213], v[124:127]
	v_mfma_f32_16x16x32_bf16 v[120:123], v[186:189], v[210:213], v[120:123]
	v_mfma_f32_16x16x32_bf16 v[108:111], v[178:181], v[218:221], v[108:111]
	v_mfma_f32_16x16x32_bf16 v[104:107], v[186:189], v[218:221], v[104:107]
	v_mfma_f32_16x16x32_bf16 v[92:95], v[178:181], v[226:229], v[92:95]
	v_mfma_f32_16x16x32_bf16 v[88:91], v[186:189], v[226:229], v[88:91]
	v_mfma_f32_16x16x32_bf16 v[76:79], v[178:181], v[234:237], v[76:79]
	v_mfma_f32_16x16x32_bf16 v[72:75], v[186:189], v[234:237], v[72:75]
	v_mfma_f32_16x16x32_bf16 v[116:119], v[190:193], v[206:209], v[116:119]
	v_mfma_f32_16x16x32_bf16 v[112:115], v[198:201], v[206:209], v[112:115]
	v_mfma_f32_16x16x32_bf16 v[100:103], v[190:193], v[214:217], v[100:103]
	v_mfma_f32_16x16x32_bf16 v[96:99], v[198:201], v[214:217], v[96:99]
	v_mfma_f32_16x16x32_bf16 v[84:87], v[190:193], v[222:225], v[84:87]
	v_mfma_f32_16x16x32_bf16 v[80:83], v[198:201], v[222:225], v[80:83]
	v_mfma_f32_16x16x32_bf16 v[68:71], v[190:193], v[230:233], v[68:71]
	v_mfma_f32_16x16x32_bf16 v[64:67], v[198:201], v[230:233], v[64:67]
	v_mfma_f32_16x16x32_bf16 v[116:119], v[194:197], v[210:213], v[116:119]
	v_mfma_f32_16x16x32_bf16 v[112:115], v[202:205], v[210:213], v[112:115]
	v_mfma_f32_16x16x32_bf16 v[100:103], v[194:197], v[218:221], v[100:103]
	v_mfma_f32_16x16x32_bf16 v[96:99], v[202:205], v[218:221], v[96:99]
	v_mfma_f32_16x16x32_bf16 v[84:87], v[194:197], v[226:229], v[84:87]
	v_mfma_f32_16x16x32_bf16 v[80:83], v[202:205], v[226:229], v[80:83]
	v_mfma_f32_16x16x32_bf16 v[68:71], v[194:197], v[234:237], v[68:71]
	v_mfma_f32_16x16x32_bf16 v[64:67], v[202:205], v[234:237], v[64:67]
	s_setprio 0
	s_barrier
	s_add_i32 s26, s61, s53
	v_lshl_add_u64 v[238:239], s[46:47], 0, v[132:133]
	s_mov_b32 m0, s26
	ds_read_b128 v[206:209], v176 offset:16384
	ds_read_b128 v[210:213], v176 offset:17408
	ds_read_b128 v[214:217], v176 offset:18432
	ds_read_b128 v[218:221], v176 offset:19456
	ds_read_b128 v[222:225], v176 offset:20480
	ds_read_b128 v[226:229], v176 offset:21504
	ds_read_b128 v[230:233], v176 offset:22528
	ds_read_b128 v[234:237], v176 offset:23552
	global_load_lds_dwordx4 v[238:239], off
	s_add_i32 m0, s26, 0x2000
	s_add_u32 s26, s46, 0x40000
	v_lshl_add_u64 v[240:241], s[46:47], 0, v[134:135]
	s_addc_u32 s27, s47, 0
	s_add_i32 s70, s62, s53
	global_load_lds_dwordx4 v[240:241], off
	s_mov_b32 m0, s70
	v_lshl_add_u64 v[244:245], s[48:49], 0, v[130:131]
	global_load_lds_dwordx4 v132, s[26:27]
	s_add_i32 m0, s70, 0x2000
	s_nop 0
	global_load_lds_dwordx4 v134, s[26:27]
	v_lshl_add_u64 v[242:243], s[48:49], 0, v[128:129]
	s_mov_b32 m0, s54
	s_nop 0
	global_load_lds_dwordx4 v[242:243], off
	s_mov_b32 m0, s55
	s_nop 0
	global_load_lds_dwordx4 v[244:245], off
	s_waitcnt vmcnt(8)
	s_waitcnt lgkmcnt(0)
	s_setprio 1
	s_barrier
	v_mfma_f32_16x16x32_bf16 v[60:63], v[144:147], v[206:209], v[60:63]
	v_mfma_f32_16x16x32_bf16 v[56:59], v[182:185], v[206:209], v[56:59]
	v_mfma_f32_16x16x32_bf16 v[44:47], v[144:147], v[214:217], v[44:47]
	v_mfma_f32_16x16x32_bf16 v[40:43], v[182:185], v[214:217], v[40:43]
	v_mfma_f32_16x16x32_bf16 v[28:31], v[144:147], v[222:225], v[28:31]
	v_mfma_f32_16x16x32_bf16 v[24:27], v[182:185], v[222:225], v[24:27]
	v_mfma_f32_16x16x32_bf16 v[12:15], v[144:147], v[230:233], v[12:15]
	v_mfma_f32_16x16x32_bf16 v[8:11], v[182:185], v[230:233], v[8:11]
	v_mfma_f32_16x16x32_bf16 v[60:63], v[178:181], v[210:213], v[60:63]
	v_mfma_f32_16x16x32_bf16 v[56:59], v[186:189], v[210:213], v[56:59]
	v_mfma_f32_16x16x32_bf16 v[44:47], v[178:181], v[218:221], v[44:47]
	v_mfma_f32_16x16x32_bf16 v[40:43], v[186:189], v[218:221], v[40:43]
	v_mfma_f32_16x16x32_bf16 v[28:31], v[178:181], v[226:229], v[28:31]
	v_mfma_f32_16x16x32_bf16 v[24:27], v[186:189], v[226:229], v[24:27]
	v_mfma_f32_16x16x32_bf16 v[12:15], v[178:181], v[234:237], v[12:15]
	v_mfma_f32_16x16x32_bf16 v[8:11], v[186:189], v[234:237], v[8:11]
	v_mfma_f32_16x16x32_bf16 v[52:55], v[190:193], v[206:209], v[52:55]
	v_mfma_f32_16x16x32_bf16 v[48:51], v[198:201], v[206:209], v[48:51]
	v_mfma_f32_16x16x32_bf16 v[36:39], v[190:193], v[214:217], v[36:39]
	v_mfma_f32_16x16x32_bf16 v[32:35], v[198:201], v[214:217], v[32:35]
	v_mfma_f32_16x16x32_bf16 v[20:23], v[190:193], v[222:225], v[20:23]
	v_mfma_f32_16x16x32_bf16 v[16:19], v[198:201], v[222:225], v[16:19]
	v_mfma_f32_16x16x32_bf16 v[4:7], v[190:193], v[230:233], v[4:7]
	v_mfma_f32_16x16x32_bf16 v[0:3], v[198:201], v[230:233], v[0:3]
	v_mfma_f32_16x16x32_bf16 v[52:55], v[194:197], v[210:213], v[52:55]
	v_mfma_f32_16x16x32_bf16 v[48:51], v[202:205], v[210:213], v[48:51]
	v_mfma_f32_16x16x32_bf16 v[36:39], v[194:197], v[218:221], v[36:39]
	v_mfma_f32_16x16x32_bf16 v[32:35], v[202:205], v[218:221], v[32:35]
	v_mfma_f32_16x16x32_bf16 v[20:23], v[194:197], v[226:229], v[20:23]
	v_mfma_f32_16x16x32_bf16 v[16:19], v[202:205], v[226:229], v[16:19]
	v_mfma_f32_16x16x32_bf16 v[4:7], v[194:197], v[234:237], v[4:7]
	v_mfma_f32_16x16x32_bf16 v[0:3], v[202:205], v[234:237], v[0:3]
	s_setprio 0
	s_barrier
; #define PG8_STAGE(bufoff, gbase, voff) do { _Pragma("unroll") for (int _i = 0; _i < 2; ++_i) \
;         __builtin_amdgcn_global_load_lds((const unsigned*)((const char*)(gbase) + (voff)[_i]), (LAS unsigned*)(lds + (bufoff) + ldsw + _i * 8192), 16, 0, 0); } while (0)
; #define PG8_LDA(dst, b, h) do { _Pragma("unroll") for (int m = 0; m < 4; ++m) _Pragma("unroll") for (int k = 0; k < 2; ++k) dst[m][k] = *(const LAS bf16x8*)(lds + PG8_SA(b, h) + aoff + m * 2048 + k * 1024); } while (0)
; #define PG8_LDB(dst, b, h) do { _Pragma("unroll") for (int n = 0; n < 2; ++n) _Pragma("unroll") for (int k = 0; k < 2; ++k) dst[n][k] = *(const LAS bf16x8*)(lds + PG8_SB(b, h) + boff + n * 2048 + k * 1024); } while (0)
; #define PG8_WAIT_V(n) asm volatile("s_waitcnt vmcnt(" #n ")" ::: "memory")
; #define PG8_WAIT_L(n) asm volatile("s_waitcnt lgkmcnt(" #n ")" ::: "memory")
; #define PG8_BAR __builtin_amdgcn_s_barrier()
; #define PG8_SCHED __builtin_amdgcn_sched_barrier(0)
; template <class Epi, bool FP8 = false>
; __device__ __forceinline__ void gemm_phase(LAS unsigned char* lds, const Gemm g, const StaticOrder& S_, const Epi& E, const int tid) {
;     ...
;             PG8_LDB(B0, 1, 0); PG8_LDB(B1, 1, 1); PG8_SCHED; PG8_LDA(At, 1, 0); PG8_STAGE(PG8_SA(0, 1), a2 + hstepA, voffA);
;             PG8_WAIT_V(8); PG8_WAIT_L(0); PG8_BAR; PG8_MMA(0, 0, At, B0); PG8_MMA(0, 1, At, B1); PG8_BAR; PG8_SCHED;
;             PG8_LDA(At, 1, 1); PG8_STAGE(PG8_SB(1, 0), b3, voffB); PG8_STAGE(PG8_SB(1, 1), b3 + hstepB, voffB); PG8_STAGE(PG8_SA(1, 0), a3, voffA);
;             PG8_WAIT_V(8); PG8_WAIT_L(0); PG8_BAR; PG8_MMA(1, 0, At, B0); PG8_MMA(1, 1, At, B1); PG8_BAR; PG8_SCHED;
;         }
;         if (wr == 0) PG8_BAR;
	s_add_i32 s70, 0, 0x18000
	v_add_u32_e32 v177, s70, v172
	s_add_i32 s71, 0, 0x1c000
	ds_read_b128 v[144:147], v177
	ds_read_b128 v[178:181], v177 offset:1024
	ds_read_b128 v[182:185], v177 offset:2048
	ds_read_b128 v[186:189], v177 offset:3072
	v_add_u32_e32 v177, s71, v172
	ds_read_b128 v[190:193], v177
	ds_read_b128 v[194:197], v177 offset:1024
	ds_read_b128 v[198:201], v177 offset:2048
	ds_read_b128 v[202:205], v177 offset:3072
	s_add_u32 s26, s48, 0x60000
	s_addc_u32 s27, s49, 0
	s_mov_b32 m0, s56
	ds_read_b128 v[206:209], v176 offset:32768
	ds_read_b128 v[210:213], v176 offset:33792
	ds_read_b128 v[214:217], v176 offset:34816
	ds_read_b128 v[218:221], v176 offset:35840
	ds_read_b128 v[222:225], v176 offset:36864
	ds_read_b128 v[226:229], v176 offset:37888
	ds_read_b128 v[230:233], v176 offset:38912
	ds_read_b128 v[234:237], v176 offset:39936
	global_load_lds_dwordx4 v128, s[26:27]
	s_mov_b32 m0, s57
	s_nop 0
	global_load_lds_dwordx4 v130, s[26:27]
	s_waitcnt vmcnt(8)
	s_waitcnt lgkmcnt(0)
	s_setprio 1
	s_barrier
	v_mfma_f32_16x16x32_bf16 v[124:127], v[144:147], v[206:209], v[124:127]
	v_mfma_f32_16x16x32_bf16 v[120:123], v[182:185], v[206:209], v[120:123]
	v_mfma_f32_16x16x32_bf16 v[108:111], v[144:147], v[214:217], v[108:111]
	v_mfma_f32_16x16x32_bf16 v[104:107], v[182:185], v[214:217], v[104:107]
	v_mfma_f32_16x16x32_bf16 v[92:95], v[144:147], v[222:225], v[92:95]
	v_mfma_f32_16x16x32_bf16 v[88:91], v[182:185], v[222:225], v[88:91]
	v_mfma_f32_16x16x32_bf16 v[76:79], v[144:147], v[230:233], v[76:79]
	v_mfma_f32_16x16x32_bf16 v[72:75], v[182:185], v[230:233], v[72:75]
	v_mfma_f32_16x16x32_bf16 v[124:127], v[178:181], v[210:213], v[124:127]
	v_mfma_f32_16x16x32_bf16 v[120:123], v[186:189], v[210:213], v[120:123]
	v_mfma_f32_16x16x32_bf16 v[108:111], v[178:181], v[218:221], v[108:111]
	v_mfma_f32_16x16x32_bf16 v[104:107], v[186:189], v[218:221], v[104:107]
	v_mfma_f32_16x16x32_bf16 v[92:95], v[178:181], v[226:229], v[92:95]
	v_mfma_f32_16x16x32_bf16 v[88:91], v[186:189], v[226:229], v[88:91]
	v_mfma_f32_16x16x32_bf16 v[76:79], v[178:181], v[234:237], v[76:79]
	v_mfma_f32_16x16x32_bf16 v[72:75], v[186:189], v[234:237], v[72:75]
	v_mfma_f32_16x16x32_bf16 v[116:119], v[190:193], v[206:209], v[116:119]
	v_mfma_f32_16x16x32_bf16 v[112:115], v[198:201], v[206:209], v[112:115]
	v_mfma_f32_16x16x32_bf16 v[100:103], v[190:193], v[214:217], v[100:103]
	v_mfma_f32_16x16x32_bf16 v[96:99], v[198:201], v[214:217], v[96:99]
	v_mfma_f32_16x16x32_bf16 v[84:87], v[190:193], v[222:225], v[84:87]
	v_mfma_f32_16x16x32_bf16 v[80:83], v[198:201], v[222:225], v[80:83]
	v_mfma_f32_16x16x32_bf16 v[68:71], v[190:193], v[230:233], v[68:71]
	v_mfma_f32_16x16x32_bf16 v[64:67], v[198:201], v[230:233], v[64:67]
	v_mfma_f32_16x16x32_bf16 v[116:119], v[194:197], v[210:213], v[116:119]
	v_mfma_f32_16x16x32_bf16 v[112:115], v[202:205], v[210:213], v[112:115]
	v_mfma_f32_16x16x32_bf16 v[100:103], v[194:197], v[218:221], v[100:103]
	v_mfma_f32_16x16x32_bf16 v[96:99], v[202:205], v[218:221], v[96:99]
	v_mfma_f32_16x16x32_bf16 v[84:87], v[194:197], v[226:229], v[84:87]
	v_mfma_f32_16x16x32_bf16 v[80:83], v[202:205], v[226:229], v[80:83]
	v_mfma_f32_16x16x32_bf16 v[68:71], v[194:197], v[234:237], v[68:71]
	v_mfma_f32_16x16x32_bf16 v[64:67], v[202:205], v[234:237], v[64:67]
	s_setprio 0
	s_barrier
	s_add_i32 s26, s70, s53
	v_lshl_add_u64 v[238:239], v[238:239], 0, s[16:17]
	s_mov_b32 m0, s26
	ds_read_b128 v[206:209], v176 offset:49152
	ds_read_b128 v[210:213], v176 offset:50176
	ds_read_b128 v[214:217], v176 offset:51200
	ds_read_b128 v[218:221], v176 offset:52224
	ds_read_b128 v[222:225], v176 offset:53248
	ds_read_b128 v[226:229], v176 offset:54272
	ds_read_b128 v[230:233], v176 offset:55296
	ds_read_b128 v[234:237], v176 offset:56320
	global_load_lds_dwordx4 v[238:239], off
	s_add_i32 m0, s26, 0x2000
	s_add_u32 s26, s46, 0x40080
	v_lshl_add_u64 v[238:239], v[240:241], 0, s[16:17]
	s_addc_u32 s27, s47, 0
	s_add_i32 s46, s71, s53
	global_load_lds_dwordx4 v[238:239], off
	s_mov_b32 m0, s46
	s_nop 0
	global_load_lds_dwordx4 v132, s[26:27]
	s_add_i32 m0, s46, 0x2000
	s_nop 0
	global_load_lds_dwordx4 v134, s[26:27]
	v_lshl_add_u64 v[238:239], v[242:243], 0, s[16:17]
	s_mov_b32 m0, s59
	s_nop 0
	global_load_lds_dwordx4 v[238:239], off
	v_lshl_add_u64 v[238:239], v[244:245], 0, s[16:17]
	s_mov_b32 m0, s60
	s_nop 0
	global_load_lds_dwordx4 v[238:239], off
	s_waitcnt vmcnt(8)
	s_waitcnt lgkmcnt(0)
	s_setprio 1
	s_barrier
	v_mfma_f32_16x16x32_bf16 v[60:63], v[144:147], v[206:209], v[60:63]
	v_mfma_f32_16x16x32_bf16 v[56:59], v[182:185], v[206:209], v[56:59]
	v_mfma_f32_16x16x32_bf16 v[44:47], v[144:147], v[214:217], v[44:47]
	v_mfma_f32_16x16x32_bf16 v[40:43], v[182:185], v[214:217], v[40:43]
	v_mfma_f32_16x16x32_bf16 v[28:31], v[144:147], v[222:225], v[28:31]
	v_mfma_f32_16x16x32_bf16 v[24:27], v[182:185], v[222:225], v[24:27]
	v_mfma_f32_16x16x32_bf16 v[12:15], v[144:147], v[230:233], v[12:15]
	v_mfma_f32_16x16x32_bf16 v[8:11], v[182:185], v[230:233], v[8:11]
	v_mfma_f32_16x16x32_bf16 v[60:63], v[178:181], v[210:213], v[60:63]
	v_mfma_f32_16x16x32_bf16 v[56:59], v[186:189], v[210:213], v[56:59]
	v_mfma_f32_16x16x32_bf16 v[44:47], v[178:181], v[218:221], v[44:47]
	v_mfma_f32_16x16x32_bf16 v[40:43], v[186:189], v[218:221], v[40:43]
	v_mfma_f32_16x16x32_bf16 v[28:31], v[178:181], v[226:229], v[28:31]
	v_mfma_f32_16x16x32_bf16 v[24:27], v[186:189], v[226:229], v[24:27]
	v_mfma_f32_16x16x32_bf16 v[12:15], v[178:181], v[234:237], v[12:15]
	v_mfma_f32_16x16x32_bf16 v[8:11], v[186:189], v[234:237], v[8:11]
	v_mfma_f32_16x16x32_bf16 v[52:55], v[190:193], v[206:209], v[52:55]
	v_mfma_f32_16x16x32_bf16 v[48:51], v[198:201], v[206:209], v[48:51]
	v_mfma_f32_16x16x32_bf16 v[36:39], v[190:193], v[214:217], v[36:39]
	v_mfma_f32_16x16x32_bf16 v[32:35], v[198:201], v[214:217], v[32:35]
	v_mfma_f32_16x16x32_bf16 v[20:23], v[190:193], v[222:225], v[20:23]
	v_mfma_f32_16x16x32_bf16 v[16:19], v[198:201], v[222:225], v[16:19]
	v_mfma_f32_16x16x32_bf16 v[4:7], v[190:193], v[230:233], v[4:7]
	v_mfma_f32_16x16x32_bf16 v[0:3], v[198:201], v[230:233], v[0:3]
	v_mfma_f32_16x16x32_bf16 v[52:55], v[194:197], v[210:213], v[52:55]
	v_mfma_f32_16x16x32_bf16 v[48:51], v[202:205], v[210:213], v[48:51]
	v_mfma_f32_16x16x32_bf16 v[36:39], v[194:197], v[218:221], v[36:39]
	v_mfma_f32_16x16x32_bf16 v[32:35], v[202:205], v[218:221], v[32:35]
	v_mfma_f32_16x16x32_bf16 v[20:23], v[194:197], v[226:229], v[20:23]
	v_mfma_f32_16x16x32_bf16 v[16:19], v[202:205], v[226:229], v[16:19]
	v_mfma_f32_16x16x32_bf16 v[4:7], v[194:197], v[234:237], v[4:7]
	v_mfma_f32_16x16x32_bf16 v[0:3], v[202:205], v[234:237], v[0:3]
	s_setprio 0
	s_barrier
	s_add_i32 s69, s69, 2
	s_add_u32 s67, s67, 0x100
	s_addc_u32 s68, s68, 0
	s_cmp_gt_u32 s69, 13
	s_mov_b64 s[26:27], s[8:9]
	s_cbranch_scc0 .LBB0_1095
	s_and_b64 vcc, exec, s[18:19]
	s_cbranch_vccz .LBB0_1098
	s_barrier

; #define PG8_STAGE(bufoff, gbase, voff) do { _Pragma("unroll") for (int _i = 0; _i < 2; ++_i) \
;         __builtin_amdgcn_global_load_lds((const unsigned*)((const char*)(gbase) + (voff)[_i]), (LAS unsigned*)(lds + (bufoff) + ldsw + _i * 8192), 16, 0, 0); } while (0)
; #define PG8_LDA(dst, b, h) do { _Pragma("unroll") for (int m = 0; m < 4; ++m) _Pragma("unroll") for (int k = 0; k < 2; ++k) dst[m][k] = *(const LAS bf16x8*)(lds + PG8_SA(b, h) + aoff + m * 2048 + k * 1024); } while (0)
; #define PG8_LDB(dst, b, h) do { _Pragma("unroll") for (int n = 0; n < 2; ++n) _Pragma("unroll") for (int k = 0; k < 2; ++k) dst[n][k] = *(const LAS bf16x8*)(lds + PG8_SB(b, h) + boff + n * 2048 + k * 1024); } while (0)
; #define PG8_WAIT_V(n) asm volatile("s_waitcnt vmcnt(" #n ")" ::: "memory")
; #define PG8_WAIT_L(n) asm volatile("s_waitcnt lgkmcnt(" #n ")" ::: "memory")
; #define PG8_BAR __builtin_amdgcn_s_barrier()
; #define PG8_SCHED __builtin_amdgcn_sched_barrier(0)
; template <class Epi, bool FP8 = false>
; __device__ __forceinline__ void gemm_phase(LAS unsigned char* lds, const Gemm g, const StaticOrder& S_, const Epi& E, const int tid) {
;     ...
;             PG8_LDB(B0, 0, 0); PG8_LDB(B1, 0, 1); PG8_SCHED; PG8_LDA(At, 0, 0); PG8_STAGE(PG8_SA(1, 1), a1 + hstepA, voffA);
;             PG8_WAIT_V(8); PG8_WAIT_L(0); PG8_BAR; PG8_MMA(0, 0, At, B0); PG8_MMA(0, 1, At, B1); PG8_BAR; PG8_SCHED;
;             PG8_LDA(At, 0, 1); PG8_STAGE(PG8_SB(0, 0), b2, voffB); PG8_STAGE(PG8_SB(0, 1), b2 + hstepB, voffB); PG8_STAGE(PG8_SA(0, 0), a2, voffA);
;             PG8_WAIT_V(8); PG8_WAIT_L(0); PG8_BAR; PG8_MMA(1, 0, At, B0); PG8_MMA(1, 1, At, B1); PG8_BAR; PG8_SCHED;
.LBB0_1121:
	ds_read_b128 v[144:147], v148
	ds_read_b128 v[152:155], v148 offset:1024
	ds_read_b128 v[160:163], v148 offset:2048
	ds_read_b128 v[164:167], v148 offset:3072
	ds_read_b128 v[168:171], v149
	ds_read_b128 v[172:175], v149 offset:1024
	ds_read_b128 v[176:179], v149 offset:2048
	ds_read_b128 v[180:183], v149 offset:3072
	s_add_u32 s8, s26, 0x100
	s_addc_u32 s9, s27, 0
	s_cmp_eq_u32 s69, 4
	s_cselect_b32 s49, s23, s9
	s_cselect_b32 s48, s22, s8
	s_cselect_b32 s47, s21, s68
	s_cselect_b32 s46, s66, s67
	s_add_i32 m0, s54, 0xc000
	ds_read_b128 v[184:187], v150
	ds_read_b128 v[188:191], v150 offset:1024
	ds_read_b128 v[192:195], v150 offset:2048
	ds_read_b128 v[196:199], v150 offset:3072
	ds_read_b128 v[200:203], v150 offset:4096
	ds_read_b128 v[204:207], v150 offset:5120
	ds_read_b128 v[208:211], v150 offset:6144
	ds_read_b128 v[212:215], v150 offset:7168
	global_load_lds_dwordx4 v136, s[26:27]
	s_add_i32 m0, s54, 0xe000
	s_nop 0
	global_load_lds_dwordx4 v138, s[26:27]
	s_waitcnt vmcnt(8)
	s_waitcnt lgkmcnt(0)
	s_setprio 1
	s_barrier
	v_mfma_f32_16x16x32_bf16 v[124:127], v[144:147], v[184:187], v[124:127]
	v_mfma_f32_16x16x32_bf16 v[120:123], v[160:163], v[184:187], v[120:123]
	v_mfma_f32_16x16x32_bf16 v[108:111], v[144:147], v[192:195], v[108:111]
	v_mfma_f32_16x16x32_bf16 v[104:107], v[160:163], v[192:195], v[104:107]
	v_mfma_f32_16x16x32_bf16 v[92:95], v[144:147], v[200:203], v[92:95]
	v_mfma_f32_16x16x32_bf16 v[88:91], v[160:163], v[200:203], v[88:91]
	v_mfma_f32_16x16x32_bf16 v[76:79], v[144:147], v[208:211], v[76:79]
	v_mfma_f32_16x16x32_bf16 v[72:75], v[160:163], v[208:211], v[72:75]
	v_mfma_f32_16x16x32_bf16 v[124:127], v[152:155], v[188:191], v[124:127]
	v_mfma_f32_16x16x32_bf16 v[120:123], v[164:167], v[188:191], v[120:123]
	v_mfma_f32_16x16x32_bf16 v[108:111], v[152:155], v[196:199], v[108:111]
	v_mfma_f32_16x16x32_bf16 v[104:107], v[164:167], v[196:199], v[104:107]
	v_mfma_f32_16x16x32_bf16 v[92:95], v[152:155], v[204:207], v[92:95]
	v_mfma_f32_16x16x32_bf16 v[88:91], v[164:167], v[204:207], v[88:91]
	v_mfma_f32_16x16x32_bf16 v[76:79], v[152:155], v[212:215], v[76:79]
	v_mfma_f32_16x16x32_bf16 v[72:75], v[164:167], v[212:215], v[72:75]
	v_mfma_f32_16x16x32_bf16 v[116:119], v[168:171], v[184:187], v[116:119]
	v_mfma_f32_16x16x32_bf16 v[112:115], v[176:179], v[184:187], v[112:115]
	v_mfma_f32_16x16x32_bf16 v[100:103], v[168:171], v[192:195], v[100:103]
	v_mfma_f32_16x16x32_bf16 v[96:99], v[176:179], v[192:195], v[96:99]
	v_mfma_f32_16x16x32_bf16 v[84:87], v[168:171], v[200:203], v[84:87]
	v_mfma_f32_16x16x32_bf16 v[80:83], v[176:179], v[200:203], v[80:83]
	v_mfma_f32_16x16x32_bf16 v[68:71], v[168:171], v[208:211], v[68:71]
	v_mfma_f32_16x16x32_bf16 v[64:67], v[176:179], v[208:211], v[64:67]
	v_mfma_f32_16x16x32_bf16 v[116:119], v[172:175], v[188:191], v[116:119]
	v_mfma_f32_16x16x32_bf16 v[112:115], v[180:183], v[188:191], v[112:115]
	v_mfma_f32_16x16x32_bf16 v[100:103], v[172:175], v[196:199], v[100:103]
	v_mfma_f32_16x16x32_bf16 v[96:99], v[180:183], v[196:199], v[96:99]
	v_mfma_f32_16x16x32_bf16 v[84:87], v[172:175], v[204:207], v[84:87]
	v_mfma_f32_16x16x32_bf16 v[80:83], v[180:183], v[204:207], v[80:83]
	v_mfma_f32_16x16x32_bf16 v[68:71], v[172:175], v[212:215], v[68:71]
	v_mfma_f32_16x16x32_bf16 v[64:67], v[180:183], v[212:215], v[64:67]
	s_setprio 0
	s_barrier
	s_add_i32 s26, s61, s53
	v_lshl_add_u64 v[216:217], s[46:47], 0, v[132:133]
	s_mov_b32 m0, s26
	ds_read_b128 v[184:187], v150 offset:16384
	ds_read_b128 v[188:191], v150 offset:17408
	ds_read_b128 v[192:195], v150 offset:18432
	ds_read_b128 v[196:199], v150 offset:19456
	ds_read_b128 v[200:203], v150 offset:20480
	ds_read_b128 v[204:207], v150 offset:21504
	ds_read_b128 v[208:211], v150 offset:22528
	ds_read_b128 v[212:215], v150 offset:23552
	global_load_lds_dwordx4 v[216:217], off
	s_add_i32 m0, s26, 0x2000
	s_add_u32 s26, s46, 0x20000
	v_lshl_add_u64 v[218:219], s[46:47], 0, v[134:135]
	s_addc_u32 s27, s47, 0
	s_add_i32 s70, s62, s53
	global_load_lds_dwordx4 v[218:219], off
	s_mov_b32 m0, s70
	v_lshl_add_u64 v[222:223], s[48:49], 0, v[130:131]
	global_load_lds_dwordx4 v132, s[26:27]
	s_add_i32 m0, s70, 0x2000
	s_nop 0
	global_load_lds_dwordx4 v134, s[26:27]
	v_lshl_add_u64 v[220:221], s[48:49], 0, v[128:129]
	s_mov_b32 m0, s54
	s_nop 0
	global_load_lds_dwordx4 v[220:221], off
	s_mov_b32 m0, s55
	s_nop 0
	global_load_lds_dwordx4 v[222:223], off
	s_waitcnt vmcnt(8)
	s_waitcnt lgkmcnt(0)
	s_setprio 1
	s_barrier
	v_mfma_f32_16x16x32_bf16 v[60:63], v[144:147], v[184:187], v[60:63]
	v_mfma_f32_16x16x32_bf16 v[56:59], v[160:163], v[184:187], v[56:59]
	v_mfma_f32_16x16x32_bf16 v[44:47], v[144:147], v[192:195], v[44:47]
	v_mfma_f32_16x16x32_bf16 v[40:43], v[160:163], v[192:195], v[40:43]
	v_mfma_f32_16x16x32_bf16 v[28:31], v[144:147], v[200:203], v[28:31]
	v_mfma_f32_16x16x32_bf16 v[24:27], v[160:163], v[200:203], v[24:27]
	v_mfma_f32_16x16x32_bf16 v[12:15], v[144:147], v[208:211], v[12:15]
	v_mfma_f32_16x16x32_bf16 v[8:11], v[160:163], v[208:211], v[8:11]
	v_mfma_f32_16x16x32_bf16 v[60:63], v[152:155], v[188:191], v[60:63]
	v_mfma_f32_16x16x32_bf16 v[56:59], v[164:167], v[188:191], v[56:59]
	v_mfma_f32_16x16x32_bf16 v[44:47], v[152:155], v[196:199], v[44:47]
	v_mfma_f32_16x16x32_bf16 v[40:43], v[164:167], v[196:199], v[40:43]
	v_mfma_f32_16x16x32_bf16 v[28:31], v[152:155], v[204:207], v[28:31]
	v_mfma_f32_16x16x32_bf16 v[24:27], v[164:167], v[204:207], v[24:27]
	v_mfma_f32_16x16x32_bf16 v[12:15], v[152:155], v[212:215], v[12:15]
	v_mfma_f32_16x16x32_bf16 v[8:11], v[164:167], v[212:215], v[8:11]
	v_mfma_f32_16x16x32_bf16 v[52:55], v[168:171], v[184:187], v[52:55]
	v_mfma_f32_16x16x32_bf16 v[48:51], v[176:179], v[184:187], v[48:51]
	v_mfma_f32_16x16x32_bf16 v[36:39], v[168:171], v[192:195], v[36:39]
	v_mfma_f32_16x16x32_bf16 v[32:35], v[176:179], v[192:195], v[32:35]
	v_mfma_f32_16x16x32_bf16 v[20:23], v[168:171], v[200:203], v[20:23]
	v_mfma_f32_16x16x32_bf16 v[16:19], v[176:179], v[200:203], v[16:19]
	v_mfma_f32_16x16x32_bf16 v[4:7], v[168:171], v[208:211], v[4:7]
	v_mfma_f32_16x16x32_bf16 v[0:3], v[176:179], v[208:211], v[0:3]
	v_mfma_f32_16x16x32_bf16 v[52:55], v[172:175], v[188:191], v[52:55]
	v_mfma_f32_16x16x32_bf16 v[48:51], v[180:183], v[188:191], v[48:51]
	v_mfma_f32_16x16x32_bf16 v[36:39], v[172:175], v[196:199], v[36:39]
	v_mfma_f32_16x16x32_bf16 v[32:35], v[180:183], v[196:199], v[32:35]
	v_mfma_f32_16x16x32_bf16 v[20:23], v[172:175], v[204:207], v[20:23]
	v_mfma_f32_16x16x32_bf16 v[16:19], v[180:183], v[204:207], v[16:19]
	v_mfma_f32_16x16x32_bf16 v[4:7], v[172:175], v[212:215], v[4:7]
	v_mfma_f32_16x16x32_bf16 v[0:3], v[180:183], v[212:215], v[0:3]
	s_setprio 0
	s_barrier
; #define PG8_STAGE(bufoff, gbase, voff) do { _Pragma("unroll") for (int _i = 0; _i < 2; ++_i) \
;         __builtin_amdgcn_global_load_lds((const unsigned*)((const char*)(gbase) + (voff)[_i]), (LAS unsigned*)(lds + (bufoff) + ldsw + _i * 8192), 16, 0, 0); } while (0)
; #define PG8_LDA(dst, b, h) do { _Pragma("unroll") for (int m = 0; m < 4; ++m) _Pragma("unroll") for (int k = 0; k < 2; ++k) dst[m][k] = *(const LAS bf16x8*)(lds + PG8_SA(b, h) + aoff + m * 2048 + k * 1024); } while (0)
; #define PG8_LDB(dst, b, h) do { _Pragma("unroll") for (int n = 0; n < 2; ++n) _Pragma("unroll") for (int k = 0; k < 2; ++k) dst[n][k] = *(const LAS bf16x8*)(lds + PG8_SB(b, h) + boff + n * 2048 + k * 1024); } while (0)
; #define PG8_WAIT_V(n) asm volatile("s_waitcnt vmcnt(" #n ")" ::: "memory")
; #define PG8_WAIT_L(n) asm volatile("s_waitcnt lgkmcnt(" #n ")" ::: "memory")
; #define PG8_BAR __builtin_amdgcn_s_barrier()
; #define PG8_SCHED __builtin_amdgcn_sched_barrier(0)
; template <class Epi, bool FP8 = false>
; __device__ __forceinline__ void gemm_phase(LAS unsigned char* lds, const Gemm g, const StaticOrder& S_, const Epi& E, const int tid) {
;     ...
;             PG8_LDB(B0, 1, 0); PG8_LDB(B1, 1, 1); PG8_SCHED; PG8_LDA(At, 1, 0); PG8_STAGE(PG8_SA(0, 1), a2 + hstepA, voffA);
;             PG8_WAIT_V(8); PG8_WAIT_L(0); PG8_BAR; PG8_MMA(0, 0, At, B0); PG8_MMA(0, 1, At, B1); PG8_BAR; PG8_SCHED;
;             PG8_LDA(At, 1, 1); PG8_STAGE(PG8_SB(1, 0), b3, voffB); PG8_STAGE(PG8_SB(1, 1), b3 + hstepB, voffB); PG8_STAGE(PG8_SA(1, 0), a3, voffA);
;             PG8_WAIT_V(8); PG8_WAIT_L(0); PG8_BAR; PG8_MMA(1, 0, At, B0); PG8_MMA(1, 1, At, B1); PG8_BAR; PG8_SCHED;
;         }
;         if (wr == 0) PG8_BAR;
	s_add_i32 s70, 0, 0x18000
	v_add_u32_e32 v151, s70, v157
	s_add_i32 s71, 0, 0x1c000
	ds_read_b128 v[144:147], v151
	ds_read_b128 v[152:155], v151 offset:1024
	ds_read_b128 v[160:163], v151 offset:2048
	ds_read_b128 v[164:167], v151 offset:3072
	v_add_u32_e32 v151, s71, v157
	ds_read_b128 v[168:171], v151
	ds_read_b128 v[172:175], v151 offset:1024
	ds_read_b128 v[176:179], v151 offset:2048
	ds_read_b128 v[180:183], v151 offset:3072
	s_add_u32 s26, s48, 0x60000
	s_addc_u32 s27, s49, 0
	s_mov_b32 m0, s56
	ds_read_b128 v[184:187], v150 offset:32768
	ds_read_b128 v[188:191], v150 offset:33792
	ds_read_b128 v[192:195], v150 offset:34816
	ds_read_b128 v[196:199], v150 offset:35840
	ds_read_b128 v[200:203], v150 offset:36864
	ds_read_b128 v[204:207], v150 offset:37888
	ds_read_b128 v[208:211], v150 offset:38912
	ds_read_b128 v[212:215], v150 offset:39936
	global_load_lds_dwordx4 v128, s[26:27]
	s_mov_b32 m0, s57
	s_nop 0
	global_load_lds_dwordx4 v130, s[26:27]
	s_waitcnt vmcnt(8)
	s_waitcnt lgkmcnt(0)
	s_setprio 1
	s_barrier
	v_mfma_f32_16x16x32_bf16 v[124:127], v[144:147], v[184:187], v[124:127]
	v_mfma_f32_16x16x32_bf16 v[120:123], v[160:163], v[184:187], v[120:123]
	v_mfma_f32_16x16x32_bf16 v[108:111], v[144:147], v[192:195], v[108:111]
	v_mfma_f32_16x16x32_bf16 v[104:107], v[160:163], v[192:195], v[104:107]
	v_mfma_f32_16x16x32_bf16 v[92:95], v[144:147], v[200:203], v[92:95]
	v_mfma_f32_16x16x32_bf16 v[88:91], v[160:163], v[200:203], v[88:91]
	v_mfma_f32_16x16x32_bf16 v[76:79], v[144:147], v[208:211], v[76:79]
	v_mfma_f32_16x16x32_bf16 v[72:75], v[160:163], v[208:211], v[72:75]
	v_mfma_f32_16x16x32_bf16 v[124:127], v[152:155], v[188:191], v[124:127]
	v_mfma_f32_16x16x32_bf16 v[120:123], v[164:167], v[188:191], v[120:123]
	v_mfma_f32_16x16x32_bf16 v[108:111], v[152:155], v[196:199], v[108:111]
	v_mfma_f32_16x16x32_bf16 v[104:107], v[164:167], v[196:199], v[104:107]
	v_mfma_f32_16x16x32_bf16 v[92:95], v[152:155], v[204:207], v[92:95]
	v_mfma_f32_16x16x32_bf16 v[88:91], v[164:167], v[204:207], v[88:91]
	v_mfma_f32_16x16x32_bf16 v[76:79], v[152:155], v[212:215], v[76:79]
	v_mfma_f32_16x16x32_bf16 v[72:75], v[164:167], v[212:215], v[72:75]
	v_mfma_f32_16x16x32_bf16 v[116:119], v[168:171], v[184:187], v[116:119]
	v_mfma_f32_16x16x32_bf16 v[112:115], v[176:179], v[184:187], v[112:115]
	v_mfma_f32_16x16x32_bf16 v[100:103], v[168:171], v[192:195], v[100:103]
	v_mfma_f32_16x16x32_bf16 v[96:99], v[176:179], v[192:195], v[96:99]
	v_mfma_f32_16x16x32_bf16 v[84:87], v[168:171], v[200:203], v[84:87]
	v_mfma_f32_16x16x32_bf16 v[80:83], v[176:179], v[200:203], v[80:83]
	v_mfma_f32_16x16x32_bf16 v[68:71], v[168:171], v[208:211], v[68:71]
	v_mfma_f32_16x16x32_bf16 v[64:67], v[176:179], v[208:211], v[64:67]
	v_mfma_f32_16x16x32_bf16 v[116:119], v[172:175], v[188:191], v[116:119]
	v_mfma_f32_16x16x32_bf16 v[112:115], v[180:183], v[188:191], v[112:115]
	v_mfma_f32_16x16x32_bf16 v[100:103], v[172:175], v[196:199], v[100:103]
	v_mfma_f32_16x16x32_bf16 v[96:99], v[180:183], v[196:199], v[96:99]
	v_mfma_f32_16x16x32_bf16 v[84:87], v[172:175], v[204:207], v[84:87]
	v_mfma_f32_16x16x32_bf16 v[80:83], v[180:183], v[204:207], v[80:83]
	v_mfma_f32_16x16x32_bf16 v[68:71], v[172:175], v[212:215], v[68:71]
	v_mfma_f32_16x16x32_bf16 v[64:67], v[180:183], v[212:215], v[64:67]
	s_setprio 0
	s_barrier
	s_add_i32 s26, s70, s53
	v_lshl_add_u64 v[216:217], v[216:217], 0, s[16:17]
	s_mov_b32 m0, s26
	ds_read_b128 v[184:187], v150 offset:49152
	ds_read_b128 v[188:191], v150 offset:50176
	ds_read_b128 v[192:195], v150 offset:51200
	ds_read_b128 v[196:199], v150 offset:52224
	ds_read_b128 v[200:203], v150 offset:53248
	ds_read_b128 v[204:207], v150 offset:54272
	ds_read_b128 v[208:211], v150 offset:55296
	ds_read_b128 v[212:215], v150 offset:56320
	global_load_lds_dwordx4 v[216:217], off
	s_add_i32 m0, s26, 0x2000
	s_add_u32 s26, s46, 0x20080
	v_lshl_add_u64 v[216:217], v[218:219], 0, s[16:17]
	s_addc_u32 s27, s47, 0
	s_add_i32 s46, s71, s53
	global_load_lds_dwordx4 v[216:217], off
	s_mov_b32 m0, s46
	s_nop 0
	global_load_lds_dwordx4 v132, s[26:27]
	s_add_i32 m0, s46, 0x2000
	s_nop 0
	global_load_lds_dwordx4 v134, s[26:27]
	v_lshl_add_u64 v[216:217], v[220:221], 0, s[16:17]
	s_mov_b32 m0, s59
	s_nop 0
	global_load_lds_dwordx4 v[216:217], off
	v_lshl_add_u64 v[216:217], v[222:223], 0, s[16:17]
	s_mov_b32 m0, s60
	s_nop 0
	global_load_lds_dwordx4 v[216:217], off
	s_waitcnt vmcnt(8)
	s_waitcnt lgkmcnt(0)
	s_setprio 1
	s_barrier
	v_mfma_f32_16x16x32_bf16 v[60:63], v[144:147], v[184:187], v[60:63]
	v_mfma_f32_16x16x32_bf16 v[56:59], v[160:163], v[184:187], v[56:59]
	v_mfma_f32_16x16x32_bf16 v[44:47], v[144:147], v[192:195], v[44:47]
	v_mfma_f32_16x16x32_bf16 v[40:43], v[160:163], v[192:195], v[40:43]
	v_mfma_f32_16x16x32_bf16 v[28:31], v[144:147], v[200:203], v[28:31]
	v_mfma_f32_16x16x32_bf16 v[24:27], v[160:163], v[200:203], v[24:27]
	v_mfma_f32_16x16x32_bf16 v[12:15], v[144:147], v[208:211], v[12:15]
	v_mfma_f32_16x16x32_bf16 v[8:11], v[160:163], v[208:211], v[8:11]
	v_mfma_f32_16x16x32_bf16 v[60:63], v[152:155], v[188:191], v[60:63]
	v_mfma_f32_16x16x32_bf16 v[56:59], v[164:167], v[188:191], v[56:59]
	v_mfma_f32_16x16x32_bf16 v[44:47], v[152:155], v[196:199], v[44:47]
	v_mfma_f32_16x16x32_bf16 v[40:43], v[164:167], v[196:199], v[40:43]
	v_mfma_f32_16x16x32_bf16 v[28:31], v[152:155], v[204:207], v[28:31]
	v_mfma_f32_16x16x32_bf16 v[24:27], v[164:167], v[204:207], v[24:27]
	v_mfma_f32_16x16x32_bf16 v[12:15], v[152:155], v[212:215], v[12:15]
	v_mfma_f32_16x16x32_bf16 v[8:11], v[164:167], v[212:215], v[8:11]
	v_mfma_f32_16x16x32_bf16 v[52:55], v[168:171], v[184:187], v[52:55]
	v_mfma_f32_16x16x32_bf16 v[48:51], v[176:179], v[184:187], v[48:51]
	v_mfma_f32_16x16x32_bf16 v[36:39], v[168:171], v[192:195], v[36:39]
	v_mfma_f32_16x16x32_bf16 v[32:35], v[176:179], v[192:195], v[32:35]
	v_mfma_f32_16x16x32_bf16 v[20:23], v[168:171], v[200:203], v[20:23]
	v_mfma_f32_16x16x32_bf16 v[16:19], v[176:179], v[200:203], v[16:19]
	v_mfma_f32_16x16x32_bf16 v[4:7], v[168:171], v[208:211], v[4:7]
	v_mfma_f32_16x16x32_bf16 v[0:3], v[176:179], v[208:211], v[0:3]
	v_mfma_f32_16x16x32_bf16 v[52:55], v[172:175], v[188:191], v[52:55]
	v_mfma_f32_16x16x32_bf16 v[48:51], v[180:183], v[188:191], v[48:51]
	v_mfma_f32_16x16x32_bf16 v[36:39], v[172:175], v[196:199], v[36:39]
	v_mfma_f32_16x16x32_bf16 v[32:35], v[180:183], v[196:199], v[32:35]
	v_mfma_f32_16x16x32_bf16 v[20:23], v[172:175], v[204:207], v[20:23]
	v_mfma_f32_16x16x32_bf16 v[16:19], v[180:183], v[204:207], v[16:19]
	v_mfma_f32_16x16x32_bf16 v[4:7], v[172:175], v[212:215], v[4:7]
	v_mfma_f32_16x16x32_bf16 v[0:3], v[180:183], v[212:215], v[0:3]
	s_setprio 0
	s_barrier
	s_add_i32 s69, s69, 2
	s_add_u32 s67, s67, 0x100
	s_addc_u32 s68, s68, 0
	s_cmp_gt_u32 s69, 5
	s_mov_b64 s[26:27], s[8:9]
	s_cbranch_scc0 .LBB0_1121
	s_and_b64 vcc, exec, s[18:19]
	s_cbranch_vccz .LBB0_1124
	s_barrier

; #define PG8_STAGE(bufoff, gbase, voff) do { _Pragma("unroll") for (int _i = 0; _i < 2; ++_i) \
;         __builtin_amdgcn_global_load_lds((const unsigned*)((const char*)(gbase) + (voff)[_i]), (LAS unsigned*)(lds + (bufoff) + ldsw + _i * 8192), 16, 0, 0); } while (0)
; #define PG8_LDA(dst, b, h) do { _Pragma("unroll") for (int m = 0; m < 4; ++m) _Pragma("unroll") for (int k = 0; k < 2; ++k) dst[m][k] = *(const LAS bf16x8*)(lds + PG8_SA(b, h) + aoff + m * 2048 + k * 1024); } while (0)
; #define PG8_LDB(dst, b, h) do { _Pragma("unroll") for (int n = 0; n < 2; ++n) _Pragma("unroll") for (int k = 0; k < 2; ++k) dst[n][k] = *(const LAS bf16x8*)(lds + PG8_SB(b, h) + boff + n * 2048 + k * 1024); } while (0)
; #define PG8_WAIT_V(n) asm volatile("s_waitcnt vmcnt(" #n ")" ::: "memory")
; #define PG8_WAIT_L(n) asm volatile("s_waitcnt lgkmcnt(" #n ")" ::: "memory")
; #define PG8_BAR __builtin_amdgcn_s_barrier()
; #define PG8_SCHED __builtin_amdgcn_sched_barrier(0)
; template <class Epi, bool FP8 = false>
; __device__ __forceinline__ void gemm_phase(LAS unsigned char* lds, const Gemm g, const StaticOrder& S_, const Epi& E, const int tid) {
;     ...
;             PG8_LDB(B0, 0, 0); PG8_LDB(B1, 0, 1); PG8_SCHED; PG8_LDA(At, 0, 0); PG8_STAGE(PG8_SA(1, 1), a1 + hstepA, voffA);
;             PG8_WAIT_V(8); PG8_WAIT_L(0); PG8_BAR; PG8_MMA(0, 0, At, B0); PG8_MMA(0, 1, At, B1); PG8_BAR; PG8_SCHED;
;             PG8_LDA(At, 0, 1); PG8_STAGE(PG8_SB(0, 0), b2, voffB); PG8_STAGE(PG8_SB(0, 1), b2 + hstepB, voffB); PG8_STAGE(PG8_SA(0, 0), a2, voffA);
;             PG8_WAIT_V(8); PG8_WAIT_L(0); PG8_BAR; PG8_MMA(1, 0, At, B0); PG8_MMA(1, 1, At, B1); PG8_BAR; PG8_SCHED;
.LBB0_1197:
	ds_read_b128 v[140:143], v152
	ds_read_b128 v[144:147], v152 offset:1024
	ds_read_b128 v[156:159], v152 offset:2048
	ds_read_b128 v[160:163], v152 offset:3072
	ds_read_b128 v[164:167], v153
	ds_read_b128 v[168:171], v153 offset:1024
	ds_read_b128 v[172:175], v153 offset:2048
	ds_read_b128 v[176:179], v153 offset:3072
	s_add_u32 s50, s48, 0xfff80080
	s_addc_u32 s51, s49, -1
	s_cmp_eq_u32 s70, 28
	s_cselect_b32 s53, s23, s51
	s_cselect_b32 s52, s43, s50
	s_cselect_b32 s51, s21, s69
	s_cselect_b32 s50, s66, s68
	s_add_i32 m0, s47, 0xc000
	ds_read_b128 v[180:183], v154
	ds_read_b128 v[184:187], v154 offset:1024
	ds_read_b128 v[188:191], v154 offset:2048
	ds_read_b128 v[192:195], v154 offset:3072
	ds_read_b128 v[196:199], v154 offset:4096
	ds_read_b128 v[200:203], v154 offset:5120
	ds_read_b128 v[204:207], v154 offset:6144
	ds_read_b128 v[208:211], v154 offset:7168
	global_load_lds_dwordx4 v132, s[48:49]
	s_add_i32 m0, s47, 0xe000
	s_nop 0
	global_load_lds_dwordx4 v134, s[48:49]
	s_waitcnt vmcnt(8)
	s_waitcnt lgkmcnt(0)
	s_setprio 1
	s_barrier
	v_mfma_f32_16x16x32_bf16 v[124:127], v[140:143], v[180:183], v[124:127]
	v_mfma_f32_16x16x32_bf16 v[120:123], v[156:159], v[180:183], v[120:123]
	v_mfma_f32_16x16x32_bf16 v[108:111], v[140:143], v[188:191], v[108:111]
	v_mfma_f32_16x16x32_bf16 v[104:107], v[156:159], v[188:191], v[104:107]
	v_mfma_f32_16x16x32_bf16 v[92:95], v[140:143], v[196:199], v[92:95]
	v_mfma_f32_16x16x32_bf16 v[88:91], v[156:159], v[196:199], v[88:91]
	v_mfma_f32_16x16x32_bf16 v[76:79], v[140:143], v[204:207], v[76:79]
	v_mfma_f32_16x16x32_bf16 v[72:75], v[156:159], v[204:207], v[72:75]
	v_mfma_f32_16x16x32_bf16 v[124:127], v[144:147], v[184:187], v[124:127]
	v_mfma_f32_16x16x32_bf16 v[120:123], v[160:163], v[184:187], v[120:123]
	v_mfma_f32_16x16x32_bf16 v[108:111], v[144:147], v[192:195], v[108:111]
	v_mfma_f32_16x16x32_bf16 v[104:107], v[160:163], v[192:195], v[104:107]
	v_mfma_f32_16x16x32_bf16 v[92:95], v[144:147], v[200:203], v[92:95]
	v_mfma_f32_16x16x32_bf16 v[88:91], v[160:163], v[200:203], v[88:91]
	v_mfma_f32_16x16x32_bf16 v[76:79], v[144:147], v[208:211], v[76:79]
	v_mfma_f32_16x16x32_bf16 v[72:75], v[160:163], v[208:211], v[72:75]
	v_mfma_f32_16x16x32_bf16 v[116:119], v[164:167], v[180:183], v[116:119]
	v_mfma_f32_16x16x32_bf16 v[112:115], v[172:175], v[180:183], v[112:115]
	v_mfma_f32_16x16x32_bf16 v[100:103], v[164:167], v[188:191], v[100:103]
	v_mfma_f32_16x16x32_bf16 v[96:99], v[172:175], v[188:191], v[96:99]
	v_mfma_f32_16x16x32_bf16 v[84:87], v[164:167], v[196:199], v[84:87]
	v_mfma_f32_16x16x32_bf16 v[80:83], v[172:175], v[196:199], v[80:83]
	v_mfma_f32_16x16x32_bf16 v[68:71], v[164:167], v[204:207], v[68:71]
	v_mfma_f32_16x16x32_bf16 v[64:67], v[172:175], v[204:207], v[64:67]
	v_mfma_f32_16x16x32_bf16 v[116:119], v[168:171], v[184:187], v[116:119]
	v_mfma_f32_16x16x32_bf16 v[112:115], v[176:179], v[184:187], v[112:115]
	v_mfma_f32_16x16x32_bf16 v[100:103], v[168:171], v[192:195], v[100:103]
	v_mfma_f32_16x16x32_bf16 v[96:99], v[176:179], v[192:195], v[96:99]
	v_mfma_f32_16x16x32_bf16 v[84:87], v[168:171], v[200:203], v[84:87]
	v_mfma_f32_16x16x32_bf16 v[80:83], v[176:179], v[200:203], v[80:83]
	v_mfma_f32_16x16x32_bf16 v[68:71], v[168:171], v[208:211], v[68:71]
	v_mfma_f32_16x16x32_bf16 v[64:67], v[176:179], v[208:211], v[64:67]
	s_setprio 0
	s_barrier
	s_add_i32 s71, s63, s56
	v_lshl_add_u64 v[212:213], s[50:51], 0, v[128:129]
	s_mov_b32 m0, s71
	ds_read_b128 v[180:183], v154 offset:16384
	ds_read_b128 v[184:187], v154 offset:17408
	ds_read_b128 v[188:191], v154 offset:18432
	ds_read_b128 v[192:195], v154 offset:19456
	ds_read_b128 v[196:199], v154 offset:20480
	ds_read_b128 v[200:203], v154 offset:21504
	ds_read_b128 v[204:207], v154 offset:22528
	ds_read_b128 v[208:211], v154 offset:23552
	global_load_lds_dwordx4 v[212:213], off
	s_add_i32 m0, s71, 0x2000
	s_add_u32 s72, s50, 0x80000
	v_lshl_add_u64 v[214:215], s[50:51], 0, v[130:131]
	s_addc_u32 s73, s51, 0
	s_add_i32 s71, s67, s56
	global_load_lds_dwordx4 v[214:215], off
	s_mov_b32 m0, s71
	v_lshl_add_u64 v[218:219], s[52:53], 0, v[130:131]
	global_load_lds_dwordx4 v128, s[72:73]
	s_add_i32 m0, s71, 0x2000
	s_nop 0
	global_load_lds_dwordx4 v130, s[72:73]
	v_lshl_add_u64 v[216:217], s[52:53], 0, v[128:129]
	s_mov_b32 m0, s47
	s_nop 0
	global_load_lds_dwordx4 v[216:217], off
	s_mov_b32 m0, s57
	s_nop 0
	global_load_lds_dwordx4 v[218:219], off
	s_waitcnt vmcnt(8)
	s_waitcnt lgkmcnt(0)
	s_setprio 1
	s_barrier
	v_mfma_f32_16x16x32_bf16 v[60:63], v[140:143], v[180:183], v[60:63]
	v_mfma_f32_16x16x32_bf16 v[56:59], v[156:159], v[180:183], v[56:59]
	v_mfma_f32_16x16x32_bf16 v[44:47], v[140:143], v[188:191], v[44:47]
	v_mfma_f32_16x16x32_bf16 v[40:43], v[156:159], v[188:191], v[40:43]
	v_mfma_f32_16x16x32_bf16 v[28:31], v[140:143], v[196:199], v[28:31]
	v_mfma_f32_16x16x32_bf16 v[24:27], v[156:159], v[196:199], v[24:27]
	v_mfma_f32_16x16x32_bf16 v[12:15], v[140:143], v[204:207], v[12:15]
	v_mfma_f32_16x16x32_bf16 v[8:11], v[156:159], v[204:207], v[8:11]
	v_mfma_f32_16x16x32_bf16 v[60:63], v[144:147], v[184:187], v[60:63]
	v_mfma_f32_16x16x32_bf16 v[56:59], v[160:163], v[184:187], v[56:59]
	v_mfma_f32_16x16x32_bf16 v[44:47], v[144:147], v[192:195], v[44:47]
	v_mfma_f32_16x16x32_bf16 v[40:43], v[160:163], v[192:195], v[40:43]
	v_mfma_f32_16x16x32_bf16 v[28:31], v[144:147], v[200:203], v[28:31]
	v_mfma_f32_16x16x32_bf16 v[24:27], v[160:163], v[200:203], v[24:27]
	v_mfma_f32_16x16x32_bf16 v[12:15], v[144:147], v[208:211], v[12:15]
	v_mfma_f32_16x16x32_bf16 v[8:11], v[160:163], v[208:211], v[8:11]
	v_mfma_f32_16x16x32_bf16 v[52:55], v[164:167], v[180:183], v[52:55]
	v_mfma_f32_16x16x32_bf16 v[48:51], v[172:175], v[180:183], v[48:51]
	v_mfma_f32_16x16x32_bf16 v[36:39], v[164:167], v[188:191], v[36:39]
	v_mfma_f32_16x16x32_bf16 v[32:35], v[172:175], v[188:191], v[32:35]
	v_mfma_f32_16x16x32_bf16 v[20:23], v[164:167], v[196:199], v[20:23]
	v_mfma_f32_16x16x32_bf16 v[16:19], v[172:175], v[196:199], v[16:19]
	v_mfma_f32_16x16x32_bf16 v[4:7], v[164:167], v[204:207], v[4:7]
	v_mfma_f32_16x16x32_bf16 v[0:3], v[172:175], v[204:207], v[0:3]
	v_mfma_f32_16x16x32_bf16 v[52:55], v[168:171], v[184:187], v[52:55]
	v_mfma_f32_16x16x32_bf16 v[48:51], v[176:179], v[184:187], v[48:51]
	v_mfma_f32_16x16x32_bf16 v[36:39], v[168:171], v[192:195], v[36:39]
	v_mfma_f32_16x16x32_bf16 v[32:35], v[176:179], v[192:195], v[32:35]
	v_mfma_f32_16x16x32_bf16 v[20:23], v[168:171], v[200:203], v[20:23]
	v_mfma_f32_16x16x32_bf16 v[16:19], v[176:179], v[200:203], v[16:19]
	v_mfma_f32_16x16x32_bf16 v[4:7], v[168:171], v[208:211], v[4:7]
	v_mfma_f32_16x16x32_bf16 v[0:3], v[176:179], v[208:211], v[0:3]
	s_setprio 0
	s_barrier
; #define PG8_STAGE(bufoff, gbase, voff) do { _Pragma("unroll") for (int _i = 0; _i < 2; ++_i) \
;         __builtin_amdgcn_global_load_lds((const unsigned*)((const char*)(gbase) + (voff)[_i]), (LAS unsigned*)(lds + (bufoff) + ldsw + _i * 8192), 16, 0, 0); } while (0)
; #define PG8_LDA(dst, b, h) do { _Pragma("unroll") for (int m = 0; m < 4; ++m) _Pragma("unroll") for (int k = 0; k < 2; ++k) dst[m][k] = *(const LAS bf16x8*)(lds + PG8_SA(b, h) + aoff + m * 2048 + k * 1024); } while (0)
; #define PG8_LDB(dst, b, h) do { _Pragma("unroll") for (int n = 0; n < 2; ++n) _Pragma("unroll") for (int k = 0; k < 2; ++k) dst[n][k] = *(const LAS bf16x8*)(lds + PG8_SB(b, h) + boff + n * 2048 + k * 1024); } while (0)
; #define PG8_WAIT_V(n) asm volatile("s_waitcnt vmcnt(" #n ")" ::: "memory")
; #define PG8_WAIT_L(n) asm volatile("s_waitcnt lgkmcnt(" #n ")" ::: "memory")
; #define PG8_BAR __builtin_amdgcn_s_barrier()
; #define PG8_SCHED __builtin_amdgcn_sched_barrier(0)
; template <class Epi, bool FP8 = false>
; __device__ __forceinline__ void gemm_phase(LAS unsigned char* lds, const Gemm g, const StaticOrder& S_, const Epi& E, const int tid) {
;     ...
;             PG8_LDB(B0, 1, 0); PG8_LDB(B1, 1, 1); PG8_SCHED; PG8_LDA(At, 1, 0); PG8_STAGE(PG8_SA(0, 1), a2 + hstepA, voffA);
;             PG8_WAIT_V(8); PG8_WAIT_L(0); PG8_BAR; PG8_MMA(0, 0, At, B0); PG8_MMA(0, 1, At, B1); PG8_BAR; PG8_SCHED;
;             PG8_LDA(At, 1, 1); PG8_STAGE(PG8_SB(1, 0), b3, voffB); PG8_STAGE(PG8_SB(1, 1), b3 + hstepB, voffB); PG8_STAGE(PG8_SA(1, 0), a3, voffA);
;             PG8_WAIT_V(8); PG8_WAIT_L(0); PG8_BAR; PG8_MMA(1, 0, At, B0); PG8_MMA(1, 1, At, B1); PG8_BAR; PG8_SCHED;
;         }
;         if (wr == 0) PG8_BAR;
	s_add_i32 s71, 0, 0x18000
	v_add_u32_e32 v155, s71, v150
	s_add_i32 s72, 0, 0x1c000
	ds_read_b128 v[140:143], v155
	ds_read_b128 v[144:147], v155 offset:1024
	ds_read_b128 v[156:159], v155 offset:2048
	ds_read_b128 v[160:163], v155 offset:3072
	v_add_u32_e32 v155, s72, v150
	ds_read_b128 v[164:167], v155
	ds_read_b128 v[168:171], v155 offset:1024
	ds_read_b128 v[172:175], v155 offset:2048
	ds_read_b128 v[176:179], v155 offset:3072
	s_add_u32 s52, s52, 0x80000
	s_addc_u32 s53, s53, 0
	s_mov_b32 m0, s58
	ds_read_b128 v[180:183], v154 offset:32768
	ds_read_b128 v[184:187], v154 offset:33792
	ds_read_b128 v[188:191], v154 offset:34816
	ds_read_b128 v[192:195], v154 offset:35840
	ds_read_b128 v[196:199], v154 offset:36864
	ds_read_b128 v[200:203], v154 offset:37888
	ds_read_b128 v[204:207], v154 offset:38912
	ds_read_b128 v[208:211], v154 offset:39936
	global_load_lds_dwordx4 v128, s[52:53]
	s_mov_b32 m0, s59
	s_nop 0
	global_load_lds_dwordx4 v130, s[52:53]
	s_waitcnt vmcnt(8)
	s_waitcnt lgkmcnt(0)
	s_setprio 1
	s_barrier
	v_mfma_f32_16x16x32_bf16 v[124:127], v[140:143], v[180:183], v[124:127]
	v_mfma_f32_16x16x32_bf16 v[120:123], v[156:159], v[180:183], v[120:123]
	v_mfma_f32_16x16x32_bf16 v[108:111], v[140:143], v[188:191], v[108:111]
	v_mfma_f32_16x16x32_bf16 v[104:107], v[156:159], v[188:191], v[104:107]
	v_mfma_f32_16x16x32_bf16 v[92:95], v[140:143], v[196:199], v[92:95]
	v_mfma_f32_16x16x32_bf16 v[88:91], v[156:159], v[196:199], v[88:91]
	v_mfma_f32_16x16x32_bf16 v[76:79], v[140:143], v[204:207], v[76:79]
	v_mfma_f32_16x16x32_bf16 v[72:75], v[156:159], v[204:207], v[72:75]
	v_mfma_f32_16x16x32_bf16 v[124:127], v[144:147], v[184:187], v[124:127]
	v_mfma_f32_16x16x32_bf16 v[120:123], v[160:163], v[184:187], v[120:123]
	v_mfma_f32_16x16x32_bf16 v[108:111], v[144:147], v[192:195], v[108:111]
	v_mfma_f32_16x16x32_bf16 v[104:107], v[160:163], v[192:195], v[104:107]
	v_mfma_f32_16x16x32_bf16 v[92:95], v[144:147], v[200:203], v[92:95]
	v_mfma_f32_16x16x32_bf16 v[88:91], v[160:163], v[200:203], v[88:91]
	v_mfma_f32_16x16x32_bf16 v[76:79], v[144:147], v[208:211], v[76:79]
	v_mfma_f32_16x16x32_bf16 v[72:75], v[160:163], v[208:211], v[72:75]
	v_mfma_f32_16x16x32_bf16 v[116:119], v[164:167], v[180:183], v[116:119]
	v_mfma_f32_16x16x32_bf16 v[112:115], v[172:175], v[180:183], v[112:115]
	v_mfma_f32_16x16x32_bf16 v[100:103], v[164:167], v[188:191], v[100:103]
	v_mfma_f32_16x16x32_bf16 v[96:99], v[172:175], v[188:191], v[96:99]
	v_mfma_f32_16x16x32_bf16 v[84:87], v[164:167], v[196:199], v[84:87]
	v_mfma_f32_16x16x32_bf16 v[80:83], v[172:175], v[196:199], v[80:83]
	v_mfma_f32_16x16x32_bf16 v[68:71], v[164:167], v[204:207], v[68:71]
	v_mfma_f32_16x16x32_bf16 v[64:67], v[172:175], v[204:207], v[64:67]
	v_mfma_f32_16x16x32_bf16 v[116:119], v[168:171], v[184:187], v[116:119]
	v_mfma_f32_16x16x32_bf16 v[112:115], v[176:179], v[184:187], v[112:115]
	v_mfma_f32_16x16x32_bf16 v[100:103], v[168:171], v[192:195], v[100:103]
	v_mfma_f32_16x16x32_bf16 v[96:99], v[176:179], v[192:195], v[96:99]
	v_mfma_f32_16x16x32_bf16 v[84:87], v[168:171], v[200:203], v[84:87]
	v_mfma_f32_16x16x32_bf16 v[80:83], v[176:179], v[200:203], v[80:83]
	v_mfma_f32_16x16x32_bf16 v[68:71], v[168:171], v[208:211], v[68:71]
	v_mfma_f32_16x16x32_bf16 v[64:67], v[176:179], v[208:211], v[64:67]
	s_setprio 0
	s_barrier
	s_add_i32 s52, s71, s56
	v_lshl_add_u64 v[212:213], v[212:213], 0, s[14:15]
	s_mov_b32 m0, s52
	ds_read_b128 v[180:183], v154 offset:49152
	ds_read_b128 v[184:187], v154 offset:50176
	ds_read_b128 v[188:191], v154 offset:51200
	ds_read_b128 v[192:195], v154 offset:52224
	ds_read_b128 v[196:199], v154 offset:53248
	ds_read_b128 v[200:203], v154 offset:54272
	ds_read_b128 v[204:207], v154 offset:55296
	ds_read_b128 v[208:211], v154 offset:56320
	global_load_lds_dwordx4 v[212:213], off
	s_add_i32 m0, s52, 0x2000
	s_add_u32 s50, s50, 0x80080
	v_lshl_add_u64 v[212:213], v[214:215], 0, s[14:15]
	s_addc_u32 s51, s51, 0
	s_add_i32 s52, s72, s56
	global_load_lds_dwordx4 v[212:213], off
	s_mov_b32 m0, s52
	s_nop 0
	global_load_lds_dwordx4 v128, s[50:51]
	s_add_i32 m0, s52, 0x2000
	s_nop 0
	global_load_lds_dwordx4 v130, s[50:51]
	v_lshl_add_u64 v[212:213], v[216:217], 0, s[14:15]
	s_mov_b32 m0, s61
	s_nop 0
	global_load_lds_dwordx4 v[212:213], off
	v_lshl_add_u64 v[212:213], v[218:219], 0, s[14:15]
	s_mov_b32 m0, s62
	s_nop 0
	global_load_lds_dwordx4 v[212:213], off
	s_waitcnt vmcnt(8)
	s_waitcnt lgkmcnt(0)
	s_setprio 1
	s_barrier
	v_mfma_f32_16x16x32_bf16 v[60:63], v[140:143], v[180:183], v[60:63]
	v_mfma_f32_16x16x32_bf16 v[56:59], v[156:159], v[180:183], v[56:59]
	v_mfma_f32_16x16x32_bf16 v[44:47], v[140:143], v[188:191], v[44:47]
	v_mfma_f32_16x16x32_bf16 v[40:43], v[156:159], v[188:191], v[40:43]
	v_mfma_f32_16x16x32_bf16 v[28:31], v[140:143], v[196:199], v[28:31]
	v_mfma_f32_16x16x32_bf16 v[24:27], v[156:159], v[196:199], v[24:27]
	v_mfma_f32_16x16x32_bf16 v[12:15], v[140:143], v[204:207], v[12:15]
	v_mfma_f32_16x16x32_bf16 v[8:11], v[156:159], v[204:207], v[8:11]
	v_mfma_f32_16x16x32_bf16 v[60:63], v[144:147], v[184:187], v[60:63]
	v_mfma_f32_16x16x32_bf16 v[56:59], v[160:163], v[184:187], v[56:59]
	v_mfma_f32_16x16x32_bf16 v[44:47], v[144:147], v[192:195], v[44:47]
	v_mfma_f32_16x16x32_bf16 v[40:43], v[160:163], v[192:195], v[40:43]
	v_mfma_f32_16x16x32_bf16 v[28:31], v[144:147], v[200:203], v[28:31]
	v_mfma_f32_16x16x32_bf16 v[24:27], v[160:163], v[200:203], v[24:27]
	v_mfma_f32_16x16x32_bf16 v[12:15], v[144:147], v[208:211], v[12:15]
	v_mfma_f32_16x16x32_bf16 v[8:11], v[160:163], v[208:211], v[8:11]
	v_mfma_f32_16x16x32_bf16 v[52:55], v[164:167], v[180:183], v[52:55]
	v_mfma_f32_16x16x32_bf16 v[48:51], v[172:175], v[180:183], v[48:51]
	v_mfma_f32_16x16x32_bf16 v[36:39], v[164:167], v[188:191], v[36:39]
	v_mfma_f32_16x16x32_bf16 v[32:35], v[172:175], v[188:191], v[32:35]
	v_mfma_f32_16x16x32_bf16 v[20:23], v[164:167], v[196:199], v[20:23]
	v_mfma_f32_16x16x32_bf16 v[16:19], v[172:175], v[196:199], v[16:19]
	v_mfma_f32_16x16x32_bf16 v[4:7], v[164:167], v[204:207], v[4:7]
	v_mfma_f32_16x16x32_bf16 v[0:3], v[172:175], v[204:207], v[0:3]
	v_mfma_f32_16x16x32_bf16 v[52:55], v[168:171], v[184:187], v[52:55]
	v_mfma_f32_16x16x32_bf16 v[48:51], v[176:179], v[184:187], v[48:51]
	v_mfma_f32_16x16x32_bf16 v[36:39], v[168:171], v[192:195], v[36:39]
	v_mfma_f32_16x16x32_bf16 v[32:35], v[176:179], v[192:195], v[32:35]
	v_mfma_f32_16x16x32_bf16 v[20:23], v[168:171], v[200:203], v[20:23]
	v_mfma_f32_16x16x32_bf16 v[16:19], v[176:179], v[200:203], v[16:19]
	v_mfma_f32_16x16x32_bf16 v[4:7], v[168:171], v[208:211], v[4:7]
	v_mfma_f32_16x16x32_bf16 v[0:3], v[176:179], v[208:211], v[0:3]
	s_setprio 0
	s_barrier
	s_add_i32 s70, s70, 2
	s_add_u32 s48, s48, 0x100
	s_addc_u32 s49, s49, 0
	s_add_u32 s68, s68, 0x100
	s_addc_u32 s69, s69, 0
	s_cmp_gt_u32 s70, 29
	s_cbranch_scc0 .LBB0_1197
	s_and_b64 vcc, exec, s[16:17]
	s_cbranch_vccz .LBB0_1200
	s_barrier

; #define PG8_STAGE(bufoff, gbase, voff) do { _Pragma("unroll") for (int _i = 0; _i < 2; ++_i) \
;         __builtin_amdgcn_global_load_lds((const unsigned*)((const char*)(gbase) + (voff)[_i]), (LAS unsigned*)(lds + (bufoff) + ldsw + _i * 8192), 16, 0, 0); } while (0)
; #define PG8_LDA(dst, b, h) do { _Pragma("unroll") for (int m = 0; m < 4; ++m) _Pragma("unroll") for (int k = 0; k < 2; ++k) dst[m][k] = *(const LAS bf16x8*)(lds + PG8_SA(b, h) + aoff + m * 2048 + k * 1024); } while (0)
; #define PG8_LDB(dst, b, h) do { _Pragma("unroll") for (int n = 0; n < 2; ++n) _Pragma("unroll") for (int k = 0; k < 2; ++k) dst[n][k] = *(const LAS bf16x8*)(lds + PG8_SB(b, h) + boff + n * 2048 + k * 1024); } while (0)
; #define PG8_WAIT_V(n) asm volatile("s_waitcnt vmcnt(" #n ")" ::: "memory")
; #define PG8_WAIT_L(n) asm volatile("s_waitcnt lgkmcnt(" #n ")" ::: "memory")
; #define PG8_BAR __builtin_amdgcn_s_barrier()
; #define PG8_SCHED __builtin_amdgcn_sched_barrier(0)
; template <class Epi, bool FP8 = false>
; __device__ __forceinline__ void gemm_phase(LAS unsigned char* lds, const Gemm g, const StaticOrder& S_, const Epi& E, const int tid) {
;     ...
;             const bool last = (t == nt - 2);
;             const char* a1 = cA + (size_t)(t + 1) * kstep;
;             const char* a2 = last ? nA : cA + (size_t)(t + 2) * kstep; const char* b2 = last ? nB : cB + (size_t)(t + 2) * kstep;
;             const char* a3 = a2 + kstep; const char* b3 = b2 + kstep;
;             PG8_LDB(B0, 0, 0); PG8_LDB(B1, 0, 1); PG8_SCHED; PG8_LDA(At, 0, 0); PG8_STAGE(PG8_SA(1, 1), a1 + hstepA, voffA);
;             PG8_WAIT_V(8); PG8_WAIT_L(0); PG8_BAR; PG8_MMA(0, 0, At, B0); PG8_MMA(0, 1, At, B1); PG8_BAR; PG8_SCHED;
;             PG8_LDA(At, 0, 1); PG8_STAGE(PG8_SB(0, 0), b2, voffB); PG8_STAGE(PG8_SB(0, 1), b2 + hstepB, voffB); PG8_STAGE(PG8_SA(0, 0), a2, voffA);
;             PG8_WAIT_V(8); PG8_WAIT_L(0); PG8_BAR; PG8_MMA(1, 0, At, B0); PG8_MMA(1, 1, At, B1); PG8_BAR; PG8_SCHED;
.LBB0_1340:
	ds_read_b128 v[150:153], v147
	ds_read_b128 v[154:157], v147 offset:1024
	ds_read_b128 v[158:161], v147 offset:2048
	ds_read_b128 v[162:165], v147 offset:3072
	ds_read_b128 v[166:169], v148
	ds_read_b128 v[170:173], v148 offset:1024
	ds_read_b128 v[174:177], v148 offset:2048
	ds_read_b128 v[178:181], v148 offset:3072
	s_add_u32 s42, s30, 0xfff80080
	s_addc_u32 s43, s31, -1
	s_cmp_eq_u32 s69, 28
	s_cselect_b32 s47, s23, s43
	s_cselect_b32 s46, s63, s42
	s_cselect_b32 s43, s21, s68
	s_cselect_b32 s42, s66, s67
	s_add_i32 m0, s29, 0xc000
	ds_read_b128 v[182:185], v149
	ds_read_b128 v[186:189], v149 offset:1024
	ds_read_b128 v[190:193], v149 offset:2048
	ds_read_b128 v[194:197], v149 offset:3072
	ds_read_b128 v[198:201], v149 offset:4096
	ds_read_b128 v[202:205], v149 offset:5120
	ds_read_b128 v[206:209], v149 offset:6144
	ds_read_b128 v[210:213], v149 offset:7168
	global_load_lds_dwordx4 v136, s[30:31]
	s_add_i32 m0, s29, 0xe000
	s_nop 0
	global_load_lds_dwordx4 v138, s[30:31]
	s_waitcnt vmcnt(8)
	s_waitcnt lgkmcnt(0)
	s_setprio 1
	s_barrier
	v_mfma_f32_16x16x32_bf16 v[124:127], v[150:153], v[182:185], v[124:127]
	v_mfma_f32_16x16x32_bf16 v[120:123], v[158:161], v[182:185], v[120:123]
	v_mfma_f32_16x16x32_bf16 v[108:111], v[150:153], v[190:193], v[108:111]
	v_mfma_f32_16x16x32_bf16 v[104:107], v[158:161], v[190:193], v[104:107]
	v_mfma_f32_16x16x32_bf16 v[92:95], v[150:153], v[198:201], v[92:95]
	v_mfma_f32_16x16x32_bf16 v[88:91], v[158:161], v[198:201], v[88:91]
	v_mfma_f32_16x16x32_bf16 v[76:79], v[150:153], v[206:209], v[76:79]
	v_mfma_f32_16x16x32_bf16 v[72:75], v[158:161], v[206:209], v[72:75]
	v_mfma_f32_16x16x32_bf16 v[124:127], v[154:157], v[186:189], v[124:127]
	v_mfma_f32_16x16x32_bf16 v[120:123], v[162:165], v[186:189], v[120:123]
	v_mfma_f32_16x16x32_bf16 v[108:111], v[154:157], v[194:197], v[108:111]
	v_mfma_f32_16x16x32_bf16 v[104:107], v[162:165], v[194:197], v[104:107]
	v_mfma_f32_16x16x32_bf16 v[92:95], v[154:157], v[202:205], v[92:95]
	v_mfma_f32_16x16x32_bf16 v[88:91], v[162:165], v[202:205], v[88:91]
	v_mfma_f32_16x16x32_bf16 v[76:79], v[154:157], v[210:213], v[76:79]
	v_mfma_f32_16x16x32_bf16 v[72:75], v[162:165], v[210:213], v[72:75]
	v_mfma_f32_16x16x32_bf16 v[116:119], v[166:169], v[182:185], v[116:119]
	v_mfma_f32_16x16x32_bf16 v[112:115], v[174:177], v[182:185], v[112:115]
	v_mfma_f32_16x16x32_bf16 v[100:103], v[166:169], v[190:193], v[100:103]
	v_mfma_f32_16x16x32_bf16 v[96:99], v[174:177], v[190:193], v[96:99]
	v_mfma_f32_16x16x32_bf16 v[84:87], v[166:169], v[198:201], v[84:87]
	v_mfma_f32_16x16x32_bf16 v[80:83], v[174:177], v[198:201], v[80:83]
	v_mfma_f32_16x16x32_bf16 v[68:71], v[166:169], v[206:209], v[68:71]
	v_mfma_f32_16x16x32_bf16 v[64:67], v[174:177], v[206:209], v[64:67]
	v_mfma_f32_16x16x32_bf16 v[116:119], v[170:173], v[186:189], v[116:119]
	v_mfma_f32_16x16x32_bf16 v[112:115], v[178:181], v[186:189], v[112:115]
	v_mfma_f32_16x16x32_bf16 v[100:103], v[170:173], v[194:197], v[100:103]
	v_mfma_f32_16x16x32_bf16 v[96:99], v[178:181], v[194:197], v[96:99]
	v_mfma_f32_16x16x32_bf16 v[84:87], v[170:173], v[202:205], v[84:87]
	v_mfma_f32_16x16x32_bf16 v[80:83], v[178:181], v[202:205], v[80:83]
	v_mfma_f32_16x16x32_bf16 v[68:71], v[170:173], v[210:213], v[68:71]
	v_mfma_f32_16x16x32_bf16 v[64:67], v[178:181], v[210:213], v[64:67]
	s_setprio 0
	s_barrier
	s_add_i32 s70, s59, s50
	v_lshl_add_u64 v[214:215], s[42:43], 0, v[128:129]
	s_mov_b32 m0, s70
	ds_read_b128 v[182:185], v149 offset:16384
	ds_read_b128 v[186:189], v149 offset:17408
	ds_read_b128 v[190:193], v149 offset:18432
	ds_read_b128 v[194:197], v149 offset:19456
	ds_read_b128 v[198:201], v149 offset:20480
	ds_read_b128 v[202:205], v149 offset:21504
	ds_read_b128 v[206:209], v149 offset:22528
	ds_read_b128 v[210:213], v149 offset:23552
	global_load_lds_dwordx4 v[214:215], off
	s_add_i32 m0, s70, 0x2000
	s_add_u32 s70, s42, 0x80000
	v_lshl_add_u64 v[216:217], s[42:43], 0, v[130:131]
	s_addc_u32 s71, s43, 0
	s_add_i32 s72, s60, s50
	global_load_lds_dwordx4 v[216:217], off
	s_mov_b32 m0, s72
	v_lshl_add_u64 v[220:221], s[46:47], 0, v[132:133]
	global_load_lds_dwordx4 v128, s[70:71]
	s_add_i32 m0, s72, 0x2000
	s_nop 0
	global_load_lds_dwordx4 v130, s[70:71]
	v_lshl_add_u64 v[218:219], s[46:47], 0, v[134:135]
	s_mov_b32 m0, s29
	s_nop 0
	global_load_lds_dwordx4 v[218:219], off
	s_mov_b32 m0, s53
	s_nop 0
	global_load_lds_dwordx4 v[220:221], off
	s_waitcnt vmcnt(8)
	s_waitcnt lgkmcnt(0)
	s_setprio 1
	s_barrier
	v_mfma_f32_16x16x32_bf16 v[60:63], v[150:153], v[182:185], v[60:63]
	v_mfma_f32_16x16x32_bf16 v[56:59], v[158:161], v[182:185], v[56:59]
	v_mfma_f32_16x16x32_bf16 v[44:47], v[150:153], v[190:193], v[44:47]
	v_mfma_f32_16x16x32_bf16 v[40:43], v[158:161], v[190:193], v[40:43]
	v_mfma_f32_16x16x32_bf16 v[28:31], v[150:153], v[198:201], v[28:31]
	v_mfma_f32_16x16x32_bf16 v[24:27], v[158:161], v[198:201], v[24:27]
	v_mfma_f32_16x16x32_bf16 v[12:15], v[150:153], v[206:209], v[12:15]
	v_mfma_f32_16x16x32_bf16 v[8:11], v[158:161], v[206:209], v[8:11]
	v_mfma_f32_16x16x32_bf16 v[60:63], v[154:157], v[186:189], v[60:63]
	v_mfma_f32_16x16x32_bf16 v[56:59], v[162:165], v[186:189], v[56:59]
	v_mfma_f32_16x16x32_bf16 v[44:47], v[154:157], v[194:197], v[44:47]
	v_mfma_f32_16x16x32_bf16 v[40:43], v[162:165], v[194:197], v[40:43]
	v_mfma_f32_16x16x32_bf16 v[28:31], v[154:157], v[202:205], v[28:31]
	v_mfma_f32_16x16x32_bf16 v[24:27], v[162:165], v[202:205], v[24:27]
	v_mfma_f32_16x16x32_bf16 v[12:15], v[154:157], v[210:213], v[12:15]
	v_mfma_f32_16x16x32_bf16 v[8:11], v[162:165], v[210:213], v[8:11]
	v_mfma_f32_16x16x32_bf16 v[52:55], v[166:169], v[182:185], v[52:55]
	v_mfma_f32_16x16x32_bf16 v[48:51], v[174:177], v[182:185], v[48:51]
	v_mfma_f32_16x16x32_bf16 v[36:39], v[166:169], v[190:193], v[36:39]
	v_mfma_f32_16x16x32_bf16 v[32:35], v[174:177], v[190:193], v[32:35]
	v_mfma_f32_16x16x32_bf16 v[20:23], v[166:169], v[198:201], v[20:23]
	v_mfma_f32_16x16x32_bf16 v[16:19], v[174:177], v[198:201], v[16:19]
	v_mfma_f32_16x16x32_bf16 v[4:7], v[166:169], v[206:209], v[4:7]
	v_mfma_f32_16x16x32_bf16 v[0:3], v[174:177], v[206:209], v[0:3]
	v_mfma_f32_16x16x32_bf16 v[52:55], v[170:173], v[186:189], v[52:55]
	v_mfma_f32_16x16x32_bf16 v[48:51], v[178:181], v[186:189], v[48:51]
	v_mfma_f32_16x16x32_bf16 v[36:39], v[170:173], v[194:197], v[36:39]
	v_mfma_f32_16x16x32_bf16 v[32:35], v[178:181], v[194:197], v[32:35]
	v_mfma_f32_16x16x32_bf16 v[20:23], v[170:173], v[202:205], v[20:23]
	v_mfma_f32_16x16x32_bf16 v[16:19], v[178:181], v[202:205], v[16:19]
	v_mfma_f32_16x16x32_bf16 v[4:7], v[170:173], v[210:213], v[4:7]
	v_mfma_f32_16x16x32_bf16 v[0:3], v[178:181], v[210:213], v[0:3]
	s_setprio 0
	s_barrier
; #define PG8_STAGE(bufoff, gbase, voff) do { _Pragma("unroll") for (int _i = 0; _i < 2; ++_i) \
;         __builtin_amdgcn_global_load_lds((const unsigned*)((const char*)(gbase) + (voff)[_i]), (LAS unsigned*)(lds + (bufoff) + ldsw + _i * 8192), 16, 0, 0); } while (0)
; #define PG8_LDA(dst, b, h) do { _Pragma("unroll") for (int m = 0; m < 4; ++m) _Pragma("unroll") for (int k = 0; k < 2; ++k) dst[m][k] = *(const LAS bf16x8*)(lds + PG8_SA(b, h) + aoff + m * 2048 + k * 1024); } while (0)
; #define PG8_LDB(dst, b, h) do { _Pragma("unroll") for (int n = 0; n < 2; ++n) _Pragma("unroll") for (int k = 0; k < 2; ++k) dst[n][k] = *(const LAS bf16x8*)(lds + PG8_SB(b, h) + boff + n * 2048 + k * 1024); } while (0)
; #define PG8_WAIT_V(n) asm volatile("s_waitcnt vmcnt(" #n ")" ::: "memory")
; #define PG8_WAIT_L(n) asm volatile("s_waitcnt lgkmcnt(" #n ")" ::: "memory")
; #define PG8_BAR __builtin_amdgcn_s_barrier()
; #define PG8_SCHED __builtin_amdgcn_sched_barrier(0)
; template <class Epi, bool FP8 = false>
; __device__ __forceinline__ void gemm_phase(LAS unsigned char* lds, const Gemm g, const StaticOrder& S_, const Epi& E, const int tid) {
;     ...
;             PG8_LDB(B0, 1, 0); PG8_LDB(B1, 1, 1); PG8_SCHED; PG8_LDA(At, 1, 0); PG8_STAGE(PG8_SA(0, 1), a2 + hstepA, voffA);
;             PG8_WAIT_V(8); PG8_WAIT_L(0); PG8_BAR; PG8_MMA(0, 0, At, B0); PG8_MMA(0, 1, At, B1); PG8_BAR; PG8_SCHED;
;             PG8_LDA(At, 1, 1); PG8_STAGE(PG8_SB(1, 0), b3, voffB); PG8_STAGE(PG8_SB(1, 1), b3 + hstepB, voffB); PG8_STAGE(PG8_SA(1, 0), a3, voffA);
;             PG8_WAIT_V(8); PG8_WAIT_L(0); PG8_BAR; PG8_MMA(1, 0, At, B0); PG8_MMA(1, 1, At, B1); PG8_BAR; PG8_SCHED;
;         }
;         if (wr == 0) PG8_BAR;
	s_add_i32 s70, 0, 0x18000
	s_add_i32 s71, 0, 0x1c000
	v_add_u32_e32 v162, s70, v145
	v_add_u32_e32 v178, s71, v145
	ds_read_b128 v[150:153], v162
	ds_read_b128 v[154:157], v162 offset:1024
	ds_read_b128 v[158:161], v162 offset:2048
	ds_read_b128 v[162:165], v162 offset:3072
	ds_read_b128 v[166:169], v178
	ds_read_b128 v[170:173], v178 offset:1024
	ds_read_b128 v[174:177], v178 offset:2048
	ds_read_b128 v[178:181], v178 offset:3072
	s_add_u32 s46, s46, 0x80000
	s_addc_u32 s47, s47, 0
	s_mov_b32 m0, s54
	ds_read_b128 v[182:185], v149 offset:32768
	ds_read_b128 v[186:189], v149 offset:33792
	ds_read_b128 v[190:193], v149 offset:34816
	ds_read_b128 v[194:197], v149 offset:35840
	ds_read_b128 v[198:201], v149 offset:36864
	ds_read_b128 v[202:205], v149 offset:37888
	ds_read_b128 v[206:209], v149 offset:38912
	ds_read_b128 v[210:213], v149 offset:39936
	global_load_lds_dwordx4 v134, s[46:47]
	s_mov_b32 m0, s55
	s_nop 0
	global_load_lds_dwordx4 v132, s[46:47]
	s_waitcnt vmcnt(8)
	s_waitcnt lgkmcnt(0)
	s_setprio 1
	s_barrier
	v_mfma_f32_16x16x32_bf16 v[124:127], v[150:153], v[182:185], v[124:127]
	v_mfma_f32_16x16x32_bf16 v[120:123], v[158:161], v[182:185], v[120:123]
	v_mfma_f32_16x16x32_bf16 v[108:111], v[150:153], v[190:193], v[108:111]
	v_mfma_f32_16x16x32_bf16 v[104:107], v[158:161], v[190:193], v[104:107]
	v_mfma_f32_16x16x32_bf16 v[92:95], v[150:153], v[198:201], v[92:95]
	v_mfma_f32_16x16x32_bf16 v[88:91], v[158:161], v[198:201], v[88:91]
	v_mfma_f32_16x16x32_bf16 v[76:79], v[150:153], v[206:209], v[76:79]
	v_mfma_f32_16x16x32_bf16 v[72:75], v[158:161], v[206:209], v[72:75]
	v_mfma_f32_16x16x32_bf16 v[124:127], v[154:157], v[186:189], v[124:127]
	v_mfma_f32_16x16x32_bf16 v[120:123], v[162:165], v[186:189], v[120:123]
	v_mfma_f32_16x16x32_bf16 v[108:111], v[154:157], v[194:197], v[108:111]
	v_mfma_f32_16x16x32_bf16 v[104:107], v[162:165], v[194:197], v[104:107]
	v_mfma_f32_16x16x32_bf16 v[92:95], v[154:157], v[202:205], v[92:95]
	v_mfma_f32_16x16x32_bf16 v[88:91], v[162:165], v[202:205], v[88:91]
	v_mfma_f32_16x16x32_bf16 v[76:79], v[154:157], v[210:213], v[76:79]
	v_mfma_f32_16x16x32_bf16 v[72:75], v[162:165], v[210:213], v[72:75]
	v_mfma_f32_16x16x32_bf16 v[116:119], v[166:169], v[182:185], v[116:119]
	v_mfma_f32_16x16x32_bf16 v[112:115], v[174:177], v[182:185], v[112:115]
	v_mfma_f32_16x16x32_bf16 v[100:103], v[166:169], v[190:193], v[100:103]
	v_mfma_f32_16x16x32_bf16 v[96:99], v[174:177], v[190:193], v[96:99]
	v_mfma_f32_16x16x32_bf16 v[84:87], v[166:169], v[198:201], v[84:87]
	v_mfma_f32_16x16x32_bf16 v[80:83], v[174:177], v[198:201], v[80:83]
	v_mfma_f32_16x16x32_bf16 v[68:71], v[166:169], v[206:209], v[68:71]
	v_mfma_f32_16x16x32_bf16 v[64:67], v[174:177], v[206:209], v[64:67]
	v_mfma_f32_16x16x32_bf16 v[116:119], v[170:173], v[186:189], v[116:119]
	v_mfma_f32_16x16x32_bf16 v[112:115], v[178:181], v[186:189], v[112:115]
	v_mfma_f32_16x16x32_bf16 v[100:103], v[170:173], v[194:197], v[100:103]
	v_mfma_f32_16x16x32_bf16 v[96:99], v[178:181], v[194:197], v[96:99]
	v_mfma_f32_16x16x32_bf16 v[84:87], v[170:173], v[202:205], v[84:87]
	v_mfma_f32_16x16x32_bf16 v[80:83], v[178:181], v[202:205], v[80:83]
	v_mfma_f32_16x16x32_bf16 v[68:71], v[170:173], v[210:213], v[68:71]
	v_mfma_f32_16x16x32_bf16 v[64:67], v[178:181], v[210:213], v[64:67]
	s_setprio 0
	s_barrier
	s_add_i32 s46, s70, s50
	v_lshl_add_u64 v[214:215], v[214:215], 0, s[16:17]
	s_mov_b32 m0, s46
	ds_read_b128 v[182:185], v149 offset:49152
	ds_read_b128 v[186:189], v149 offset:50176
	ds_read_b128 v[190:193], v149 offset:51200
	ds_read_b128 v[194:197], v149 offset:52224
	ds_read_b128 v[198:201], v149 offset:53248
	ds_read_b128 v[202:205], v149 offset:54272
	ds_read_b128 v[206:209], v149 offset:55296
	ds_read_b128 v[210:213], v149 offset:56320
	global_load_lds_dwordx4 v[214:215], off
	s_add_i32 m0, s46, 0x2000
	s_add_u32 s42, s42, 0x80080
	v_lshl_add_u64 v[214:215], v[216:217], 0, s[16:17]
	s_addc_u32 s43, s43, 0
	s_add_i32 s46, s71, s50
	global_load_lds_dwordx4 v[214:215], off
	s_mov_b32 m0, s46
	s_nop 0
	global_load_lds_dwordx4 v128, s[42:43]
	s_add_i32 m0, s46, 0x2000
	s_nop 0
	global_load_lds_dwordx4 v130, s[42:43]
	v_lshl_add_u64 v[214:215], v[218:219], 0, s[16:17]
	s_mov_b32 m0, s57
	s_nop 0
	global_load_lds_dwordx4 v[214:215], off
	v_lshl_add_u64 v[214:215], v[220:221], 0, s[16:17]
	s_mov_b32 m0, s58
	s_nop 0
	global_load_lds_dwordx4 v[214:215], off
	s_waitcnt vmcnt(8)
	s_waitcnt lgkmcnt(0)
	s_setprio 1
	s_barrier
	v_mfma_f32_16x16x32_bf16 v[60:63], v[150:153], v[182:185], v[60:63]
	v_mfma_f32_16x16x32_bf16 v[56:59], v[158:161], v[182:185], v[56:59]
	v_mfma_f32_16x16x32_bf16 v[44:47], v[150:153], v[190:193], v[44:47]
	v_mfma_f32_16x16x32_bf16 v[40:43], v[158:161], v[190:193], v[40:43]
	v_mfma_f32_16x16x32_bf16 v[28:31], v[150:153], v[198:201], v[28:31]
	v_mfma_f32_16x16x32_bf16 v[24:27], v[158:161], v[198:201], v[24:27]
	v_mfma_f32_16x16x32_bf16 v[12:15], v[150:153], v[206:209], v[12:15]
	v_mfma_f32_16x16x32_bf16 v[8:11], v[158:161], v[206:209], v[8:11]
	v_mfma_f32_16x16x32_bf16 v[60:63], v[154:157], v[186:189], v[60:63]
	v_mfma_f32_16x16x32_bf16 v[56:59], v[162:165], v[186:189], v[56:59]
	v_mfma_f32_16x16x32_bf16 v[44:47], v[154:157], v[194:197], v[44:47]
	v_mfma_f32_16x16x32_bf16 v[40:43], v[162:165], v[194:197], v[40:43]
	v_mfma_f32_16x16x32_bf16 v[28:31], v[154:157], v[202:205], v[28:31]
	v_mfma_f32_16x16x32_bf16 v[24:27], v[162:165], v[202:205], v[24:27]
	v_mfma_f32_16x16x32_bf16 v[12:15], v[154:157], v[210:213], v[12:15]
	v_mfma_f32_16x16x32_bf16 v[8:11], v[162:165], v[210:213], v[8:11]
	v_mfma_f32_16x16x32_bf16 v[52:55], v[166:169], v[182:185], v[52:55]
	v_mfma_f32_16x16x32_bf16 v[48:51], v[174:177], v[182:185], v[48:51]
	v_mfma_f32_16x16x32_bf16 v[36:39], v[166:169], v[190:193], v[36:39]
	v_mfma_f32_16x16x32_bf16 v[32:35], v[174:177], v[190:193], v[32:35]
	v_mfma_f32_16x16x32_bf16 v[20:23], v[166:169], v[198:201], v[20:23]
	v_mfma_f32_16x16x32_bf16 v[16:19], v[174:177], v[198:201], v[16:19]
	v_mfma_f32_16x16x32_bf16 v[4:7], v[166:169], v[206:209], v[4:7]
	v_mfma_f32_16x16x32_bf16 v[0:3], v[174:177], v[206:209], v[0:3]
	v_mfma_f32_16x16x32_bf16 v[52:55], v[170:173], v[186:189], v[52:55]
	v_mfma_f32_16x16x32_bf16 v[48:51], v[178:181], v[186:189], v[48:51]
	v_mfma_f32_16x16x32_bf16 v[36:39], v[170:173], v[194:197], v[36:39]
	v_mfma_f32_16x16x32_bf16 v[32:35], v[178:181], v[194:197], v[32:35]
	v_mfma_f32_16x16x32_bf16 v[20:23], v[170:173], v[202:205], v[20:23]
	v_mfma_f32_16x16x32_bf16 v[16:19], v[178:181], v[202:205], v[16:19]
	v_mfma_f32_16x16x32_bf16 v[4:7], v[170:173], v[210:213], v[4:7]
	v_mfma_f32_16x16x32_bf16 v[0:3], v[178:181], v[210:213], v[0:3]
	s_setprio 0
	s_barrier
	s_add_i32 s69, s69, 2
	s_add_u32 s30, s30, 0x100
	s_addc_u32 s31, s31, 0
	s_add_u32 s67, s67, 0x100
	s_addc_u32 s68, s68, 0
	s_cmp_gt_u32 s69, 29
	s_cbranch_scc0 .LBB0_1340
	s_and_b64 vcc, exec, s[18:19]
	s_cbranch_vccz .LBB0_1343
	s_barrier

; #define PG8_STAGE(bufoff, gbase, voff) do { _Pragma("unroll") for (int _i = 0; _i < 2; ++_i) \
;         __builtin_amdgcn_global_load_lds((const unsigned*)((const char*)(gbase) + (voff)[_i]), (LAS unsigned*)(lds + (bufoff) + ldsw + _i * 8192), 16, 0, 0); } while (0)
; #define PG8_LDA(dst, b, h) do { _Pragma("unroll") for (int m = 0; m < 4; ++m) _Pragma("unroll") for (int k = 0; k < 2; ++k) dst[m][k] = *(const LAS bf16x8*)(lds + PG8_SA(b, h) + aoff + m * 2048 + k * 1024); } while (0)
; #define PG8_LDB(dst, b, h) do { _Pragma("unroll") for (int n = 0; n < 2; ++n) _Pragma("unroll") for (int k = 0; k < 2; ++k) dst[n][k] = *(const LAS bf16x8*)(lds + PG8_SB(b, h) + boff + n * 2048 + k * 1024); } while (0)
; #define PG8_WAIT_V(n) asm volatile("s_waitcnt vmcnt(" #n ")" ::: "memory")
; #define PG8_WAIT_L(n) asm volatile("s_waitcnt lgkmcnt(" #n ")" ::: "memory")
; #define PG8_BAR __builtin_amdgcn_s_barrier()
; #define PG8_SCHED __builtin_amdgcn_sched_barrier(0)
; template <class Epi, bool FP8 = false>
; __device__ __forceinline__ void gemm_phase(LAS unsigned char* lds, const Gemm g, const StaticOrder& S_, const Epi& E, const int tid) {
;     ...
;             const bool last = (t == nt - 2);
;             const char* a1 = cA + (size_t)(t + 1) * kstep;
;             const char* a2 = last ? nA : cA + (size_t)(t + 2) * kstep; const char* b2 = last ? nB : cB + (size_t)(t + 2) * kstep;
;             const char* a3 = a2 + kstep; const char* b3 = b2 + kstep;
;             PG8_LDB(B0, 0, 0); PG8_LDB(B1, 0, 1); PG8_SCHED; PG8_LDA(At, 0, 0); PG8_STAGE(PG8_SA(1, 1), a1 + hstepA, voffA);
;             PG8_WAIT_V(8); PG8_WAIT_L(0); PG8_BAR; PG8_MMA(0, 0, At, B0); PG8_MMA(0, 1, At, B1); PG8_BAR; PG8_SCHED;
;             PG8_LDA(At, 0, 1); PG8_STAGE(PG8_SB(0, 0), b2, voffB); PG8_STAGE(PG8_SB(0, 1), b2 + hstepB, voffB); PG8_STAGE(PG8_SA(0, 0), a2, voffA);
;             PG8_WAIT_V(8); PG8_WAIT_L(0); PG8_BAR; PG8_MMA(1, 0, At, B0); PG8_MMA(1, 1, At, B1); PG8_BAR; PG8_SCHED;
.LBB0_1420:
	ds_read_b128 v[140:143], v152
	ds_read_b128 v[144:147], v152 offset:1024
	ds_read_b128 v[156:159], v152 offset:2048
	ds_read_b128 v[160:163], v152 offset:3072
	ds_read_b128 v[164:167], v153
	ds_read_b128 v[168:171], v153 offset:1024
	ds_read_b128 v[172:175], v153 offset:2048
	ds_read_b128 v[176:179], v153 offset:3072
	s_add_u32 s28, s26, 0x100
	s_addc_u32 s29, s27, 0
	s_cmpk_eq_i32 s66, 0x54
	s_cselect_b32 s43, s7, s29
	s_cselect_b32 s42, s6, s28
	s_cselect_b32 s31, s25, s63
	s_cselect_b32 s30, s24, s62
	s_add_i32 m0, s49, 0xc000
	ds_read_b128 v[180:183], v154
	ds_read_b128 v[184:187], v154 offset:1024
	ds_read_b128 v[188:191], v154 offset:2048
	ds_read_b128 v[192:195], v154 offset:3072
	ds_read_b128 v[196:199], v154 offset:4096
	ds_read_b128 v[200:203], v154 offset:5120
	ds_read_b128 v[204:207], v154 offset:6144
	ds_read_b128 v[208:211], v154 offset:7168
	global_load_lds_dwordx4 v132, s[26:27]
	s_add_i32 m0, s49, 0xe000
	s_nop 0
	global_load_lds_dwordx4 v134, s[26:27]
	s_waitcnt vmcnt(8)
	s_waitcnt lgkmcnt(0)
	s_setprio 1
	s_barrier
	v_mfma_f32_16x16x32_bf16 v[124:127], v[140:143], v[180:183], v[124:127]
	v_mfma_f32_16x16x32_bf16 v[120:123], v[156:159], v[180:183], v[120:123]
	v_mfma_f32_16x16x32_bf16 v[108:111], v[140:143], v[188:191], v[108:111]
	v_mfma_f32_16x16x32_bf16 v[104:107], v[156:159], v[188:191], v[104:107]
	v_mfma_f32_16x16x32_bf16 v[92:95], v[140:143], v[196:199], v[92:95]
	v_mfma_f32_16x16x32_bf16 v[88:91], v[156:159], v[196:199], v[88:91]
	v_mfma_f32_16x16x32_bf16 v[76:79], v[140:143], v[204:207], v[76:79]
	v_mfma_f32_16x16x32_bf16 v[72:75], v[156:159], v[204:207], v[72:75]
	v_mfma_f32_16x16x32_bf16 v[124:127], v[144:147], v[184:187], v[124:127]
	v_mfma_f32_16x16x32_bf16 v[120:123], v[160:163], v[184:187], v[120:123]
	v_mfma_f32_16x16x32_bf16 v[108:111], v[144:147], v[192:195], v[108:111]
	v_mfma_f32_16x16x32_bf16 v[104:107], v[160:163], v[192:195], v[104:107]
	v_mfma_f32_16x16x32_bf16 v[92:95], v[144:147], v[200:203], v[92:95]
	v_mfma_f32_16x16x32_bf16 v[88:91], v[160:163], v[200:203], v[88:91]
	v_mfma_f32_16x16x32_bf16 v[76:79], v[144:147], v[208:211], v[76:79]
	v_mfma_f32_16x16x32_bf16 v[72:75], v[160:163], v[208:211], v[72:75]
	v_mfma_f32_16x16x32_bf16 v[116:119], v[164:167], v[180:183], v[116:119]
	v_mfma_f32_16x16x32_bf16 v[112:115], v[172:175], v[180:183], v[112:115]
	v_mfma_f32_16x16x32_bf16 v[100:103], v[164:167], v[188:191], v[100:103]
	v_mfma_f32_16x16x32_bf16 v[96:99], v[172:175], v[188:191], v[96:99]
	v_mfma_f32_16x16x32_bf16 v[84:87], v[164:167], v[196:199], v[84:87]
	v_mfma_f32_16x16x32_bf16 v[80:83], v[172:175], v[196:199], v[80:83]
	v_mfma_f32_16x16x32_bf16 v[68:71], v[164:167], v[204:207], v[68:71]
	v_mfma_f32_16x16x32_bf16 v[64:67], v[172:175], v[204:207], v[64:67]
	v_mfma_f32_16x16x32_bf16 v[116:119], v[168:171], v[184:187], v[116:119]
	v_mfma_f32_16x16x32_bf16 v[112:115], v[176:179], v[184:187], v[112:115]
	v_mfma_f32_16x16x32_bf16 v[100:103], v[168:171], v[192:195], v[100:103]
	v_mfma_f32_16x16x32_bf16 v[96:99], v[176:179], v[192:195], v[96:99]
	v_mfma_f32_16x16x32_bf16 v[84:87], v[168:171], v[200:203], v[84:87]
	v_mfma_f32_16x16x32_bf16 v[80:83], v[176:179], v[200:203], v[80:83]
	v_mfma_f32_16x16x32_bf16 v[68:71], v[168:171], v[208:211], v[68:71]
	v_mfma_f32_16x16x32_bf16 v[64:67], v[176:179], v[208:211], v[64:67]
	s_setprio 0
	s_barrier
	s_add_i32 s26, s56, s48
	v_lshl_add_u64 v[212:213], s[30:31], 0, v[128:129]
	s_mov_b32 m0, s26
	ds_read_b128 v[180:183], v154 offset:16384
	ds_read_b128 v[184:187], v154 offset:17408
	ds_read_b128 v[188:191], v154 offset:18432
	ds_read_b128 v[192:195], v154 offset:19456
	ds_read_b128 v[196:199], v154 offset:20480
	ds_read_b128 v[200:203], v154 offset:21504
	ds_read_b128 v[204:207], v154 offset:22528
	ds_read_b128 v[208:211], v154 offset:23552
	global_load_lds_dwordx4 v[212:213], off
	s_add_i32 m0, s26, 0x2000
	s_add_u32 s26, s30, 0x160000
	v_lshl_add_u64 v[214:215], s[30:31], 0, v[130:131]
	s_addc_u32 s27, s31, 0
	s_add_i32 s67, s57, s48
	global_load_lds_dwordx4 v[214:215], off
	s_mov_b32 m0, s67
	v_lshl_add_u64 v[218:219], s[42:43], 0, v[130:131]
	global_load_lds_dwordx4 v128, s[26:27]
	s_add_i32 m0, s67, 0x2000
	s_nop 0
	global_load_lds_dwordx4 v130, s[26:27]
	v_lshl_add_u64 v[216:217], s[42:43], 0, v[128:129]
	s_mov_b32 m0, s49
	s_nop 0
	global_load_lds_dwordx4 v[216:217], off
	s_mov_b32 m0, s50
	s_nop 0
	global_load_lds_dwordx4 v[218:219], off
	s_waitcnt vmcnt(8)
	s_waitcnt lgkmcnt(0)
	s_setprio 1
	s_barrier
	v_mfma_f32_16x16x32_bf16 v[60:63], v[140:143], v[180:183], v[60:63]
	v_mfma_f32_16x16x32_bf16 v[56:59], v[156:159], v[180:183], v[56:59]
	v_mfma_f32_16x16x32_bf16 v[44:47], v[140:143], v[188:191], v[44:47]
	v_mfma_f32_16x16x32_bf16 v[40:43], v[156:159], v[188:191], v[40:43]
	v_mfma_f32_16x16x32_bf16 v[28:31], v[140:143], v[196:199], v[28:31]
	v_mfma_f32_16x16x32_bf16 v[24:27], v[156:159], v[196:199], v[24:27]
	v_mfma_f32_16x16x32_bf16 v[12:15], v[140:143], v[204:207], v[12:15]
	v_mfma_f32_16x16x32_bf16 v[8:11], v[156:159], v[204:207], v[8:11]
	v_mfma_f32_16x16x32_bf16 v[60:63], v[144:147], v[184:187], v[60:63]
	v_mfma_f32_16x16x32_bf16 v[56:59], v[160:163], v[184:187], v[56:59]
	v_mfma_f32_16x16x32_bf16 v[44:47], v[144:147], v[192:195], v[44:47]
	v_mfma_f32_16x16x32_bf16 v[40:43], v[160:163], v[192:195], v[40:43]
	v_mfma_f32_16x16x32_bf16 v[28:31], v[144:147], v[200:203], v[28:31]
	v_mfma_f32_16x16x32_bf16 v[24:27], v[160:163], v[200:203], v[24:27]
	v_mfma_f32_16x16x32_bf16 v[12:15], v[144:147], v[208:211], v[12:15]
	v_mfma_f32_16x16x32_bf16 v[8:11], v[160:163], v[208:211], v[8:11]
	v_mfma_f32_16x16x32_bf16 v[52:55], v[164:167], v[180:183], v[52:55]
	v_mfma_f32_16x16x32_bf16 v[48:51], v[172:175], v[180:183], v[48:51]
	v_mfma_f32_16x16x32_bf16 v[36:39], v[164:167], v[188:191], v[36:39]
	v_mfma_f32_16x16x32_bf16 v[32:35], v[172:175], v[188:191], v[32:35]
	v_mfma_f32_16x16x32_bf16 v[20:23], v[164:167], v[196:199], v[20:23]
	v_mfma_f32_16x16x32_bf16 v[16:19], v[172:175], v[196:199], v[16:19]
	v_mfma_f32_16x16x32_bf16 v[4:7], v[164:167], v[204:207], v[4:7]
	v_mfma_f32_16x16x32_bf16 v[0:3], v[172:175], v[204:207], v[0:3]
	v_mfma_f32_16x16x32_bf16 v[52:55], v[168:171], v[184:187], v[52:55]
	v_mfma_f32_16x16x32_bf16 v[48:51], v[176:179], v[184:187], v[48:51]
	v_mfma_f32_16x16x32_bf16 v[36:39], v[168:171], v[192:195], v[36:39]
	v_mfma_f32_16x16x32_bf16 v[32:35], v[176:179], v[192:195], v[32:35]
	v_mfma_f32_16x16x32_bf16 v[20:23], v[168:171], v[200:203], v[20:23]
	v_mfma_f32_16x16x32_bf16 v[16:19], v[176:179], v[200:203], v[16:19]
	v_mfma_f32_16x16x32_bf16 v[4:7], v[168:171], v[208:211], v[4:7]
	v_mfma_f32_16x16x32_bf16 v[0:3], v[176:179], v[208:211], v[0:3]
	s_setprio 0
	s_barrier
; #define PG8_STAGE(bufoff, gbase, voff) do { _Pragma("unroll") for (int _i = 0; _i < 2; ++_i) \
;         __builtin_amdgcn_global_load_lds((const unsigned*)((const char*)(gbase) + (voff)[_i]), (LAS unsigned*)(lds + (bufoff) + ldsw + _i * 8192), 16, 0, 0); } while (0)
; #define PG8_LDA(dst, b, h) do { _Pragma("unroll") for (int m = 0; m < 4; ++m) _Pragma("unroll") for (int k = 0; k < 2; ++k) dst[m][k] = *(const LAS bf16x8*)(lds + PG8_SA(b, h) + aoff + m * 2048 + k * 1024); } while (0)
; #define PG8_LDB(dst, b, h) do { _Pragma("unroll") for (int n = 0; n < 2; ++n) _Pragma("unroll") for (int k = 0; k < 2; ++k) dst[n][k] = *(const LAS bf16x8*)(lds + PG8_SB(b, h) + boff + n * 2048 + k * 1024); } while (0)
; #define PG8_WAIT_V(n) asm volatile("s_waitcnt vmcnt(" #n ")" ::: "memory")
; #define PG8_WAIT_L(n) asm volatile("s_waitcnt lgkmcnt(" #n ")" ::: "memory")
; #define PG8_BAR __builtin_amdgcn_s_barrier()
; #define PG8_SCHED __builtin_amdgcn_sched_barrier(0)
; template <class Epi, bool FP8 = false>
; __device__ __forceinline__ void gemm_phase(LAS unsigned char* lds, const Gemm g, const StaticOrder& S_, const Epi& E, const int tid) {
;     ...
;             PG8_LDB(B0, 1, 0); PG8_LDB(B1, 1, 1); PG8_SCHED; PG8_LDA(At, 1, 0); PG8_STAGE(PG8_SA(0, 1), a2 + hstepA, voffA);
;             PG8_WAIT_V(8); PG8_WAIT_L(0); PG8_BAR; PG8_MMA(0, 0, At, B0); PG8_MMA(0, 1, At, B1); PG8_BAR; PG8_SCHED;
;             PG8_LDA(At, 1, 1); PG8_STAGE(PG8_SB(1, 0), b3, voffB); PG8_STAGE(PG8_SB(1, 1), b3 + hstepB, voffB); PG8_STAGE(PG8_SA(1, 0), a3, voffA);
;             PG8_WAIT_V(8); PG8_WAIT_L(0); PG8_BAR; PG8_MMA(1, 0, At, B0); PG8_MMA(1, 1, At, B1); PG8_BAR; PG8_SCHED;
;         }
;         if (wr == 0) PG8_BAR;
	s_add_i32 s67, 0, 0x18000
	v_add_u32_e32 v155, s67, v150
	s_add_i32 s68, 0, 0x1c000
	ds_read_b128 v[140:143], v155
	ds_read_b128 v[144:147], v155 offset:1024
	ds_read_b128 v[156:159], v155 offset:2048
	ds_read_b128 v[160:163], v155 offset:3072
	v_add_u32_e32 v155, s68, v150
	ds_read_b128 v[164:167], v155
	ds_read_b128 v[168:171], v155 offset:1024
	ds_read_b128 v[172:175], v155 offset:2048
	ds_read_b128 v[176:179], v155 offset:3072
	s_add_u32 s26, s42, 0x160000
	s_addc_u32 s27, s43, 0
	s_mov_b32 m0, s51
	ds_read_b128 v[180:183], v154 offset:32768
	ds_read_b128 v[184:187], v154 offset:33792
	ds_read_b128 v[188:191], v154 offset:34816
	ds_read_b128 v[192:195], v154 offset:35840
	ds_read_b128 v[196:199], v154 offset:36864
	ds_read_b128 v[200:203], v154 offset:37888
	ds_read_b128 v[204:207], v154 offset:38912
	ds_read_b128 v[208:211], v154 offset:39936
	global_load_lds_dwordx4 v128, s[26:27]
	s_mov_b32 m0, s52
	s_nop 0
	global_load_lds_dwordx4 v130, s[26:27]
	s_waitcnt vmcnt(8)
	s_waitcnt lgkmcnt(0)
	s_setprio 1
	s_barrier
	v_mfma_f32_16x16x32_bf16 v[124:127], v[140:143], v[180:183], v[124:127]
	v_mfma_f32_16x16x32_bf16 v[120:123], v[156:159], v[180:183], v[120:123]
	v_mfma_f32_16x16x32_bf16 v[108:111], v[140:143], v[188:191], v[108:111]
	v_mfma_f32_16x16x32_bf16 v[104:107], v[156:159], v[188:191], v[104:107]
	v_mfma_f32_16x16x32_bf16 v[92:95], v[140:143], v[196:199], v[92:95]
	v_mfma_f32_16x16x32_bf16 v[88:91], v[156:159], v[196:199], v[88:91]
	v_mfma_f32_16x16x32_bf16 v[76:79], v[140:143], v[204:207], v[76:79]
	v_mfma_f32_16x16x32_bf16 v[72:75], v[156:159], v[204:207], v[72:75]
	v_mfma_f32_16x16x32_bf16 v[124:127], v[144:147], v[184:187], v[124:127]
	v_mfma_f32_16x16x32_bf16 v[120:123], v[160:163], v[184:187], v[120:123]
	v_mfma_f32_16x16x32_bf16 v[108:111], v[144:147], v[192:195], v[108:111]
	v_mfma_f32_16x16x32_bf16 v[104:107], v[160:163], v[192:195], v[104:107]
	v_mfma_f32_16x16x32_bf16 v[92:95], v[144:147], v[200:203], v[92:95]
	v_mfma_f32_16x16x32_bf16 v[88:91], v[160:163], v[200:203], v[88:91]
	v_mfma_f32_16x16x32_bf16 v[76:79], v[144:147], v[208:211], v[76:79]
	v_mfma_f32_16x16x32_bf16 v[72:75], v[160:163], v[208:211], v[72:75]
	v_mfma_f32_16x16x32_bf16 v[116:119], v[164:167], v[180:183], v[116:119]
	v_mfma_f32_16x16x32_bf16 v[112:115], v[172:175], v[180:183], v[112:115]
	v_mfma_f32_16x16x32_bf16 v[100:103], v[164:167], v[188:191], v[100:103]
	v_mfma_f32_16x16x32_bf16 v[96:99], v[172:175], v[188:191], v[96:99]
	v_mfma_f32_16x16x32_bf16 v[84:87], v[164:167], v[196:199], v[84:87]
	v_mfma_f32_16x16x32_bf16 v[80:83], v[172:175], v[196:199], v[80:83]
	v_mfma_f32_16x16x32_bf16 v[68:71], v[164:167], v[204:207], v[68:71]
	v_mfma_f32_16x16x32_bf16 v[64:67], v[172:175], v[204:207], v[64:67]
	v_mfma_f32_16x16x32_bf16 v[116:119], v[168:171], v[184:187], v[116:119]
	v_mfma_f32_16x16x32_bf16 v[112:115], v[176:179], v[184:187], v[112:115]
	v_mfma_f32_16x16x32_bf16 v[100:103], v[168:171], v[192:195], v[100:103]
	v_mfma_f32_16x16x32_bf16 v[96:99], v[176:179], v[192:195], v[96:99]
	v_mfma_f32_16x16x32_bf16 v[84:87], v[168:171], v[200:203], v[84:87]
	v_mfma_f32_16x16x32_bf16 v[80:83], v[176:179], v[200:203], v[80:83]
	v_mfma_f32_16x16x32_bf16 v[68:71], v[168:171], v[208:211], v[68:71]
	v_mfma_f32_16x16x32_bf16 v[64:67], v[176:179], v[208:211], v[64:67]
	s_setprio 0
	s_barrier
	s_add_i32 s26, s67, s48
	v_lshl_add_u64 v[212:213], v[212:213], 0, s[18:19]
	s_mov_b32 m0, s26
	ds_read_b128 v[180:183], v154 offset:49152
	ds_read_b128 v[184:187], v154 offset:50176
	ds_read_b128 v[188:191], v154 offset:51200
	ds_read_b128 v[192:195], v154 offset:52224
	ds_read_b128 v[196:199], v154 offset:53248
	ds_read_b128 v[200:203], v154 offset:54272
	ds_read_b128 v[204:207], v154 offset:55296
	ds_read_b128 v[208:211], v154 offset:56320
	global_load_lds_dwordx4 v[212:213], off
	s_add_i32 m0, s26, 0x2000
	s_add_u32 s26, s30, 0x160080
	v_lshl_add_u64 v[212:213], v[214:215], 0, s[18:19]
	s_addc_u32 s27, s31, 0
	s_add_i32 s30, s68, s48
	global_load_lds_dwordx4 v[212:213], off
	s_mov_b32 m0, s30
	s_nop 0
	global_load_lds_dwordx4 v128, s[26:27]
	s_add_i32 m0, s30, 0x2000
	s_nop 0
	global_load_lds_dwordx4 v130, s[26:27]
	v_lshl_add_u64 v[212:213], v[216:217], 0, s[18:19]
	s_mov_b32 m0, s54
	s_nop 0
	global_load_lds_dwordx4 v[212:213], off
	v_lshl_add_u64 v[212:213], v[218:219], 0, s[18:19]
	s_mov_b32 m0, s55
	s_nop 0
	global_load_lds_dwordx4 v[212:213], off
	s_waitcnt vmcnt(8)
	s_waitcnt lgkmcnt(0)
	s_setprio 1
	s_barrier
	v_mfma_f32_16x16x32_bf16 v[60:63], v[140:143], v[180:183], v[60:63]
	v_mfma_f32_16x16x32_bf16 v[56:59], v[156:159], v[180:183], v[56:59]
	v_mfma_f32_16x16x32_bf16 v[44:47], v[140:143], v[188:191], v[44:47]
	v_mfma_f32_16x16x32_bf16 v[40:43], v[156:159], v[188:191], v[40:43]
	v_mfma_f32_16x16x32_bf16 v[28:31], v[140:143], v[196:199], v[28:31]
	v_mfma_f32_16x16x32_bf16 v[24:27], v[156:159], v[196:199], v[24:27]
	v_mfma_f32_16x16x32_bf16 v[12:15], v[140:143], v[204:207], v[12:15]
	v_mfma_f32_16x16x32_bf16 v[8:11], v[156:159], v[204:207], v[8:11]
	v_mfma_f32_16x16x32_bf16 v[60:63], v[144:147], v[184:187], v[60:63]
	v_mfma_f32_16x16x32_bf16 v[56:59], v[160:163], v[184:187], v[56:59]
	v_mfma_f32_16x16x32_bf16 v[44:47], v[144:147], v[192:195], v[44:47]
	v_mfma_f32_16x16x32_bf16 v[40:43], v[160:163], v[192:195], v[40:43]
	v_mfma_f32_16x16x32_bf16 v[28:31], v[144:147], v[200:203], v[28:31]
	v_mfma_f32_16x16x32_bf16 v[24:27], v[160:163], v[200:203], v[24:27]
	v_mfma_f32_16x16x32_bf16 v[12:15], v[144:147], v[208:211], v[12:15]
	v_mfma_f32_16x16x32_bf16 v[8:11], v[160:163], v[208:211], v[8:11]
	v_mfma_f32_16x16x32_bf16 v[52:55], v[164:167], v[180:183], v[52:55]
	v_mfma_f32_16x16x32_bf16 v[48:51], v[172:175], v[180:183], v[48:51]
	v_mfma_f32_16x16x32_bf16 v[36:39], v[164:167], v[188:191], v[36:39]
	v_mfma_f32_16x16x32_bf16 v[32:35], v[172:175], v[188:191], v[32:35]
	v_mfma_f32_16x16x32_bf16 v[20:23], v[164:167], v[196:199], v[20:23]
	v_mfma_f32_16x16x32_bf16 v[16:19], v[172:175], v[196:199], v[16:19]
	v_mfma_f32_16x16x32_bf16 v[4:7], v[164:167], v[204:207], v[4:7]
	v_mfma_f32_16x16x32_bf16 v[0:3], v[172:175], v[204:207], v[0:3]
	v_mfma_f32_16x16x32_bf16 v[52:55], v[168:171], v[184:187], v[52:55]
	v_mfma_f32_16x16x32_bf16 v[48:51], v[176:179], v[184:187], v[48:51]
	v_mfma_f32_16x16x32_bf16 v[36:39], v[168:171], v[192:195], v[36:39]
	v_mfma_f32_16x16x32_bf16 v[32:35], v[176:179], v[192:195], v[32:35]
	v_mfma_f32_16x16x32_bf16 v[20:23], v[168:171], v[200:203], v[20:23]
	v_mfma_f32_16x16x32_bf16 v[16:19], v[176:179], v[200:203], v[16:19]
	v_mfma_f32_16x16x32_bf16 v[4:7], v[168:171], v[208:211], v[4:7]
	v_mfma_f32_16x16x32_bf16 v[0:3], v[176:179], v[208:211], v[0:3]
	s_setprio 0
	s_barrier
	s_add_i32 s66, s66, 2
	s_add_u32 s62, s62, 0x100
	s_addc_u32 s63, s63, 0
	s_cmpk_gt_u32 s66, 0x55
	s_mov_b64 s[26:27], s[28:29]
	s_cbranch_scc0 .LBB0_1420
	s_and_b64 vcc, exec, s[20:21]
	s_cbranch_vccz .LBB0_1423
	s_barrier
